# GEMM loops: merged the vmcnt/lgkmcnt waits, dropped the redundant post-barrier lgkmcnt(0) and filler s_nops
# speedup vs baseline: 1.0171x; 1.0021x over previous
; #define PG8_STAGE(bufoff, gbase, voff) do { _Pragma("unroll") for (int _i = 0; _i < 2; ++_i) \
;         __builtin_amdgcn_global_load_lds((const unsigned*)((const char*)(gbase) + (voff)[_i]), (LAS unsigned*)(lds + (bufoff) + ldsw + _i * 8192), 16, 0, 0); } while (0)
; #define PG8_LDA(dst, b, h) do { _Pragma("unroll") for (int m = 0; m < 4; ++m) _Pragma("unroll") for (int k = 0; k < 2; ++k) dst[m][k] = *(const LAS bf16x8*)(lds + PG8_SA(b, h) + aoff + m * 2048 + k * 1024); } while (0)
; #define PG8_LDB(dst, b, h) do { _Pragma("unroll") for (int n = 0; n < 2; ++n) _Pragma("unroll") for (int k = 0; k < 2; ++k) dst[n][k] = *(const LAS bf16x8*)(lds + PG8_SB(b, h) + boff + n * 2048 + k * 1024); } while (0)
; #define PG8_WAIT_V(n) asm volatile("s_waitcnt vmcnt(" #n ")" ::: "memory")
; #define PG8_WAIT_L(n) asm volatile("s_waitcnt lgkmcnt(" #n ")" ::: "memory")
; #define PG8_BAR __builtin_amdgcn_s_barrier()
; __device__ __forceinline__ void gemm_phase(LAS unsigned char* lds, const Params& p, const bf16_t* gA, const bf16_t* gBt, const int gM, const int gN, const int gK, const int epi, const int perm, bf16_t* const Hp, const int goff, const float coef) {
;     ...
;         const bool has_next = S.next(ui + 1, nxt);
;         const char* nA = has_next ? (const char*)gA + (size_t)nxt.pm * tstep + (nxt.ks > 0 ? nxt.ks * ksl : 0) : cA; const char* nB = has_next ? (const char*)gBt + (size_t)nxt.pn * tstep + (nxt.ks > 0 ? nxt.ks * ksl : 0) : cB;
;         const int nt = cur.ks >= 0 ? ntf / 4 : ntf;
;         for (int t = 0; t < nt; t += 2) {
;             const bool last = (t == nt - 2);
;             const char* a1 = cA + (size_t)(t + 1) * kstep;
;             const char* a2 = last ? nA : cA + (size_t)(t + 2) * kstep; const char* b2 = last ? nB : cB + (size_t)(t + 2) * kstep;
;             const char* a3 = a2 + kstep; const char* b3 = b2 + kstep;
;             PG8_LDB(B0, 0, 0); PG8_LDB(B1, 0, 1); PG8_SCHED; PG8_LDA(At, 0, 0); PG8_STAGE(PG8_SA(1, 1), a1 + hstep, voffA);
;             PG8_WAIT_V(8); PG8_WAIT_L(0); PG8_BAR; PG8_MMA(0, 0, At, B0); PG8_MMA(0, 1, At, B1); PG8_BAR; PG8_SCHED;
;             PG8_LDA(At, 0, 1); PG8_STAGE(PG8_SB(0, 0), b2, voffB); PG8_STAGE(PG8_SB(0, 1), b2 + hstep, voffB); PG8_STAGE(PG8_SA(0, 0), a2, voffA);
;             PG8_WAIT_V(8); PG8_WAIT_L(0); PG8_BAR; PG8_MMA(1, 0, At, B0); PG8_MMA(1, 1, At, B1); PG8_BAR; PG8_SCHED;
.LBB0_169:
	s_ashr_i32 s25, s24, 31
	s_lshl_b64 s[30:31], s[24:25], 20
	s_add_u32 s25, s3, s30
	s_addc_u32 s27, s10, s31
	s_lshl_b64 s[30:31], s[0:1], 10
	s_cmp_gt_i32 s0, 0
	s_cselect_b32 s52, s30, 0
	s_cselect_b32 s51, s31, 0
	s_add_u32 s30, s25, s52
	s_addc_u32 s31, s27, s51
	s_and_b64 s[34:35], s[28:29], exec
	s_cselect_b32 s25, s31, s45
	s_cselect_b32 s50, s30, s44
	s_ashr_i32 s27, s26, 31
	s_lshl_b64 s[34:35], s[26:27], 20
	s_add_u32 s27, s74, s34
	s_addc_u32 s35, s75, s35
	s_add_u32 s34, s27, s52
	s_addc_u32 s35, s35, s51
	s_and_b64 s[52:53], s[28:29], exec
	s_cselect_b32 s27, s35, s47
	s_cselect_b32 s51, s34, s46
	s_cmp_gt_i32 s49, -1
	s_cselect_b32 s52, 8, 32
	s_add_i32 s53, s52, -2
	s_add_u32 s44, s44, 0x80080
	s_addc_u32 s45, s45, 0
	s_add_u32 s54, s46, 0x100
	s_mov_b32 s48, 0
	s_addc_u32 s55, s47, 0
	v_add_u32_e32 v222, 0x18000, v146
	v_add_u32_e32 v223, 0x1c000, v146
	ds_read_b128 v[158:161], v155
	ds_read_b128 v[162:165], v155 offset:1024
	ds_read_b128 v[166:169], v155 offset:2048
	ds_read_b128 v[170:173], v155 offset:3072
	ds_read_b128 v[174:177], v156
	ds_read_b128 v[178:181], v156 offset:1024
	ds_read_b128 v[182:185], v156 offset:2048
	ds_read_b128 v[186:189], v156 offset:3072
	s_add_i32 s56, s48, 2
	s_add_u32 s46, s44, 0xfff80080
	s_addc_u32 s47, s45, -1
	s_cmp_eq_u32 s53, s48
	s_cselect_b32 s48, s50, s46
	s_cselect_b32 s49, s25, s47
	s_cselect_b32 s47, s27, s55
	s_cselect_b32 s46, s51, s54
	s_add_i32 m0, s14, 0xc000
	ds_read_b128 v[190:193], v157
	ds_read_b128 v[194:197], v157 offset:1024
	ds_read_b128 v[198:201], v157 offset:2048
	ds_read_b128 v[202:205], v157 offset:3072
	ds_read_b128 v[206:209], v157 offset:4096
	ds_read_b128 v[210:213], v157 offset:5120
	ds_read_b128 v[214:217], v157 offset:6144
	ds_read_b128 v[218:221], v157 offset:7168
	global_load_lds_dwordx4 v136, s[44:45]
	s_add_i32 m0, s14, 0xe000
	s_nop 0
	global_load_lds_dwordx4 v138, s[44:45]
	s_waitcnt vmcnt(8) lgkmcnt(0)
	s_barrier
	v_mfma_f32_16x16x32_bf16 v[124:127], v[158:161], v[190:193], 0
	v_mfma_f32_16x16x32_bf16 v[120:123], v[166:169], v[190:193], 0
	v_mfma_f32_16x16x32_bf16 v[108:111], v[158:161], v[198:201], 0
	v_mfma_f32_16x16x32_bf16 v[104:107], v[166:169], v[198:201], 0
	v_mfma_f32_16x16x32_bf16 v[92:95], v[158:161], v[206:209], 0
	v_mfma_f32_16x16x32_bf16 v[88:91], v[166:169], v[206:209], 0
	v_mfma_f32_16x16x32_bf16 v[76:79], v[158:161], v[214:217], 0
	v_mfma_f32_16x16x32_bf16 v[72:75], v[166:169], v[214:217], 0
	v_mfma_f32_16x16x32_bf16 v[124:127], v[162:165], v[194:197], v[124:127]
	v_mfma_f32_16x16x32_bf16 v[120:123], v[170:173], v[194:197], v[120:123]
	v_mfma_f32_16x16x32_bf16 v[108:111], v[162:165], v[202:205], v[108:111]
	v_mfma_f32_16x16x32_bf16 v[104:107], v[170:173], v[202:205], v[104:107]
	v_mfma_f32_16x16x32_bf16 v[92:95], v[162:165], v[210:213], v[92:95]
	v_mfma_f32_16x16x32_bf16 v[88:91], v[170:173], v[210:213], v[88:91]
	v_mfma_f32_16x16x32_bf16 v[76:79], v[162:165], v[218:221], v[76:79]
	v_mfma_f32_16x16x32_bf16 v[72:75], v[170:173], v[218:221], v[72:75]
	v_mfma_f32_16x16x32_bf16 v[116:119], v[174:177], v[190:193], 0
	v_mfma_f32_16x16x32_bf16 v[112:115], v[182:185], v[190:193], 0
	v_mfma_f32_16x16x32_bf16 v[100:103], v[174:177], v[198:201], 0
	v_mfma_f32_16x16x32_bf16 v[96:99], v[182:185], v[198:201], 0
	v_mfma_f32_16x16x32_bf16 v[84:87], v[174:177], v[206:209], 0
	v_mfma_f32_16x16x32_bf16 v[80:83], v[182:185], v[206:209], 0
	v_mfma_f32_16x16x32_bf16 v[68:71], v[174:177], v[214:217], 0
	v_mfma_f32_16x16x32_bf16 v[64:67], v[182:185], v[214:217], 0
	v_mfma_f32_16x16x32_bf16 v[116:119], v[178:181], v[194:197], v[116:119]
	v_mfma_f32_16x16x32_bf16 v[112:115], v[186:189], v[194:197], v[112:115]
	v_mfma_f32_16x16x32_bf16 v[100:103], v[178:181], v[202:205], v[100:103]
	v_mfma_f32_16x16x32_bf16 v[96:99], v[186:189], v[202:205], v[96:99]
	v_mfma_f32_16x16x32_bf16 v[84:87], v[178:181], v[210:213], v[84:87]
	v_mfma_f32_16x16x32_bf16 v[80:83], v[186:189], v[210:213], v[80:83]
	v_mfma_f32_16x16x32_bf16 v[68:71], v[178:181], v[218:221], v[68:71]
	v_mfma_f32_16x16x32_bf16 v[64:67], v[186:189], v[218:221], v[64:67]
	s_barrier
	s_add_i32 s57, s23, s11
	s_mov_b32 m0, s57
	ds_read_b128 v[190:193], v157 offset:16384
	ds_read_b128 v[194:197], v157 offset:17408
	ds_read_b128 v[198:201], v157 offset:18432
	ds_read_b128 v[202:205], v157 offset:19456
	ds_read_b128 v[206:209], v157 offset:20480
	ds_read_b128 v[210:213], v157 offset:21504
	ds_read_b128 v[214:217], v157 offset:22528
	ds_read_b128 v[218:221], v157 offset:23552
	global_load_lds_dwordx4 v130, s[46:47]
	s_add_i32 m0, s57, 0x2000
	s_add_u32 s58, s46, 0x80000
	s_addc_u32 s59, s47, 0
	s_add_i32 s57, s33, s11
	global_load_lds_dwordx4 v134, s[46:47]
	s_mov_b32 m0, s57
	s_nop 0
	global_load_lds_dwordx4 v130, s[58:59]
	s_add_i32 m0, s57, 0x2000
	s_nop 0
	global_load_lds_dwordx4 v134, s[58:59]
	s_mov_b32 m0, s14
	s_nop 0
	global_load_lds_dwordx4 v128, s[48:49]
	s_mov_b32 m0, s15
	s_nop 0
	global_load_lds_dwordx4 v132, s[48:49]
	s_waitcnt vmcnt(8) lgkmcnt(0)
	s_barrier
; #define PG8_STAGE(bufoff, gbase, voff) do { _Pragma("unroll") for (int _i = 0; _i < 2; ++_i) \
;         __builtin_amdgcn_global_load_lds((const unsigned*)((const char*)(gbase) + (voff)[_i]), (LAS unsigned*)(lds + (bufoff) + ldsw + _i * 8192), 16, 0, 0); } while (0)
; #define PG8_LDA(dst, b, h) do { _Pragma("unroll") for (int m = 0; m < 4; ++m) _Pragma("unroll") for (int k = 0; k < 2; ++k) dst[m][k] = *(const LAS bf16x8*)(lds + PG8_SA(b, h) + aoff + m * 2048 + k * 1024); } while (0)
; #define PG8_LDB(dst, b, h) do { _Pragma("unroll") for (int n = 0; n < 2; ++n) _Pragma("unroll") for (int k = 0; k < 2; ++k) dst[n][k] = *(const LAS bf16x8*)(lds + PG8_SB(b, h) + boff + n * 2048 + k * 1024); } while (0)
; #define PG8_MMA(ai, bj, At, Bt) do { __builtin_amdgcn_s_setprio(1); _Pragma("unroll") for (int m = 0; m < 4; ++m) _Pragma("unroll") for (int n = 0; n < 2; ++n) _Pragma("unroll") for (int k = 0; k < 2; ++k) \
;         acc[ai][bj][m][n] = __builtin_amdgcn_mfma_f32_16x16x32_bf16(Bt[n][k], At[m][k], acc[ai][bj][m][n], 0, 0, 0); __builtin_amdgcn_s_setprio(0); } while (0)
; #define PG8_WAIT_V(n) asm volatile("s_waitcnt vmcnt(" #n ")" ::: "memory")
; #define PG8_WAIT_L(n) asm volatile("s_waitcnt lgkmcnt(" #n ")" ::: "memory")
; #define PG8_BAR __builtin_amdgcn_s_barrier()
; #define PG8_SCHED __builtin_amdgcn_sched_barrier(0)
; __device__ __forceinline__ void gemm_phase(LAS unsigned char* lds, const Params& p, const bf16_t* gA, const bf16_t* gBt, const int gM, const int gN, const int gK, const int epi, const int perm, bf16_t* const Hp, const int goff, const float coef) {
;     ...
;             PG8_WAIT_V(8); PG8_WAIT_L(0); PG8_BAR; PG8_MMA(1, 0, At, B0); PG8_MMA(1, 1, At, B1); PG8_BAR; PG8_SCHED;
;             PG8_LDB(B0, 1, 0); PG8_LDB(B1, 1, 1); PG8_SCHED; PG8_LDA(At, 1, 0); PG8_STAGE(PG8_SA(0, 1), a2 + hstep, voffA);
;             PG8_WAIT_V(8); PG8_WAIT_L(0); PG8_BAR; PG8_MMA(0, 0, At, B0); PG8_MMA(0, 1, At, B1); PG8_BAR; PG8_SCHED;
	v_mfma_f32_16x16x32_bf16 v[60:63], v[158:161], v[190:193], 0
	v_mfma_f32_16x16x32_bf16 v[56:59], v[166:169], v[190:193], 0
	v_mfma_f32_16x16x32_bf16 v[44:47], v[158:161], v[198:201], 0
	v_mfma_f32_16x16x32_bf16 v[40:43], v[166:169], v[198:201], 0
	v_mfma_f32_16x16x32_bf16 v[28:31], v[158:161], v[206:209], 0
	v_mfma_f32_16x16x32_bf16 v[24:27], v[166:169], v[206:209], 0
	v_mfma_f32_16x16x32_bf16 v[12:15], v[158:161], v[214:217], 0
	v_mfma_f32_16x16x32_bf16 v[8:11], v[166:169], v[214:217], 0
	v_mfma_f32_16x16x32_bf16 v[60:63], v[162:165], v[194:197], v[60:63]
	v_mfma_f32_16x16x32_bf16 v[56:59], v[170:173], v[194:197], v[56:59]
	v_mfma_f32_16x16x32_bf16 v[44:47], v[162:165], v[202:205], v[44:47]
	v_mfma_f32_16x16x32_bf16 v[40:43], v[170:173], v[202:205], v[40:43]
	v_mfma_f32_16x16x32_bf16 v[28:31], v[162:165], v[210:213], v[28:31]
	v_mfma_f32_16x16x32_bf16 v[24:27], v[170:173], v[210:213], v[24:27]
	v_mfma_f32_16x16x32_bf16 v[12:15], v[162:165], v[218:221], v[12:15]
	v_mfma_f32_16x16x32_bf16 v[8:11], v[170:173], v[218:221], v[8:11]
	v_mfma_f32_16x16x32_bf16 v[52:55], v[174:177], v[190:193], 0
	v_mfma_f32_16x16x32_bf16 v[48:51], v[182:185], v[190:193], 0
	v_mfma_f32_16x16x32_bf16 v[36:39], v[174:177], v[198:201], 0
	v_mfma_f32_16x16x32_bf16 v[32:35], v[182:185], v[198:201], 0
	v_mfma_f32_16x16x32_bf16 v[20:23], v[174:177], v[206:209], 0
	v_mfma_f32_16x16x32_bf16 v[16:19], v[182:185], v[206:209], 0
	v_mfma_f32_16x16x32_bf16 v[4:7], v[174:177], v[214:217], 0
	v_mfma_f32_16x16x32_bf16 v[0:3], v[182:185], v[214:217], 0
	v_mfma_f32_16x16x32_bf16 v[52:55], v[178:181], v[194:197], v[52:55]
	v_mfma_f32_16x16x32_bf16 v[48:51], v[186:189], v[194:197], v[48:51]
	v_mfma_f32_16x16x32_bf16 v[36:39], v[178:181], v[202:205], v[36:39]
	v_mfma_f32_16x16x32_bf16 v[32:35], v[186:189], v[202:205], v[32:35]
	v_mfma_f32_16x16x32_bf16 v[20:23], v[178:181], v[210:213], v[20:23]
	v_mfma_f32_16x16x32_bf16 v[16:19], v[186:189], v[210:213], v[16:19]
	v_mfma_f32_16x16x32_bf16 v[4:7], v[178:181], v[218:221], v[4:7]
	v_mfma_f32_16x16x32_bf16 v[0:3], v[186:189], v[218:221], v[0:3]
	s_barrier
	s_add_i32 s57, 0, 0x18000
	s_add_i32 s58, 0, 0x1c000
	ds_read_b128 v[158:161], v222
	ds_read_b128 v[162:165], v222 offset:1024
	ds_read_b128 v[166:169], v222 offset:2048
	ds_read_b128 v[170:173], v222 offset:3072
	ds_read_b128 v[174:177], v223
	ds_read_b128 v[178:181], v223 offset:1024
	ds_read_b128 v[182:185], v223 offset:2048
	ds_read_b128 v[186:189], v223 offset:3072
	s_add_u32 s48, s48, 0x80000
	s_addc_u32 s49, s49, 0
	s_mov_b32 m0, s16
	ds_read_b128 v[190:193], v157 offset:32768
	ds_read_b128 v[194:197], v157 offset:33792
	ds_read_b128 v[198:201], v157 offset:34816
	ds_read_b128 v[202:205], v157 offset:35840
	ds_read_b128 v[206:209], v157 offset:36864
	ds_read_b128 v[210:213], v157 offset:37888
	ds_read_b128 v[214:217], v157 offset:38912
	ds_read_b128 v[218:221], v157 offset:39936
	global_load_lds_dwordx4 v128, s[48:49]
	s_mov_b32 m0, s17
	s_nop 0
	global_load_lds_dwordx4 v132, s[48:49]
	s_waitcnt vmcnt(8) lgkmcnt(0)
	s_barrier
	v_mfma_f32_16x16x32_bf16 v[124:127], v[158:161], v[190:193], v[124:127]
	v_mfma_f32_16x16x32_bf16 v[120:123], v[166:169], v[190:193], v[120:123]
	v_mfma_f32_16x16x32_bf16 v[108:111], v[158:161], v[198:201], v[108:111]
	v_mfma_f32_16x16x32_bf16 v[104:107], v[166:169], v[198:201], v[104:107]
	v_mfma_f32_16x16x32_bf16 v[92:95], v[158:161], v[206:209], v[92:95]
	v_mfma_f32_16x16x32_bf16 v[88:91], v[166:169], v[206:209], v[88:91]
	v_mfma_f32_16x16x32_bf16 v[76:79], v[158:161], v[214:217], v[76:79]
	v_mfma_f32_16x16x32_bf16 v[72:75], v[166:169], v[214:217], v[72:75]
	v_mfma_f32_16x16x32_bf16 v[124:127], v[162:165], v[194:197], v[124:127]
	v_mfma_f32_16x16x32_bf16 v[120:123], v[170:173], v[194:197], v[120:123]
	v_mfma_f32_16x16x32_bf16 v[108:111], v[162:165], v[202:205], v[108:111]
	v_mfma_f32_16x16x32_bf16 v[104:107], v[170:173], v[202:205], v[104:107]
	v_mfma_f32_16x16x32_bf16 v[92:95], v[162:165], v[210:213], v[92:95]
	v_mfma_f32_16x16x32_bf16 v[88:91], v[170:173], v[210:213], v[88:91]
	v_mfma_f32_16x16x32_bf16 v[76:79], v[162:165], v[218:221], v[76:79]
	v_mfma_f32_16x16x32_bf16 v[72:75], v[170:173], v[218:221], v[72:75]
	v_mfma_f32_16x16x32_bf16 v[116:119], v[174:177], v[190:193], v[116:119]
	v_mfma_f32_16x16x32_bf16 v[112:115], v[182:185], v[190:193], v[112:115]
	v_mfma_f32_16x16x32_bf16 v[100:103], v[174:177], v[198:201], v[100:103]
	v_mfma_f32_16x16x32_bf16 v[96:99], v[182:185], v[198:201], v[96:99]
	v_mfma_f32_16x16x32_bf16 v[84:87], v[174:177], v[206:209], v[84:87]
	v_mfma_f32_16x16x32_bf16 v[80:83], v[182:185], v[206:209], v[80:83]
	v_mfma_f32_16x16x32_bf16 v[68:71], v[174:177], v[214:217], v[68:71]
	v_mfma_f32_16x16x32_bf16 v[64:67], v[182:185], v[214:217], v[64:67]
	v_mfma_f32_16x16x32_bf16 v[116:119], v[178:181], v[194:197], v[116:119]
	v_mfma_f32_16x16x32_bf16 v[112:115], v[186:189], v[194:197], v[112:115]
	v_mfma_f32_16x16x32_bf16 v[100:103], v[178:181], v[202:205], v[100:103]
	v_mfma_f32_16x16x32_bf16 v[96:99], v[186:189], v[202:205], v[96:99]
	v_mfma_f32_16x16x32_bf16 v[84:87], v[178:181], v[210:213], v[84:87]
	v_mfma_f32_16x16x32_bf16 v[80:83], v[186:189], v[210:213], v[80:83]
	v_mfma_f32_16x16x32_bf16 v[68:71], v[178:181], v[218:221], v[68:71]
	v_mfma_f32_16x16x32_bf16 v[64:67], v[186:189], v[218:221], v[64:67]
	s_barrier
; #define PG8_STAGE(bufoff, gbase, voff) do { _Pragma("unroll") for (int _i = 0; _i < 2; ++_i) \
;         __builtin_amdgcn_global_load_lds((const unsigned*)((const char*)(gbase) + (voff)[_i]), (LAS unsigned*)(lds + (bufoff) + ldsw + _i * 8192), 16, 0, 0); } while (0)
; #define PG8_LDA(dst, b, h) do { _Pragma("unroll") for (int m = 0; m < 4; ++m) _Pragma("unroll") for (int k = 0; k < 2; ++k) dst[m][k] = *(const LAS bf16x8*)(lds + PG8_SA(b, h) + aoff + m * 2048 + k * 1024); } while (0)
; #define PG8_LDB(dst, b, h) do { _Pragma("unroll") for (int n = 0; n < 2; ++n) _Pragma("unroll") for (int k = 0; k < 2; ++k) dst[n][k] = *(const LAS bf16x8*)(lds + PG8_SB(b, h) + boff + n * 2048 + k * 1024); } while (0)
; #define PG8_BAR __builtin_amdgcn_s_barrier()
; __device__ __forceinline__ void gemm_phase(LAS unsigned char* lds, const Params& p, const bf16_t* gA, const bf16_t* gBt, const int gM, const int gN, const int gK, const int epi, const int perm, bf16_t* const Hp, const int goff, const float coef) {
;     ...
;         for (int t = 0; t < nt; t += 2) {
;             const bool last = (t == nt - 2);
;             const char* a1 = cA + (size_t)(t + 1) * kstep;
;             const char* a2 = last ? nA : cA + (size_t)(t + 2) * kstep; const char* b2 = last ? nB : cB + (size_t)(t + 2) * kstep;
;             const char* a3 = a2 + kstep; const char* b3 = b2 + kstep;
;             PG8_LDB(B0, 0, 0); PG8_LDB(B1, 0, 1); PG8_SCHED; PG8_LDA(At, 0, 0); PG8_STAGE(PG8_SA(1, 1), a1 + hstep, voffA);
;             PG8_WAIT_V(8); PG8_WAIT_L(0); PG8_BAR; PG8_MMA(0, 0, At, B0); PG8_MMA(0, 1, At, B1); PG8_BAR; PG8_SCHED;
;             PG8_LDA(At, 0, 1); PG8_STAGE(PG8_SB(0, 0), b2, voffB); PG8_STAGE(PG8_SB(0, 1), b2 + hstep, voffB); PG8_STAGE(PG8_SA(0, 0), a2, voffA);
;             PG8_WAIT_V(8); PG8_WAIT_L(0); PG8_BAR; PG8_MMA(1, 0, At, B0); PG8_MMA(1, 1, At, B1); PG8_BAR; PG8_SCHED;
;             PG8_LDB(B0, 1, 0); PG8_LDB(B1, 1, 1); PG8_SCHED; PG8_LDA(At, 1, 0); PG8_STAGE(PG8_SA(0, 1), a2 + hstep, voffA);
;             PG8_WAIT_V(8); PG8_WAIT_L(0); PG8_BAR; PG8_MMA(0, 0, At, B0); PG8_MMA(0, 1, At, B1); PG8_BAR; PG8_SCHED;
;             PG8_LDA(At, 1, 1); PG8_STAGE(PG8_SB(1, 0), b3, voffB); PG8_STAGE(PG8_SB(1, 1), b3 + hstep, voffB); PG8_STAGE(PG8_SA(1, 0), a3, voffA);
;             PG8_WAIT_V(8); PG8_WAIT_L(0); PG8_BAR; PG8_MMA(1, 0, At, B0); PG8_MMA(1, 1, At, B1); PG8_BAR; PG8_SCHED;
	s_mov_b64 s[98:99], s[48:49]
	s_add_i32 s48, s57, s11
	s_mov_b32 m0, s48
	ds_read_b128 v[190:193], v157 offset:49152
	ds_read_b128 v[194:197], v157 offset:50176
	ds_read_b128 v[198:201], v157 offset:51200
	ds_read_b128 v[202:205], v157 offset:52224
	ds_read_b128 v[206:209], v157 offset:53248
	ds_read_b128 v[210:213], v157 offset:54272
	ds_read_b128 v[214:217], v157 offset:55296
	ds_read_b128 v[218:221], v157 offset:56320
	s_add_u32 s100, s46, 0x80
	s_addc_u32 s101, s47, 0
	global_load_lds_dwordx4 v130, s[100:101]
	s_add_i32 m0, s48, 0x2000
	s_add_u32 s46, s46, 0x80080
	s_addc_u32 s47, s47, 0
	s_add_i32 s48, s58, s11
	global_load_lds_dwordx4 v134, s[100:101]
	s_mov_b32 m0, s48
	s_nop 0
	global_load_lds_dwordx4 v130, s[46:47]
	s_add_i32 m0, s48, 0x2000
	s_nop 0
	global_load_lds_dwordx4 v134, s[46:47]
	s_mov_b32 m0, s19
	s_add_u32 s100, s98, 0xfff80080
	s_addc_u32 s101, s99, -1
	global_load_lds_dwordx4 v128, s[100:101]
	s_mov_b32 m0, s20
	s_nop 0
	global_load_lds_dwordx4 v132, s[100:101]
	s_waitcnt vmcnt(8) lgkmcnt(0)
	s_barrier
	v_mfma_f32_16x16x32_bf16 v[60:63], v[158:161], v[190:193], v[60:63]
	v_mfma_f32_16x16x32_bf16 v[56:59], v[166:169], v[190:193], v[56:59]
	v_mfma_f32_16x16x32_bf16 v[44:47], v[158:161], v[198:201], v[44:47]
	v_mfma_f32_16x16x32_bf16 v[40:43], v[166:169], v[198:201], v[40:43]
	v_mfma_f32_16x16x32_bf16 v[28:31], v[158:161], v[206:209], v[28:31]
	v_mfma_f32_16x16x32_bf16 v[24:27], v[166:169], v[206:209], v[24:27]
	v_mfma_f32_16x16x32_bf16 v[12:15], v[158:161], v[214:217], v[12:15]
	v_mfma_f32_16x16x32_bf16 v[8:11], v[166:169], v[214:217], v[8:11]
	v_mfma_f32_16x16x32_bf16 v[60:63], v[162:165], v[194:197], v[60:63]
	v_mfma_f32_16x16x32_bf16 v[56:59], v[170:173], v[194:197], v[56:59]
	v_mfma_f32_16x16x32_bf16 v[44:47], v[162:165], v[202:205], v[44:47]
	v_mfma_f32_16x16x32_bf16 v[40:43], v[170:173], v[202:205], v[40:43]
	v_mfma_f32_16x16x32_bf16 v[28:31], v[162:165], v[210:213], v[28:31]
	v_mfma_f32_16x16x32_bf16 v[24:27], v[170:173], v[210:213], v[24:27]
	v_mfma_f32_16x16x32_bf16 v[12:15], v[162:165], v[218:221], v[12:15]
	v_mfma_f32_16x16x32_bf16 v[8:11], v[170:173], v[218:221], v[8:11]
	v_mfma_f32_16x16x32_bf16 v[52:55], v[174:177], v[190:193], v[52:55]
	v_mfma_f32_16x16x32_bf16 v[48:51], v[182:185], v[190:193], v[48:51]
	v_mfma_f32_16x16x32_bf16 v[36:39], v[174:177], v[198:201], v[36:39]
	v_mfma_f32_16x16x32_bf16 v[32:35], v[182:185], v[198:201], v[32:35]
	v_mfma_f32_16x16x32_bf16 v[20:23], v[174:177], v[206:209], v[20:23]
	v_mfma_f32_16x16x32_bf16 v[16:19], v[182:185], v[206:209], v[16:19]
	v_mfma_f32_16x16x32_bf16 v[4:7], v[174:177], v[214:217], v[4:7]
	v_mfma_f32_16x16x32_bf16 v[0:3], v[182:185], v[214:217], v[0:3]
	v_mfma_f32_16x16x32_bf16 v[52:55], v[178:181], v[194:197], v[52:55]
	v_mfma_f32_16x16x32_bf16 v[48:51], v[186:189], v[194:197], v[48:51]
	v_mfma_f32_16x16x32_bf16 v[36:39], v[178:181], v[202:205], v[36:39]
	v_mfma_f32_16x16x32_bf16 v[32:35], v[186:189], v[202:205], v[32:35]
	v_mfma_f32_16x16x32_bf16 v[20:23], v[178:181], v[210:213], v[20:23]
	v_mfma_f32_16x16x32_bf16 v[16:19], v[186:189], v[210:213], v[16:19]
	v_mfma_f32_16x16x32_bf16 v[4:7], v[178:181], v[218:221], v[4:7]
	v_mfma_f32_16x16x32_bf16 v[0:3], v[186:189], v[218:221], v[0:3]
	s_barrier
	s_add_u32 s44, s44, 0x100
	s_addc_u32 s45, s45, 0
	s_add_u32 s54, s54, 0x100
	s_addc_u32 s55, s55, 0
	s_cmp_ge_u32 s56, s52
	s_mov_b32 s48, s56
	s_cbranch_scc1 .Lpeel_exit_0
.LBB0_170:
	ds_read_b128 v[158:161], v155
	ds_read_b128 v[162:165], v155 offset:1024
	ds_read_b128 v[166:169], v155 offset:2048
	ds_read_b128 v[170:173], v155 offset:3072
	ds_read_b128 v[174:177], v156
	ds_read_b128 v[178:181], v156 offset:1024
	ds_read_b128 v[182:185], v156 offset:2048
	ds_read_b128 v[186:189], v156 offset:3072
	s_add_i32 s56, s48, 2
	s_add_u32 s46, s44, 0xfff80080
	s_addc_u32 s47, s45, -1
	s_cmp_eq_u32 s53, s48
	s_cselect_b32 s48, s50, s46
	s_cselect_b32 s49, s25, s47
	s_cselect_b32 s47, s27, s55
	s_cselect_b32 s46, s51, s54
	s_add_i32 m0, s14, 0xc000
	ds_read_b128 v[190:193], v157
	ds_read_b128 v[194:197], v157 offset:1024
	ds_read_b128 v[198:201], v157 offset:2048
	ds_read_b128 v[202:205], v157 offset:3072
	ds_read_b128 v[206:209], v157 offset:4096
	ds_read_b128 v[210:213], v157 offset:5120
	ds_read_b128 v[214:217], v157 offset:6144
	ds_read_b128 v[218:221], v157 offset:7168
	global_load_lds_dwordx4 v136, s[44:45]
	s_add_i32 m0, s14, 0xe000
	s_nop 0
	global_load_lds_dwordx4 v138, s[44:45]
	s_waitcnt vmcnt(8) lgkmcnt(0)
	s_barrier
	v_mfma_f32_16x16x32_bf16 v[124:127], v[158:161], v[190:193], v[124:127]
	v_mfma_f32_16x16x32_bf16 v[120:123], v[166:169], v[190:193], v[120:123]
	v_mfma_f32_16x16x32_bf16 v[108:111], v[158:161], v[198:201], v[108:111]
	v_mfma_f32_16x16x32_bf16 v[104:107], v[166:169], v[198:201], v[104:107]
	v_mfma_f32_16x16x32_bf16 v[92:95], v[158:161], v[206:209], v[92:95]
	v_mfma_f32_16x16x32_bf16 v[88:91], v[166:169], v[206:209], v[88:91]
	v_mfma_f32_16x16x32_bf16 v[76:79], v[158:161], v[214:217], v[76:79]
	v_mfma_f32_16x16x32_bf16 v[72:75], v[166:169], v[214:217], v[72:75]
	v_mfma_f32_16x16x32_bf16 v[124:127], v[162:165], v[194:197], v[124:127]
	v_mfma_f32_16x16x32_bf16 v[120:123], v[170:173], v[194:197], v[120:123]
	v_mfma_f32_16x16x32_bf16 v[108:111], v[162:165], v[202:205], v[108:111]
	v_mfma_f32_16x16x32_bf16 v[104:107], v[170:173], v[202:205], v[104:107]
	v_mfma_f32_16x16x32_bf16 v[92:95], v[162:165], v[210:213], v[92:95]
	v_mfma_f32_16x16x32_bf16 v[88:91], v[170:173], v[210:213], v[88:91]
	v_mfma_f32_16x16x32_bf16 v[76:79], v[162:165], v[218:221], v[76:79]
	v_mfma_f32_16x16x32_bf16 v[72:75], v[170:173], v[218:221], v[72:75]
	v_mfma_f32_16x16x32_bf16 v[116:119], v[174:177], v[190:193], v[116:119]
	v_mfma_f32_16x16x32_bf16 v[112:115], v[182:185], v[190:193], v[112:115]
	v_mfma_f32_16x16x32_bf16 v[100:103], v[174:177], v[198:201], v[100:103]
	v_mfma_f32_16x16x32_bf16 v[96:99], v[182:185], v[198:201], v[96:99]
	v_mfma_f32_16x16x32_bf16 v[84:87], v[174:177], v[206:209], v[84:87]
	v_mfma_f32_16x16x32_bf16 v[80:83], v[182:185], v[206:209], v[80:83]
	v_mfma_f32_16x16x32_bf16 v[68:71], v[174:177], v[214:217], v[68:71]
	v_mfma_f32_16x16x32_bf16 v[64:67], v[182:185], v[214:217], v[64:67]
	v_mfma_f32_16x16x32_bf16 v[116:119], v[178:181], v[194:197], v[116:119]
	v_mfma_f32_16x16x32_bf16 v[112:115], v[186:189], v[194:197], v[112:115]
	v_mfma_f32_16x16x32_bf16 v[100:103], v[178:181], v[202:205], v[100:103]
	v_mfma_f32_16x16x32_bf16 v[96:99], v[186:189], v[202:205], v[96:99]
	v_mfma_f32_16x16x32_bf16 v[84:87], v[178:181], v[210:213], v[84:87]
	v_mfma_f32_16x16x32_bf16 v[80:83], v[186:189], v[210:213], v[80:83]
	v_mfma_f32_16x16x32_bf16 v[68:71], v[178:181], v[218:221], v[68:71]
	v_mfma_f32_16x16x32_bf16 v[64:67], v[186:189], v[218:221], v[64:67]
	s_barrier
; #define PG8_STAGE(bufoff, gbase, voff) do { _Pragma("unroll") for (int _i = 0; _i < 2; ++_i) \
;         __builtin_amdgcn_global_load_lds((const unsigned*)((const char*)(gbase) + (voff)[_i]), (LAS unsigned*)(lds + (bufoff) + ldsw + _i * 8192), 16, 0, 0); } while (0)
; #define PG8_LDA(dst, b, h) do { _Pragma("unroll") for (int m = 0; m < 4; ++m) _Pragma("unroll") for (int k = 0; k < 2; ++k) dst[m][k] = *(const LAS bf16x8*)(lds + PG8_SA(b, h) + aoff + m * 2048 + k * 1024); } while (0)
; #define PG8_LDB(dst, b, h) do { _Pragma("unroll") for (int n = 0; n < 2; ++n) _Pragma("unroll") for (int k = 0; k < 2; ++k) dst[n][k] = *(const LAS bf16x8*)(lds + PG8_SB(b, h) + boff + n * 2048 + k * 1024); } while (0)
; #define PG8_MMA(ai, bj, At, Bt) do { __builtin_amdgcn_s_setprio(1); _Pragma("unroll") for (int m = 0; m < 4; ++m) _Pragma("unroll") for (int n = 0; n < 2; ++n) _Pragma("unroll") for (int k = 0; k < 2; ++k) \
;         acc[ai][bj][m][n] = __builtin_amdgcn_mfma_f32_16x16x32_bf16(Bt[n][k], At[m][k], acc[ai][bj][m][n], 0, 0, 0); __builtin_amdgcn_s_setprio(0); } while (0)
; #define PG8_WAIT_V(n) asm volatile("s_waitcnt vmcnt(" #n ")" ::: "memory")
; #define PG8_WAIT_L(n) asm volatile("s_waitcnt lgkmcnt(" #n ")" ::: "memory")
; #define PG8_BAR __builtin_amdgcn_s_barrier()
; #define PG8_SCHED __builtin_amdgcn_sched_barrier(0)
; __device__ __forceinline__ void gemm_phase(LAS unsigned char* lds, const Params& p, const bf16_t* gA, const bf16_t* gBt, const int gM, const int gN, const int gK, const int epi, const int perm, bf16_t* const Hp, const int goff, const float coef) {
;     ...
;             PG8_LDA(At, 0, 1); PG8_STAGE(PG8_SB(0, 0), b2, voffB); PG8_STAGE(PG8_SB(0, 1), b2 + hstep, voffB); PG8_STAGE(PG8_SA(0, 0), a2, voffA);
;             PG8_WAIT_V(8); PG8_WAIT_L(0); PG8_BAR; PG8_MMA(1, 0, At, B0); PG8_MMA(1, 1, At, B1); PG8_BAR; PG8_SCHED;
;             PG8_LDB(B0, 1, 0); PG8_LDB(B1, 1, 1); PG8_SCHED; PG8_LDA(At, 1, 0); PG8_STAGE(PG8_SA(0, 1), a2 + hstep, voffA);
;             PG8_WAIT_V(8); PG8_WAIT_L(0); PG8_BAR; PG8_MMA(0, 0, At, B0); PG8_MMA(0, 1, At, B1); PG8_BAR; PG8_SCHED;
	s_add_i32 s57, s23, s11
	s_mov_b32 m0, s57
	ds_read_b128 v[190:193], v157 offset:16384
	ds_read_b128 v[194:197], v157 offset:17408
	ds_read_b128 v[198:201], v157 offset:18432
	ds_read_b128 v[202:205], v157 offset:19456
	ds_read_b128 v[206:209], v157 offset:20480
	ds_read_b128 v[210:213], v157 offset:21504
	ds_read_b128 v[214:217], v157 offset:22528
	ds_read_b128 v[218:221], v157 offset:23552
	global_load_lds_dwordx4 v130, s[46:47]
	s_add_i32 m0, s57, 0x2000
	s_add_u32 s58, s46, 0x80000
	s_addc_u32 s59, s47, 0
	s_add_i32 s57, s33, s11
	global_load_lds_dwordx4 v134, s[46:47]
	s_mov_b32 m0, s57
	s_nop 0
	global_load_lds_dwordx4 v130, s[58:59]
	s_add_i32 m0, s57, 0x2000
	s_nop 0
	global_load_lds_dwordx4 v134, s[58:59]
	s_mov_b32 m0, s14
	s_nop 0
	global_load_lds_dwordx4 v128, s[48:49]
	s_mov_b32 m0, s15
	s_nop 0
	global_load_lds_dwordx4 v132, s[48:49]
	s_waitcnt vmcnt(8) lgkmcnt(0)
	s_barrier
	v_mfma_f32_16x16x32_bf16 v[60:63], v[158:161], v[190:193], v[60:63]
	v_mfma_f32_16x16x32_bf16 v[56:59], v[166:169], v[190:193], v[56:59]
	v_mfma_f32_16x16x32_bf16 v[44:47], v[158:161], v[198:201], v[44:47]
	v_mfma_f32_16x16x32_bf16 v[40:43], v[166:169], v[198:201], v[40:43]
	v_mfma_f32_16x16x32_bf16 v[28:31], v[158:161], v[206:209], v[28:31]
	v_mfma_f32_16x16x32_bf16 v[24:27], v[166:169], v[206:209], v[24:27]
	v_mfma_f32_16x16x32_bf16 v[12:15], v[158:161], v[214:217], v[12:15]
	v_mfma_f32_16x16x32_bf16 v[8:11], v[166:169], v[214:217], v[8:11]
	v_mfma_f32_16x16x32_bf16 v[60:63], v[162:165], v[194:197], v[60:63]
	v_mfma_f32_16x16x32_bf16 v[56:59], v[170:173], v[194:197], v[56:59]
	v_mfma_f32_16x16x32_bf16 v[44:47], v[162:165], v[202:205], v[44:47]
	v_mfma_f32_16x16x32_bf16 v[40:43], v[170:173], v[202:205], v[40:43]
	v_mfma_f32_16x16x32_bf16 v[28:31], v[162:165], v[210:213], v[28:31]
	v_mfma_f32_16x16x32_bf16 v[24:27], v[170:173], v[210:213], v[24:27]
	v_mfma_f32_16x16x32_bf16 v[12:15], v[162:165], v[218:221], v[12:15]
	v_mfma_f32_16x16x32_bf16 v[8:11], v[170:173], v[218:221], v[8:11]
	v_mfma_f32_16x16x32_bf16 v[52:55], v[174:177], v[190:193], v[52:55]
	v_mfma_f32_16x16x32_bf16 v[48:51], v[182:185], v[190:193], v[48:51]
	v_mfma_f32_16x16x32_bf16 v[36:39], v[174:177], v[198:201], v[36:39]
	v_mfma_f32_16x16x32_bf16 v[32:35], v[182:185], v[198:201], v[32:35]
	v_mfma_f32_16x16x32_bf16 v[20:23], v[174:177], v[206:209], v[20:23]
	v_mfma_f32_16x16x32_bf16 v[16:19], v[182:185], v[206:209], v[16:19]
	v_mfma_f32_16x16x32_bf16 v[4:7], v[174:177], v[214:217], v[4:7]
	v_mfma_f32_16x16x32_bf16 v[0:3], v[182:185], v[214:217], v[0:3]
	v_mfma_f32_16x16x32_bf16 v[52:55], v[178:181], v[194:197], v[52:55]
	v_mfma_f32_16x16x32_bf16 v[48:51], v[186:189], v[194:197], v[48:51]
	v_mfma_f32_16x16x32_bf16 v[36:39], v[178:181], v[202:205], v[36:39]
	v_mfma_f32_16x16x32_bf16 v[32:35], v[186:189], v[202:205], v[32:35]
	v_mfma_f32_16x16x32_bf16 v[20:23], v[178:181], v[210:213], v[20:23]
	v_mfma_f32_16x16x32_bf16 v[16:19], v[186:189], v[210:213], v[16:19]
	v_mfma_f32_16x16x32_bf16 v[4:7], v[178:181], v[218:221], v[4:7]
	v_mfma_f32_16x16x32_bf16 v[0:3], v[186:189], v[218:221], v[0:3]
	s_barrier
	s_add_i32 s57, 0, 0x18000
	s_add_i32 s58, 0, 0x1c000
	ds_read_b128 v[158:161], v222
	ds_read_b128 v[162:165], v222 offset:1024
	ds_read_b128 v[166:169], v222 offset:2048
	ds_read_b128 v[170:173], v222 offset:3072
	ds_read_b128 v[174:177], v223
	ds_read_b128 v[178:181], v223 offset:1024
	ds_read_b128 v[182:185], v223 offset:2048
	ds_read_b128 v[186:189], v223 offset:3072
	s_add_u32 s48, s48, 0x80000
	s_addc_u32 s49, s49, 0
	s_mov_b32 m0, s16
	ds_read_b128 v[190:193], v157 offset:32768
	ds_read_b128 v[194:197], v157 offset:33792
	ds_read_b128 v[198:201], v157 offset:34816
	ds_read_b128 v[202:205], v157 offset:35840
	ds_read_b128 v[206:209], v157 offset:36864
	ds_read_b128 v[210:213], v157 offset:37888
	ds_read_b128 v[214:217], v157 offset:38912
	ds_read_b128 v[218:221], v157 offset:39936
	global_load_lds_dwordx4 v128, s[48:49]
	s_mov_b32 m0, s17
	s_nop 0
	global_load_lds_dwordx4 v132, s[48:49]
	s_waitcnt vmcnt(8) lgkmcnt(0)
	s_barrier
; #define PG8_STAGE(bufoff, gbase, voff) do { _Pragma("unroll") for (int _i = 0; _i < 2; ++_i) \
;         __builtin_amdgcn_global_load_lds((const unsigned*)((const char*)(gbase) + (voff)[_i]), (LAS unsigned*)(lds + (bufoff) + ldsw + _i * 8192), 16, 0, 0); } while (0)
; #define PG8_LDA(dst, b, h) do { _Pragma("unroll") for (int m = 0; m < 4; ++m) _Pragma("unroll") for (int k = 0; k < 2; ++k) dst[m][k] = *(const LAS bf16x8*)(lds + PG8_SA(b, h) + aoff + m * 2048 + k * 1024); } while (0)
; #define PG8_MMA(ai, bj, At, Bt) do { __builtin_amdgcn_s_setprio(1); _Pragma("unroll") for (int m = 0; m < 4; ++m) _Pragma("unroll") for (int n = 0; n < 2; ++n) _Pragma("unroll") for (int k = 0; k < 2; ++k) \
;         acc[ai][bj][m][n] = __builtin_amdgcn_mfma_f32_16x16x32_bf16(Bt[n][k], At[m][k], acc[ai][bj][m][n], 0, 0, 0); __builtin_amdgcn_s_setprio(0); } while (0)
; #define PG8_WAIT_V(n) asm volatile("s_waitcnt vmcnt(" #n ")" ::: "memory")
; #define PG8_WAIT_L(n) asm volatile("s_waitcnt lgkmcnt(" #n ")" ::: "memory")
; #define PG8_BAR __builtin_amdgcn_s_barrier()
; #define PG8_SCHED __builtin_amdgcn_sched_barrier(0)
; __device__ __forceinline__ void gemm_phase(LAS unsigned char* lds, const Params& p, const bf16_t* gA, const bf16_t* gBt, const int gM, const int gN, const int gK, const int epi, const int perm, bf16_t* const Hp, const int goff, const float coef) {
;     ...
;             PG8_WAIT_V(8); PG8_WAIT_L(0); PG8_BAR; PG8_MMA(0, 0, At, B0); PG8_MMA(0, 1, At, B1); PG8_BAR; PG8_SCHED;
;             PG8_LDA(At, 1, 1); PG8_STAGE(PG8_SB(1, 0), b3, voffB); PG8_STAGE(PG8_SB(1, 1), b3 + hstep, voffB); PG8_STAGE(PG8_SA(1, 0), a3, voffA);
;             PG8_WAIT_V(8); PG8_WAIT_L(0); PG8_BAR; PG8_MMA(1, 0, At, B0); PG8_MMA(1, 1, At, B1); PG8_BAR; PG8_SCHED;
;         }
	v_mfma_f32_16x16x32_bf16 v[124:127], v[158:161], v[190:193], v[124:127]
	v_mfma_f32_16x16x32_bf16 v[120:123], v[166:169], v[190:193], v[120:123]
	v_mfma_f32_16x16x32_bf16 v[108:111], v[158:161], v[198:201], v[108:111]
	v_mfma_f32_16x16x32_bf16 v[104:107], v[166:169], v[198:201], v[104:107]
	v_mfma_f32_16x16x32_bf16 v[92:95], v[158:161], v[206:209], v[92:95]
	v_mfma_f32_16x16x32_bf16 v[88:91], v[166:169], v[206:209], v[88:91]
	v_mfma_f32_16x16x32_bf16 v[76:79], v[158:161], v[214:217], v[76:79]
	v_mfma_f32_16x16x32_bf16 v[72:75], v[166:169], v[214:217], v[72:75]
	v_mfma_f32_16x16x32_bf16 v[124:127], v[162:165], v[194:197], v[124:127]
	v_mfma_f32_16x16x32_bf16 v[120:123], v[170:173], v[194:197], v[120:123]
	v_mfma_f32_16x16x32_bf16 v[108:111], v[162:165], v[202:205], v[108:111]
	v_mfma_f32_16x16x32_bf16 v[104:107], v[170:173], v[202:205], v[104:107]
	v_mfma_f32_16x16x32_bf16 v[92:95], v[162:165], v[210:213], v[92:95]
	v_mfma_f32_16x16x32_bf16 v[88:91], v[170:173], v[210:213], v[88:91]
	v_mfma_f32_16x16x32_bf16 v[76:79], v[162:165], v[218:221], v[76:79]
	v_mfma_f32_16x16x32_bf16 v[72:75], v[170:173], v[218:221], v[72:75]
	v_mfma_f32_16x16x32_bf16 v[116:119], v[174:177], v[190:193], v[116:119]
	v_mfma_f32_16x16x32_bf16 v[112:115], v[182:185], v[190:193], v[112:115]
	v_mfma_f32_16x16x32_bf16 v[100:103], v[174:177], v[198:201], v[100:103]
	v_mfma_f32_16x16x32_bf16 v[96:99], v[182:185], v[198:201], v[96:99]
	v_mfma_f32_16x16x32_bf16 v[84:87], v[174:177], v[206:209], v[84:87]
	v_mfma_f32_16x16x32_bf16 v[80:83], v[182:185], v[206:209], v[80:83]
	v_mfma_f32_16x16x32_bf16 v[68:71], v[174:177], v[214:217], v[68:71]
	v_mfma_f32_16x16x32_bf16 v[64:67], v[182:185], v[214:217], v[64:67]
	v_mfma_f32_16x16x32_bf16 v[116:119], v[178:181], v[194:197], v[116:119]
	v_mfma_f32_16x16x32_bf16 v[112:115], v[186:189], v[194:197], v[112:115]
	v_mfma_f32_16x16x32_bf16 v[100:103], v[178:181], v[202:205], v[100:103]
	v_mfma_f32_16x16x32_bf16 v[96:99], v[186:189], v[202:205], v[96:99]
	v_mfma_f32_16x16x32_bf16 v[84:87], v[178:181], v[210:213], v[84:87]
	v_mfma_f32_16x16x32_bf16 v[80:83], v[186:189], v[210:213], v[80:83]
	v_mfma_f32_16x16x32_bf16 v[68:71], v[178:181], v[218:221], v[68:71]
	v_mfma_f32_16x16x32_bf16 v[64:67], v[186:189], v[218:221], v[64:67]
	s_barrier
	s_mov_b64 s[98:99], s[48:49]
	s_add_i32 s48, s57, s11
	s_mov_b32 m0, s48
	ds_read_b128 v[190:193], v157 offset:49152
	ds_read_b128 v[194:197], v157 offset:50176
	ds_read_b128 v[198:201], v157 offset:51200
	ds_read_b128 v[202:205], v157 offset:52224
	ds_read_b128 v[206:209], v157 offset:53248
	ds_read_b128 v[210:213], v157 offset:54272
	ds_read_b128 v[214:217], v157 offset:55296
	ds_read_b128 v[218:221], v157 offset:56320
	s_add_u32 s100, s46, 0x80
	s_addc_u32 s101, s47, 0
	global_load_lds_dwordx4 v130, s[100:101]
	s_add_i32 m0, s48, 0x2000
	s_add_u32 s46, s46, 0x80080
	s_addc_u32 s47, s47, 0
	s_add_i32 s48, s58, s11
	global_load_lds_dwordx4 v134, s[100:101]
	s_mov_b32 m0, s48
	s_nop 0
	global_load_lds_dwordx4 v130, s[46:47]
	s_add_i32 m0, s48, 0x2000
	s_nop 0
	global_load_lds_dwordx4 v134, s[46:47]
	s_mov_b32 m0, s19
	s_add_u32 s100, s98, 0xfff80080
	s_addc_u32 s101, s99, -1
	global_load_lds_dwordx4 v128, s[100:101]
	s_mov_b32 m0, s20
	s_nop 0
	global_load_lds_dwordx4 v132, s[100:101]
	s_waitcnt vmcnt(8) lgkmcnt(0)
	s_barrier
	v_mfma_f32_16x16x32_bf16 v[60:63], v[158:161], v[190:193], v[60:63]
	v_mfma_f32_16x16x32_bf16 v[56:59], v[166:169], v[190:193], v[56:59]
	v_mfma_f32_16x16x32_bf16 v[44:47], v[158:161], v[198:201], v[44:47]
	v_mfma_f32_16x16x32_bf16 v[40:43], v[166:169], v[198:201], v[40:43]
	v_mfma_f32_16x16x32_bf16 v[28:31], v[158:161], v[206:209], v[28:31]
	v_mfma_f32_16x16x32_bf16 v[24:27], v[166:169], v[206:209], v[24:27]
	v_mfma_f32_16x16x32_bf16 v[12:15], v[158:161], v[214:217], v[12:15]
	v_mfma_f32_16x16x32_bf16 v[8:11], v[166:169], v[214:217], v[8:11]
	v_mfma_f32_16x16x32_bf16 v[60:63], v[162:165], v[194:197], v[60:63]
	v_mfma_f32_16x16x32_bf16 v[56:59], v[170:173], v[194:197], v[56:59]
	v_mfma_f32_16x16x32_bf16 v[44:47], v[162:165], v[202:205], v[44:47]
	v_mfma_f32_16x16x32_bf16 v[40:43], v[170:173], v[202:205], v[40:43]
	v_mfma_f32_16x16x32_bf16 v[28:31], v[162:165], v[210:213], v[28:31]
	v_mfma_f32_16x16x32_bf16 v[24:27], v[170:173], v[210:213], v[24:27]
	v_mfma_f32_16x16x32_bf16 v[12:15], v[162:165], v[218:221], v[12:15]
	v_mfma_f32_16x16x32_bf16 v[8:11], v[170:173], v[218:221], v[8:11]
	v_mfma_f32_16x16x32_bf16 v[52:55], v[174:177], v[190:193], v[52:55]
	v_mfma_f32_16x16x32_bf16 v[48:51], v[182:185], v[190:193], v[48:51]
	v_mfma_f32_16x16x32_bf16 v[36:39], v[174:177], v[198:201], v[36:39]
	v_mfma_f32_16x16x32_bf16 v[32:35], v[182:185], v[198:201], v[32:35]
	v_mfma_f32_16x16x32_bf16 v[20:23], v[174:177], v[206:209], v[20:23]
	v_mfma_f32_16x16x32_bf16 v[16:19], v[182:185], v[206:209], v[16:19]
	v_mfma_f32_16x16x32_bf16 v[4:7], v[174:177], v[214:217], v[4:7]
	v_mfma_f32_16x16x32_bf16 v[0:3], v[182:185], v[214:217], v[0:3]
	v_mfma_f32_16x16x32_bf16 v[52:55], v[178:181], v[194:197], v[52:55]
	v_mfma_f32_16x16x32_bf16 v[48:51], v[186:189], v[194:197], v[48:51]
	v_mfma_f32_16x16x32_bf16 v[36:39], v[178:181], v[202:205], v[36:39]
	v_mfma_f32_16x16x32_bf16 v[32:35], v[186:189], v[202:205], v[32:35]
	v_mfma_f32_16x16x32_bf16 v[20:23], v[178:181], v[210:213], v[20:23]
	v_mfma_f32_16x16x32_bf16 v[16:19], v[186:189], v[210:213], v[16:19]
	v_mfma_f32_16x16x32_bf16 v[4:7], v[178:181], v[218:221], v[4:7]
	v_mfma_f32_16x16x32_bf16 v[0:3], v[186:189], v[218:221], v[0:3]
	s_barrier
	s_add_u32 s44, s44, 0x100
	s_addc_u32 s45, s45, 0
	s_add_u32 s54, s54, 0x100
	s_addc_u32 s55, s55, 0
	s_cmp_ge_u32 s56, s52
	s_mov_b32 s48, s56
	s_cbranch_scc0 .LBB0_170

; #define PG8_STAGE(bufoff, gbase, voff) do { _Pragma("unroll") for (int _i = 0; _i < 2; ++_i) \
;         __builtin_amdgcn_global_load_lds((const unsigned*)((const char*)(gbase) + (voff)[_i]), (LAS unsigned*)(lds + (bufoff) + ldsw + _i * 8192), 16, 0, 0); } while (0)
; #define PG8_LDA(dst, b, h) do { _Pragma("unroll") for (int m = 0; m < 4; ++m) _Pragma("unroll") for (int k = 0; k < 2; ++k) dst[m][k] = *(const LAS bf16x8*)(lds + PG8_SA(b, h) + aoff + m * 2048 + k * 1024); } while (0)
; #define PG8_LDB(dst, b, h) do { _Pragma("unroll") for (int n = 0; n < 2; ++n) _Pragma("unroll") for (int k = 0; k < 2; ++k) dst[n][k] = *(const LAS bf16x8*)(lds + PG8_SB(b, h) + boff + n * 2048 + k * 1024); } while (0)
; #define PG8_WAIT_V(n) asm volatile("s_waitcnt vmcnt(" #n ")" ::: "memory")
; #define PG8_WAIT_L(n) asm volatile("s_waitcnt lgkmcnt(" #n ")" ::: "memory")
; #define PG8_BAR __builtin_amdgcn_s_barrier()
; __device__ __forceinline__ void gemm_phase(LAS unsigned char* lds, const Params& p, const bf16_t* gA, const bf16_t* gBt, const int gM, const int gN, const int gK, const int epi, const int perm, bf16_t* const Hp, const int goff, const float coef) {
;     ...
;         const bool has_next = S.next(ui + 1, nxt);
;         const char* nA = has_next ? (const char*)gA + (size_t)nxt.pm * tstep + (nxt.ks > 0 ? nxt.ks * ksl : 0) : cA; const char* nB = has_next ? (const char*)gBt + (size_t)nxt.pn * tstep + (nxt.ks > 0 ? nxt.ks * ksl : 0) : cB;
;         const int nt = cur.ks >= 0 ? ntf / 4 : ntf;
;         for (int t = 0; t < nt; t += 2) {
;             const bool last = (t == nt - 2);
;             const char* a1 = cA + (size_t)(t + 1) * kstep;
;             const char* a2 = last ? nA : cA + (size_t)(t + 2) * kstep; const char* b2 = last ? nB : cB + (size_t)(t + 2) * kstep;
;             const char* a3 = a2 + kstep; const char* b3 = b2 + kstep;
;             PG8_LDB(B0, 0, 0); PG8_LDB(B1, 0, 1); PG8_SCHED; PG8_LDA(At, 0, 0); PG8_STAGE(PG8_SA(1, 1), a1 + hstep, voffA);
;             PG8_WAIT_V(8); PG8_WAIT_L(0); PG8_BAR; PG8_MMA(0, 0, At, B0); PG8_MMA(0, 1, At, B1); PG8_BAR; PG8_SCHED;
;             PG8_LDA(At, 0, 1); PG8_STAGE(PG8_SB(0, 0), b2, voffB); PG8_STAGE(PG8_SB(0, 1), b2 + hstep, voffB); PG8_STAGE(PG8_SA(0, 0), a2, voffA);
;             PG8_WAIT_V(8); PG8_WAIT_L(0); PG8_BAR; PG8_MMA(1, 0, At, B0); PG8_MMA(1, 1, At, B1); PG8_BAR; PG8_SCHED;
.LBB0_263:
	s_cmp_gt_i32 s6, -1
	s_cselect_b64 s[4:5], -1, 0
	s_and_b64 s[38:39], s[4:5], exec
	s_cselect_b32 s54, 22, 0x58
	s_add_i32 s55, s54, -2
	s_add_u32 s30, s30, 0x160080
	s_addc_u32 s31, s31, 0
	s_add_u32 s56, s34, 0x100
	s_addc_u32 s57, s35, 0
	s_mov_b32 s34, 0
	v_add_u32_e32 v222, 0x18000, v158
	v_add_u32_e32 v223, 0x1c000, v158
	ds_read_b128 v[146:149], v167
	ds_read_b128 v[150:153], v167 offset:1024
	ds_read_b128 v[154:157], v167 offset:2048
	ds_read_b128 v[170:173], v167 offset:3072
	ds_read_b128 v[174:177], v168
	ds_read_b128 v[178:181], v168 offset:1024
	ds_read_b128 v[182:185], v168 offset:2048
	ds_read_b128 v[186:189], v168 offset:3072
	s_add_i32 s58, s34, 2
	s_add_u32 s35, s30, 0xffea0080
	s_addc_u32 s38, s31, -1
	s_cmp_eq_u32 s55, s34
	s_cselect_b32 s34, s28, s56
	s_cselect_b32 s39, s27, s38
	s_cselect_b32 s38, s26, s35
	s_cselect_b32 s35, s29, s57
	s_add_i32 m0, s17, 0xc000
	ds_read_b128 v[190:193], v169
	ds_read_b128 v[194:197], v169 offset:1024
	ds_read_b128 v[198:201], v169 offset:2048
	ds_read_b128 v[202:205], v169 offset:3072
	ds_read_b128 v[206:209], v169 offset:4096
	ds_read_b128 v[210:213], v169 offset:5120
	ds_read_b128 v[214:217], v169 offset:6144
	ds_read_b128 v[218:221], v169 offset:7168
	global_load_lds_dwordx4 v136, s[30:31]
	s_add_i32 m0, s17, 0xe000
	s_nop 0
	global_load_lds_dwordx4 v138, s[30:31]
	s_waitcnt vmcnt(8) lgkmcnt(0)
	s_barrier
	v_mfma_f32_16x16x32_bf16 v[124:127], v[146:149], v[190:193], 0
	v_mfma_f32_16x16x32_bf16 v[120:123], v[154:157], v[190:193], 0
	v_mfma_f32_16x16x32_bf16 v[116:119], v[146:149], v[198:201], 0
	v_mfma_f32_16x16x32_bf16 v[112:115], v[154:157], v[198:201], 0
	v_mfma_f32_16x16x32_bf16 v[108:111], v[146:149], v[206:209], 0
	v_mfma_f32_16x16x32_bf16 v[104:107], v[154:157], v[206:209], 0
	v_mfma_f32_16x16x32_bf16 v[100:103], v[146:149], v[214:217], 0
	v_mfma_f32_16x16x32_bf16 v[96:99], v[154:157], v[214:217], 0
	v_mfma_f32_16x16x32_bf16 v[124:127], v[150:153], v[194:197], v[124:127]
	v_mfma_f32_16x16x32_bf16 v[120:123], v[170:173], v[194:197], v[120:123]
	v_mfma_f32_16x16x32_bf16 v[116:119], v[150:153], v[202:205], v[116:119]
	v_mfma_f32_16x16x32_bf16 v[112:115], v[170:173], v[202:205], v[112:115]
	v_mfma_f32_16x16x32_bf16 v[108:111], v[150:153], v[210:213], v[108:111]
	v_mfma_f32_16x16x32_bf16 v[104:107], v[170:173], v[210:213], v[104:107]
	v_mfma_f32_16x16x32_bf16 v[100:103], v[150:153], v[218:221], v[100:103]
	v_mfma_f32_16x16x32_bf16 v[96:99], v[170:173], v[218:221], v[96:99]
	v_mfma_f32_16x16x32_bf16 v[68:71], v[174:177], v[190:193], 0
	v_mfma_f32_16x16x32_bf16 v[60:63], v[182:185], v[190:193], 0
	v_mfma_f32_16x16x32_bf16 v[52:55], v[174:177], v[198:201], 0
	v_mfma_f32_16x16x32_bf16 v[48:51], v[182:185], v[198:201], 0
	v_mfma_f32_16x16x32_bf16 v[44:47], v[174:177], v[206:209], 0
	v_mfma_f32_16x16x32_bf16 v[40:43], v[182:185], v[206:209], 0
	v_mfma_f32_16x16x32_bf16 v[36:39], v[174:177], v[214:217], 0
	v_mfma_f32_16x16x32_bf16 v[32:35], v[182:185], v[214:217], 0
	v_mfma_f32_16x16x32_bf16 v[68:71], v[178:181], v[194:197], v[68:71]
	v_mfma_f32_16x16x32_bf16 v[60:63], v[186:189], v[194:197], v[60:63]
	v_mfma_f32_16x16x32_bf16 v[52:55], v[178:181], v[202:205], v[52:55]
	v_mfma_f32_16x16x32_bf16 v[48:51], v[186:189], v[202:205], v[48:51]
	v_mfma_f32_16x16x32_bf16 v[44:47], v[178:181], v[210:213], v[44:47]
	v_mfma_f32_16x16x32_bf16 v[40:43], v[186:189], v[210:213], v[40:43]
	v_mfma_f32_16x16x32_bf16 v[36:39], v[178:181], v[218:221], v[36:39]
	v_mfma_f32_16x16x32_bf16 v[32:35], v[186:189], v[218:221], v[32:35]
	s_barrier
	s_add_i32 s59, s46, s16
	s_mov_b32 m0, s59
	ds_read_b128 v[190:193], v169 offset:16384
	ds_read_b128 v[194:197], v169 offset:17408
	ds_read_b128 v[198:201], v169 offset:18432
	ds_read_b128 v[202:205], v169 offset:19456
	ds_read_b128 v[206:209], v169 offset:20480
	ds_read_b128 v[210:213], v169 offset:21504
	ds_read_b128 v[214:217], v169 offset:22528
	ds_read_b128 v[218:221], v169 offset:23552
	global_load_lds_dwordx4 v130, s[34:35]
	s_add_i32 m0, s59, 0x2000
	s_add_u32 s60, s34, 0x160000
	s_addc_u32 s61, s35, 0
	s_add_i32 s59, s47, s16
	global_load_lds_dwordx4 v134, s[34:35]
	s_mov_b32 m0, s59
	s_nop 0
	global_load_lds_dwordx4 v130, s[60:61]
	s_add_i32 m0, s59, 0x2000
	s_nop 0
	global_load_lds_dwordx4 v134, s[60:61]
	s_mov_b32 m0, s17
	s_nop 0
	global_load_lds_dwordx4 v128, s[38:39]
	s_mov_b32 m0, s18
	s_nop 0
	global_load_lds_dwordx4 v132, s[38:39]
	s_waitcnt vmcnt(8) lgkmcnt(0)
	s_barrier
	v_mfma_f32_16x16x32_bf16 v[92:95], v[146:149], v[190:193], 0
	v_mfma_f32_16x16x32_bf16 v[88:91], v[154:157], v[190:193], 0
	v_mfma_f32_16x16x32_bf16 v[84:87], v[146:149], v[198:201], 0
	v_mfma_f32_16x16x32_bf16 v[80:83], v[154:157], v[198:201], 0
	v_mfma_f32_16x16x32_bf16 v[76:79], v[146:149], v[206:209], 0
	v_mfma_f32_16x16x32_bf16 v[72:75], v[154:157], v[206:209], 0
	v_mfma_f32_16x16x32_bf16 v[64:67], v[146:149], v[214:217], 0
	v_mfma_f32_16x16x32_bf16 v[56:59], v[154:157], v[214:217], 0
	v_mfma_f32_16x16x32_bf16 v[92:95], v[150:153], v[194:197], v[92:95]
	v_mfma_f32_16x16x32_bf16 v[88:91], v[170:173], v[194:197], v[88:91]
	v_mfma_f32_16x16x32_bf16 v[84:87], v[150:153], v[202:205], v[84:87]
	v_mfma_f32_16x16x32_bf16 v[80:83], v[170:173], v[202:205], v[80:83]
	v_mfma_f32_16x16x32_bf16 v[76:79], v[150:153], v[210:213], v[76:79]
	v_mfma_f32_16x16x32_bf16 v[72:75], v[170:173], v[210:213], v[72:75]
	v_mfma_f32_16x16x32_bf16 v[64:67], v[150:153], v[218:221], v[64:67]
	v_mfma_f32_16x16x32_bf16 v[56:59], v[170:173], v[218:221], v[56:59]
	v_mfma_f32_16x16x32_bf16 v[28:31], v[174:177], v[190:193], 0
	v_mfma_f32_16x16x32_bf16 v[24:27], v[182:185], v[190:193], 0
	v_mfma_f32_16x16x32_bf16 v[20:23], v[174:177], v[198:201], 0
	v_mfma_f32_16x16x32_bf16 v[16:19], v[182:185], v[198:201], 0
	v_mfma_f32_16x16x32_bf16 v[12:15], v[174:177], v[206:209], 0
	v_mfma_f32_16x16x32_bf16 v[8:11], v[182:185], v[206:209], 0
	v_mfma_f32_16x16x32_bf16 v[4:7], v[174:177], v[214:217], 0
	v_mfma_f32_16x16x32_bf16 v[0:3], v[182:185], v[214:217], 0
	v_mfma_f32_16x16x32_bf16 v[28:31], v[178:181], v[194:197], v[28:31]
	v_mfma_f32_16x16x32_bf16 v[24:27], v[186:189], v[194:197], v[24:27]
	v_mfma_f32_16x16x32_bf16 v[20:23], v[178:181], v[202:205], v[20:23]
	v_mfma_f32_16x16x32_bf16 v[16:19], v[186:189], v[202:205], v[16:19]
	v_mfma_f32_16x16x32_bf16 v[12:15], v[178:181], v[210:213], v[12:15]
	v_mfma_f32_16x16x32_bf16 v[8:11], v[186:189], v[210:213], v[8:11]
	v_mfma_f32_16x16x32_bf16 v[4:7], v[178:181], v[218:221], v[4:7]
	v_mfma_f32_16x16x32_bf16 v[0:3], v[186:189], v[218:221], v[0:3]
	s_barrier
; #define PG8_STAGE(bufoff, gbase, voff) do { _Pragma("unroll") for (int _i = 0; _i < 2; ++_i) \
;         __builtin_amdgcn_global_load_lds((const unsigned*)((const char*)(gbase) + (voff)[_i]), (LAS unsigned*)(lds + (bufoff) + ldsw + _i * 8192), 16, 0, 0); } while (0)
; #define PG8_LDA(dst, b, h) do { _Pragma("unroll") for (int m = 0; m < 4; ++m) _Pragma("unroll") for (int k = 0; k < 2; ++k) dst[m][k] = *(const LAS bf16x8*)(lds + PG8_SA(b, h) + aoff + m * 2048 + k * 1024); } while (0)
; #define PG8_LDB(dst, b, h) do { _Pragma("unroll") for (int n = 0; n < 2; ++n) _Pragma("unroll") for (int k = 0; k < 2; ++k) dst[n][k] = *(const LAS bf16x8*)(lds + PG8_SB(b, h) + boff + n * 2048 + k * 1024); } while (0)
; #define PG8_MMA(ai, bj, At, Bt) do { __builtin_amdgcn_s_setprio(1); _Pragma("unroll") for (int m = 0; m < 4; ++m) _Pragma("unroll") for (int n = 0; n < 2; ++n) _Pragma("unroll") for (int k = 0; k < 2; ++k) \
;         acc[ai][bj][m][n] = __builtin_amdgcn_mfma_f32_16x16x32_bf16(Bt[n][k], At[m][k], acc[ai][bj][m][n], 0, 0, 0); __builtin_amdgcn_s_setprio(0); } while (0)
; #define PG8_WAIT_V(n) asm volatile("s_waitcnt vmcnt(" #n ")" ::: "memory")
; #define PG8_WAIT_L(n) asm volatile("s_waitcnt lgkmcnt(" #n ")" ::: "memory")
; #define PG8_BAR __builtin_amdgcn_s_barrier()
; #define PG8_SCHED __builtin_amdgcn_sched_barrier(0)
; __device__ __forceinline__ void gemm_phase(LAS unsigned char* lds, const Params& p, const bf16_t* gA, const bf16_t* gBt, const int gM, const int gN, const int gK, const int epi, const int perm, bf16_t* const Hp, const int goff, const float coef) {
;     ...
;             PG8_LDB(B0, 1, 0); PG8_LDB(B1, 1, 1); PG8_SCHED; PG8_LDA(At, 1, 0); PG8_STAGE(PG8_SA(0, 1), a2 + hstep, voffA);
;             PG8_WAIT_V(8); PG8_WAIT_L(0); PG8_BAR; PG8_MMA(0, 0, At, B0); PG8_MMA(0, 1, At, B1); PG8_BAR; PG8_SCHED;
;             PG8_LDA(At, 1, 1); PG8_STAGE(PG8_SB(1, 0), b3, voffB); PG8_STAGE(PG8_SB(1, 1), b3 + hstep, voffB); PG8_STAGE(PG8_SA(1, 0), a3, voffA);
;             PG8_WAIT_V(8); PG8_WAIT_L(0); PG8_BAR; PG8_MMA(1, 0, At, B0); PG8_MMA(1, 1, At, B1); PG8_BAR; PG8_SCHED;
;         }
	s_add_i32 s59, 0, 0x18000
	s_add_i32 s60, 0, 0x1c000
	ds_read_b128 v[146:149], v222
	ds_read_b128 v[150:153], v222 offset:1024
	ds_read_b128 v[154:157], v222 offset:2048
	ds_read_b128 v[170:173], v222 offset:3072
	ds_read_b128 v[174:177], v223
	ds_read_b128 v[178:181], v223 offset:1024
	ds_read_b128 v[182:185], v223 offset:2048
	ds_read_b128 v[186:189], v223 offset:3072
	s_add_u32 s38, s38, 0x160000
	s_addc_u32 s39, s39, 0
	s_mov_b32 m0, s19
	ds_read_b128 v[190:193], v169 offset:32768
	ds_read_b128 v[194:197], v169 offset:33792
	ds_read_b128 v[198:201], v169 offset:34816
	ds_read_b128 v[202:205], v169 offset:35840
	ds_read_b128 v[206:209], v169 offset:36864
	ds_read_b128 v[210:213], v169 offset:37888
	ds_read_b128 v[214:217], v169 offset:38912
	ds_read_b128 v[218:221], v169 offset:39936
	global_load_lds_dwordx4 v128, s[38:39]
	s_mov_b32 m0, s20
	s_nop 0
	global_load_lds_dwordx4 v132, s[38:39]
	s_waitcnt vmcnt(8) lgkmcnt(0)
	s_barrier
	v_mfma_f32_16x16x32_bf16 v[124:127], v[146:149], v[190:193], v[124:127]
	v_mfma_f32_16x16x32_bf16 v[120:123], v[154:157], v[190:193], v[120:123]
	v_mfma_f32_16x16x32_bf16 v[116:119], v[146:149], v[198:201], v[116:119]
	v_mfma_f32_16x16x32_bf16 v[112:115], v[154:157], v[198:201], v[112:115]
	v_mfma_f32_16x16x32_bf16 v[108:111], v[146:149], v[206:209], v[108:111]
	v_mfma_f32_16x16x32_bf16 v[104:107], v[154:157], v[206:209], v[104:107]
	v_mfma_f32_16x16x32_bf16 v[100:103], v[146:149], v[214:217], v[100:103]
	v_mfma_f32_16x16x32_bf16 v[96:99], v[154:157], v[214:217], v[96:99]
	v_mfma_f32_16x16x32_bf16 v[124:127], v[150:153], v[194:197], v[124:127]
	v_mfma_f32_16x16x32_bf16 v[120:123], v[170:173], v[194:197], v[120:123]
	v_mfma_f32_16x16x32_bf16 v[116:119], v[150:153], v[202:205], v[116:119]
	v_mfma_f32_16x16x32_bf16 v[112:115], v[170:173], v[202:205], v[112:115]
	v_mfma_f32_16x16x32_bf16 v[108:111], v[150:153], v[210:213], v[108:111]
	v_mfma_f32_16x16x32_bf16 v[104:107], v[170:173], v[210:213], v[104:107]
	v_mfma_f32_16x16x32_bf16 v[100:103], v[150:153], v[218:221], v[100:103]
	v_mfma_f32_16x16x32_bf16 v[96:99], v[170:173], v[218:221], v[96:99]
	v_mfma_f32_16x16x32_bf16 v[68:71], v[174:177], v[190:193], v[68:71]
	v_mfma_f32_16x16x32_bf16 v[60:63], v[182:185], v[190:193], v[60:63]
	v_mfma_f32_16x16x32_bf16 v[52:55], v[174:177], v[198:201], v[52:55]
	v_mfma_f32_16x16x32_bf16 v[48:51], v[182:185], v[198:201], v[48:51]
	v_mfma_f32_16x16x32_bf16 v[44:47], v[174:177], v[206:209], v[44:47]
	v_mfma_f32_16x16x32_bf16 v[40:43], v[182:185], v[206:209], v[40:43]
	v_mfma_f32_16x16x32_bf16 v[36:39], v[174:177], v[214:217], v[36:39]
	v_mfma_f32_16x16x32_bf16 v[32:35], v[182:185], v[214:217], v[32:35]
	v_mfma_f32_16x16x32_bf16 v[68:71], v[178:181], v[194:197], v[68:71]
	v_mfma_f32_16x16x32_bf16 v[60:63], v[186:189], v[194:197], v[60:63]
	v_mfma_f32_16x16x32_bf16 v[52:55], v[178:181], v[202:205], v[52:55]
	v_mfma_f32_16x16x32_bf16 v[48:51], v[186:189], v[202:205], v[48:51]
	v_mfma_f32_16x16x32_bf16 v[44:47], v[178:181], v[210:213], v[44:47]
	v_mfma_f32_16x16x32_bf16 v[40:43], v[186:189], v[210:213], v[40:43]
	v_mfma_f32_16x16x32_bf16 v[36:39], v[178:181], v[218:221], v[36:39]
	v_mfma_f32_16x16x32_bf16 v[32:35], v[186:189], v[218:221], v[32:35]
	s_barrier
	s_mov_b64 s[98:99], s[38:39]
	s_add_i32 s38, s59, s16
	s_mov_b32 m0, s38
	ds_read_b128 v[190:193], v169 offset:49152
	ds_read_b128 v[194:197], v169 offset:50176
	ds_read_b128 v[198:201], v169 offset:51200
	ds_read_b128 v[202:205], v169 offset:52224
	ds_read_b128 v[206:209], v169 offset:53248
	ds_read_b128 v[210:213], v169 offset:54272
	ds_read_b128 v[214:217], v169 offset:55296
	ds_read_b128 v[218:221], v169 offset:56320
	s_add_u32 s100, s34, 0x80
	s_addc_u32 s101, s35, 0
	global_load_lds_dwordx4 v130, s[100:101]
	s_add_i32 m0, s38, 0x2000
	s_add_u32 s34, s34, 0x160080
	s_addc_u32 s35, s35, 0
	s_add_i32 s38, s60, s16
	global_load_lds_dwordx4 v134, s[100:101]
	s_mov_b32 m0, s38
	s_nop 0
	global_load_lds_dwordx4 v130, s[34:35]
	s_add_i32 m0, s38, 0x2000
	s_nop 0
	global_load_lds_dwordx4 v134, s[34:35]
	s_mov_b32 m0, s23
	s_add_u32 s100, s98, 0xffea0080
	s_addc_u32 s101, s99, -1
	global_load_lds_dwordx4 v128, s[100:101]
	s_mov_b32 m0, s33
	s_nop 0
	global_load_lds_dwordx4 v132, s[100:101]
	s_waitcnt vmcnt(8) lgkmcnt(0)
	s_barrier
	v_mfma_f32_16x16x32_bf16 v[92:95], v[146:149], v[190:193], v[92:95]
	v_mfma_f32_16x16x32_bf16 v[88:91], v[154:157], v[190:193], v[88:91]
	v_mfma_f32_16x16x32_bf16 v[84:87], v[146:149], v[198:201], v[84:87]
	v_mfma_f32_16x16x32_bf16 v[80:83], v[154:157], v[198:201], v[80:83]
	v_mfma_f32_16x16x32_bf16 v[76:79], v[146:149], v[206:209], v[76:79]
	v_mfma_f32_16x16x32_bf16 v[72:75], v[154:157], v[206:209], v[72:75]
	v_mfma_f32_16x16x32_bf16 v[64:67], v[146:149], v[214:217], v[64:67]
	v_mfma_f32_16x16x32_bf16 v[56:59], v[154:157], v[214:217], v[56:59]
	v_mfma_f32_16x16x32_bf16 v[92:95], v[150:153], v[194:197], v[92:95]
	v_mfma_f32_16x16x32_bf16 v[88:91], v[170:173], v[194:197], v[88:91]
	v_mfma_f32_16x16x32_bf16 v[84:87], v[150:153], v[202:205], v[84:87]
	v_mfma_f32_16x16x32_bf16 v[80:83], v[170:173], v[202:205], v[80:83]
	v_mfma_f32_16x16x32_bf16 v[76:79], v[150:153], v[210:213], v[76:79]
	v_mfma_f32_16x16x32_bf16 v[72:75], v[170:173], v[210:213], v[72:75]
	v_mfma_f32_16x16x32_bf16 v[64:67], v[150:153], v[218:221], v[64:67]
	v_mfma_f32_16x16x32_bf16 v[56:59], v[170:173], v[218:221], v[56:59]
	v_mfma_f32_16x16x32_bf16 v[28:31], v[174:177], v[190:193], v[28:31]
	v_mfma_f32_16x16x32_bf16 v[24:27], v[182:185], v[190:193], v[24:27]
	v_mfma_f32_16x16x32_bf16 v[20:23], v[174:177], v[198:201], v[20:23]
	v_mfma_f32_16x16x32_bf16 v[16:19], v[182:185], v[198:201], v[16:19]
	v_mfma_f32_16x16x32_bf16 v[12:15], v[174:177], v[206:209], v[12:15]
	v_mfma_f32_16x16x32_bf16 v[8:11], v[182:185], v[206:209], v[8:11]
	v_mfma_f32_16x16x32_bf16 v[4:7], v[174:177], v[214:217], v[4:7]
	v_mfma_f32_16x16x32_bf16 v[0:3], v[182:185], v[214:217], v[0:3]
	v_mfma_f32_16x16x32_bf16 v[28:31], v[178:181], v[194:197], v[28:31]
	v_mfma_f32_16x16x32_bf16 v[24:27], v[186:189], v[194:197], v[24:27]
	v_mfma_f32_16x16x32_bf16 v[20:23], v[178:181], v[202:205], v[20:23]
	v_mfma_f32_16x16x32_bf16 v[16:19], v[186:189], v[202:205], v[16:19]
	v_mfma_f32_16x16x32_bf16 v[12:15], v[178:181], v[210:213], v[12:15]
	v_mfma_f32_16x16x32_bf16 v[8:11], v[186:189], v[210:213], v[8:11]
	v_mfma_f32_16x16x32_bf16 v[4:7], v[178:181], v[218:221], v[4:7]
	v_mfma_f32_16x16x32_bf16 v[0:3], v[186:189], v[218:221], v[0:3]
	s_barrier
	s_add_u32 s30, s30, 0x100
	s_addc_u32 s31, s31, 0
	s_add_u32 s56, s56, 0x100
	s_addc_u32 s57, s57, 0
	s_cmp_ge_u32 s58, s54
	s_mov_b64 s[98:99], s[34:35]
	s_mov_b32 s34, s58
	s_cbranch_scc1 .Lpeel_exit_1
; #define PG8_STAGE(bufoff, gbase, voff) do { _Pragma("unroll") for (int _i = 0; _i < 2; ++_i) \
;         __builtin_amdgcn_global_load_lds((const unsigned*)((const char*)(gbase) + (voff)[_i]), (LAS unsigned*)(lds + (bufoff) + ldsw + _i * 8192), 16, 0, 0); } while (0)
; #define PG8_LDA(dst, b, h) do { _Pragma("unroll") for (int m = 0; m < 4; ++m) _Pragma("unroll") for (int k = 0; k < 2; ++k) dst[m][k] = *(const LAS bf16x8*)(lds + PG8_SA(b, h) + aoff + m * 2048 + k * 1024); } while (0)
; #define PG8_LDB(dst, b, h) do { _Pragma("unroll") for (int n = 0; n < 2; ++n) _Pragma("unroll") for (int k = 0; k < 2; ++k) dst[n][k] = *(const LAS bf16x8*)(lds + PG8_SB(b, h) + boff + n * 2048 + k * 1024); } while (0)
; #define PG8_MMA(ai, bj, At, Bt) do { __builtin_amdgcn_s_setprio(1); _Pragma("unroll") for (int m = 0; m < 4; ++m) _Pragma("unroll") for (int n = 0; n < 2; ++n) _Pragma("unroll") for (int k = 0; k < 2; ++k) \
;         acc[ai][bj][m][n] = __builtin_amdgcn_mfma_f32_16x16x32_bf16(Bt[n][k], At[m][k], acc[ai][bj][m][n], 0, 0, 0); __builtin_amdgcn_s_setprio(0); } while (0)
; #define PG8_WAIT_V(n) asm volatile("s_waitcnt vmcnt(" #n ")" ::: "memory")
; #define PG8_WAIT_L(n) asm volatile("s_waitcnt lgkmcnt(" #n ")" ::: "memory")
; __device__ __forceinline__ void gemm_phase(LAS unsigned char* lds, const Params& p, const bf16_t* gA, const bf16_t* gBt, const int gM, const int gN, const int gK, const int epi, const int perm, bf16_t* const Hp, const int goff, const float coef) {
;     ...
;         for (int t = 0; t < nt; t += 2) {
;             const bool last = (t == nt - 2);
;             const char* a1 = cA + (size_t)(t + 1) * kstep;
;             const char* a2 = last ? nA : cA + (size_t)(t + 2) * kstep; const char* b2 = last ? nB : cB + (size_t)(t + 2) * kstep;
;             const char* a3 = a2 + kstep; const char* b3 = b2 + kstep;
;             PG8_LDB(B0, 0, 0); PG8_LDB(B1, 0, 1); PG8_SCHED; PG8_LDA(At, 0, 0); PG8_STAGE(PG8_SA(1, 1), a1 + hstep, voffA);
;             PG8_WAIT_V(8); PG8_WAIT_L(0); PG8_BAR; PG8_MMA(0, 0, At, B0); PG8_MMA(0, 1, At, B1); PG8_BAR; PG8_SCHED;
;             PG8_LDA(At, 0, 1); PG8_STAGE(PG8_SB(0, 0), b2, voffB); PG8_STAGE(PG8_SB(0, 1), b2 + hstep, voffB); PG8_STAGE(PG8_SA(0, 0), a2, voffA);
;             PG8_WAIT_V(8); PG8_WAIT_L(0); PG8_BAR; PG8_MMA(1, 0, At, B0); PG8_MMA(1, 1, At, B1); PG8_BAR; PG8_SCHED;
.LBB0_264:
	ds_read_b128 v[146:149], v167
	ds_read_b128 v[150:153], v167 offset:1024
	ds_read_b128 v[154:157], v167 offset:2048
	ds_read_b128 v[170:173], v167 offset:3072
	ds_read_b128 v[174:177], v168
	ds_read_b128 v[178:181], v168 offset:1024
	ds_read_b128 v[182:185], v168 offset:2048
	ds_read_b128 v[186:189], v168 offset:3072
	s_add_i32 s58, s34, 2
	s_add_u32 s35, s30, 0xffea0080
	s_addc_u32 s38, s31, -1
	s_cmp_eq_u32 s55, s34
	s_cselect_b32 s34, s28, s56
	s_cselect_b32 s39, s27, s38
	s_cselect_b32 s38, s26, s35
	s_cselect_b32 s35, s29, s57
	s_add_i32 m0, s17, 0xc000
	ds_read_b128 v[190:193], v169
	ds_read_b128 v[194:197], v169 offset:1024
	ds_read_b128 v[198:201], v169 offset:2048
	ds_read_b128 v[202:205], v169 offset:3072
	ds_read_b128 v[206:209], v169 offset:4096
	ds_read_b128 v[210:213], v169 offset:5120
	ds_read_b128 v[214:217], v169 offset:6144
	ds_read_b128 v[218:221], v169 offset:7168
	global_load_lds_dwordx4 v136, s[30:31]
	s_add_i32 m0, s17, 0xe000
	s_nop 0
	global_load_lds_dwordx4 v138, s[30:31]
	s_waitcnt vmcnt(8) lgkmcnt(0)
	s_barrier
	v_mfma_f32_16x16x32_bf16 v[124:127], v[146:149], v[190:193], v[124:127]
	v_mfma_f32_16x16x32_bf16 v[120:123], v[154:157], v[190:193], v[120:123]
	v_mfma_f32_16x16x32_bf16 v[116:119], v[146:149], v[198:201], v[116:119]
	v_mfma_f32_16x16x32_bf16 v[112:115], v[154:157], v[198:201], v[112:115]
	v_mfma_f32_16x16x32_bf16 v[108:111], v[146:149], v[206:209], v[108:111]
	v_mfma_f32_16x16x32_bf16 v[104:107], v[154:157], v[206:209], v[104:107]
	v_mfma_f32_16x16x32_bf16 v[100:103], v[146:149], v[214:217], v[100:103]
	v_mfma_f32_16x16x32_bf16 v[96:99], v[154:157], v[214:217], v[96:99]
	v_mfma_f32_16x16x32_bf16 v[124:127], v[150:153], v[194:197], v[124:127]
	v_mfma_f32_16x16x32_bf16 v[120:123], v[170:173], v[194:197], v[120:123]
	v_mfma_f32_16x16x32_bf16 v[116:119], v[150:153], v[202:205], v[116:119]
	v_mfma_f32_16x16x32_bf16 v[112:115], v[170:173], v[202:205], v[112:115]
	v_mfma_f32_16x16x32_bf16 v[108:111], v[150:153], v[210:213], v[108:111]
	v_mfma_f32_16x16x32_bf16 v[104:107], v[170:173], v[210:213], v[104:107]
	v_mfma_f32_16x16x32_bf16 v[100:103], v[150:153], v[218:221], v[100:103]
	v_mfma_f32_16x16x32_bf16 v[96:99], v[170:173], v[218:221], v[96:99]
	v_mfma_f32_16x16x32_bf16 v[68:71], v[174:177], v[190:193], v[68:71]
	v_mfma_f32_16x16x32_bf16 v[60:63], v[182:185], v[190:193], v[60:63]
	v_mfma_f32_16x16x32_bf16 v[52:55], v[174:177], v[198:201], v[52:55]
	v_mfma_f32_16x16x32_bf16 v[48:51], v[182:185], v[198:201], v[48:51]
	v_mfma_f32_16x16x32_bf16 v[44:47], v[174:177], v[206:209], v[44:47]
	v_mfma_f32_16x16x32_bf16 v[40:43], v[182:185], v[206:209], v[40:43]
	v_mfma_f32_16x16x32_bf16 v[36:39], v[174:177], v[214:217], v[36:39]
	v_mfma_f32_16x16x32_bf16 v[32:35], v[182:185], v[214:217], v[32:35]
	v_mfma_f32_16x16x32_bf16 v[68:71], v[178:181], v[194:197], v[68:71]
	v_mfma_f32_16x16x32_bf16 v[60:63], v[186:189], v[194:197], v[60:63]
	v_mfma_f32_16x16x32_bf16 v[52:55], v[178:181], v[202:205], v[52:55]
	v_mfma_f32_16x16x32_bf16 v[48:51], v[186:189], v[202:205], v[48:51]
	v_mfma_f32_16x16x32_bf16 v[44:47], v[178:181], v[210:213], v[44:47]
	v_mfma_f32_16x16x32_bf16 v[40:43], v[186:189], v[210:213], v[40:43]
	v_mfma_f32_16x16x32_bf16 v[36:39], v[178:181], v[218:221], v[36:39]
	v_mfma_f32_16x16x32_bf16 v[32:35], v[186:189], v[218:221], v[32:35]
	s_barrier
	s_add_i32 s59, s46, s16
	s_mov_b32 m0, s59
	ds_read_b128 v[190:193], v169 offset:16384
	ds_read_b128 v[194:197], v169 offset:17408
	ds_read_b128 v[198:201], v169 offset:18432
	ds_read_b128 v[202:205], v169 offset:19456
	ds_read_b128 v[206:209], v169 offset:20480
	ds_read_b128 v[210:213], v169 offset:21504
	ds_read_b128 v[214:217], v169 offset:22528
	ds_read_b128 v[218:221], v169 offset:23552
	global_load_lds_dwordx4 v130, s[34:35]
	s_add_i32 m0, s59, 0x2000
	s_add_u32 s60, s34, 0x160000
	s_addc_u32 s61, s35, 0
	s_add_i32 s59, s47, s16
	global_load_lds_dwordx4 v134, s[34:35]
	s_mov_b32 m0, s59
	s_nop 0
	global_load_lds_dwordx4 v130, s[60:61]
	s_add_i32 m0, s59, 0x2000
	s_nop 0
	global_load_lds_dwordx4 v134, s[60:61]
	s_mov_b32 m0, s17
	s_nop 0
	global_load_lds_dwordx4 v128, s[38:39]
	s_mov_b32 m0, s18
	s_nop 0
	global_load_lds_dwordx4 v132, s[38:39]
	s_waitcnt vmcnt(8) lgkmcnt(0)
	s_barrier
	v_mfma_f32_16x16x32_bf16 v[92:95], v[146:149], v[190:193], v[92:95]
	v_mfma_f32_16x16x32_bf16 v[88:91], v[154:157], v[190:193], v[88:91]
	v_mfma_f32_16x16x32_bf16 v[84:87], v[146:149], v[198:201], v[84:87]
	v_mfma_f32_16x16x32_bf16 v[80:83], v[154:157], v[198:201], v[80:83]
	v_mfma_f32_16x16x32_bf16 v[76:79], v[146:149], v[206:209], v[76:79]
	v_mfma_f32_16x16x32_bf16 v[72:75], v[154:157], v[206:209], v[72:75]
	v_mfma_f32_16x16x32_bf16 v[64:67], v[146:149], v[214:217], v[64:67]
	v_mfma_f32_16x16x32_bf16 v[56:59], v[154:157], v[214:217], v[56:59]
	v_mfma_f32_16x16x32_bf16 v[92:95], v[150:153], v[194:197], v[92:95]
	v_mfma_f32_16x16x32_bf16 v[88:91], v[170:173], v[194:197], v[88:91]
	v_mfma_f32_16x16x32_bf16 v[84:87], v[150:153], v[202:205], v[84:87]
	v_mfma_f32_16x16x32_bf16 v[80:83], v[170:173], v[202:205], v[80:83]
	v_mfma_f32_16x16x32_bf16 v[76:79], v[150:153], v[210:213], v[76:79]
	v_mfma_f32_16x16x32_bf16 v[72:75], v[170:173], v[210:213], v[72:75]
	v_mfma_f32_16x16x32_bf16 v[64:67], v[150:153], v[218:221], v[64:67]
	v_mfma_f32_16x16x32_bf16 v[56:59], v[170:173], v[218:221], v[56:59]
	v_mfma_f32_16x16x32_bf16 v[28:31], v[174:177], v[190:193], v[28:31]
	v_mfma_f32_16x16x32_bf16 v[24:27], v[182:185], v[190:193], v[24:27]
	v_mfma_f32_16x16x32_bf16 v[20:23], v[174:177], v[198:201], v[20:23]
	v_mfma_f32_16x16x32_bf16 v[16:19], v[182:185], v[198:201], v[16:19]
	v_mfma_f32_16x16x32_bf16 v[12:15], v[174:177], v[206:209], v[12:15]
	v_mfma_f32_16x16x32_bf16 v[8:11], v[182:185], v[206:209], v[8:11]
	v_mfma_f32_16x16x32_bf16 v[4:7], v[174:177], v[214:217], v[4:7]
	v_mfma_f32_16x16x32_bf16 v[0:3], v[182:185], v[214:217], v[0:3]
	v_mfma_f32_16x16x32_bf16 v[28:31], v[178:181], v[194:197], v[28:31]
	v_mfma_f32_16x16x32_bf16 v[24:27], v[186:189], v[194:197], v[24:27]
	v_mfma_f32_16x16x32_bf16 v[20:23], v[178:181], v[202:205], v[20:23]
	v_mfma_f32_16x16x32_bf16 v[16:19], v[186:189], v[202:205], v[16:19]
	v_mfma_f32_16x16x32_bf16 v[12:15], v[178:181], v[210:213], v[12:15]
	v_mfma_f32_16x16x32_bf16 v[8:11], v[186:189], v[210:213], v[8:11]
	v_mfma_f32_16x16x32_bf16 v[4:7], v[178:181], v[218:221], v[4:7]
	v_mfma_f32_16x16x32_bf16 v[0:3], v[186:189], v[218:221], v[0:3]
	s_barrier
; #define PG8_STAGE(bufoff, gbase, voff) do { _Pragma("unroll") for (int _i = 0; _i < 2; ++_i) \
;         __builtin_amdgcn_global_load_lds((const unsigned*)((const char*)(gbase) + (voff)[_i]), (LAS unsigned*)(lds + (bufoff) + ldsw + _i * 8192), 16, 0, 0); } while (0)
; #define PG8_LDA(dst, b, h) do { _Pragma("unroll") for (int m = 0; m < 4; ++m) _Pragma("unroll") for (int k = 0; k < 2; ++k) dst[m][k] = *(const LAS bf16x8*)(lds + PG8_SA(b, h) + aoff + m * 2048 + k * 1024); } while (0)
; #define PG8_LDB(dst, b, h) do { _Pragma("unroll") for (int n = 0; n < 2; ++n) _Pragma("unroll") for (int k = 0; k < 2; ++k) dst[n][k] = *(const LAS bf16x8*)(lds + PG8_SB(b, h) + boff + n * 2048 + k * 1024); } while (0)
; #define PG8_MMA(ai, bj, At, Bt) do { __builtin_amdgcn_s_setprio(1); _Pragma("unroll") for (int m = 0; m < 4; ++m) _Pragma("unroll") for (int n = 0; n < 2; ++n) _Pragma("unroll") for (int k = 0; k < 2; ++k) \
;         acc[ai][bj][m][n] = __builtin_amdgcn_mfma_f32_16x16x32_bf16(Bt[n][k], At[m][k], acc[ai][bj][m][n], 0, 0, 0); __builtin_amdgcn_s_setprio(0); } while (0)
; #define PG8_WAIT_V(n) asm volatile("s_waitcnt vmcnt(" #n ")" ::: "memory")
; #define PG8_WAIT_L(n) asm volatile("s_waitcnt lgkmcnt(" #n ")" ::: "memory")
; #define PG8_BAR __builtin_amdgcn_s_barrier()
; #define PG8_SCHED __builtin_amdgcn_sched_barrier(0)
; __device__ __forceinline__ void gemm_phase(LAS unsigned char* lds, const Params& p, const bf16_t* gA, const bf16_t* gBt, const int gM, const int gN, const int gK, const int epi, const int perm, bf16_t* const Hp, const int goff, const float coef) {
;     ...
;             PG8_LDB(B0, 1, 0); PG8_LDB(B1, 1, 1); PG8_SCHED; PG8_LDA(At, 1, 0); PG8_STAGE(PG8_SA(0, 1), a2 + hstep, voffA);
;             PG8_WAIT_V(8); PG8_WAIT_L(0); PG8_BAR; PG8_MMA(0, 0, At, B0); PG8_MMA(0, 1, At, B1); PG8_BAR; PG8_SCHED;
;             PG8_LDA(At, 1, 1); PG8_STAGE(PG8_SB(1, 0), b3, voffB); PG8_STAGE(PG8_SB(1, 1), b3 + hstep, voffB); PG8_STAGE(PG8_SA(1, 0), a3, voffA);
;             PG8_WAIT_V(8); PG8_WAIT_L(0); PG8_BAR; PG8_MMA(1, 0, At, B0); PG8_MMA(1, 1, At, B1); PG8_BAR; PG8_SCHED;
;         }
	s_add_i32 s59, 0, 0x18000
	s_add_i32 s60, 0, 0x1c000
	ds_read_b128 v[146:149], v222
	ds_read_b128 v[150:153], v222 offset:1024
	ds_read_b128 v[154:157], v222 offset:2048
	ds_read_b128 v[170:173], v222 offset:3072
	ds_read_b128 v[174:177], v223
	ds_read_b128 v[178:181], v223 offset:1024
	ds_read_b128 v[182:185], v223 offset:2048
	ds_read_b128 v[186:189], v223 offset:3072
	s_add_u32 s38, s38, 0x160000
	s_addc_u32 s39, s39, 0
	s_mov_b32 m0, s19
	ds_read_b128 v[190:193], v169 offset:32768
	ds_read_b128 v[194:197], v169 offset:33792
	ds_read_b128 v[198:201], v169 offset:34816
	ds_read_b128 v[202:205], v169 offset:35840
	ds_read_b128 v[206:209], v169 offset:36864
	ds_read_b128 v[210:213], v169 offset:37888
	ds_read_b128 v[214:217], v169 offset:38912
	ds_read_b128 v[218:221], v169 offset:39936
	global_load_lds_dwordx4 v128, s[38:39]
	s_mov_b32 m0, s20
	s_nop 0
	global_load_lds_dwordx4 v132, s[38:39]
	s_waitcnt vmcnt(8) lgkmcnt(0)
	s_barrier
	v_mfma_f32_16x16x32_bf16 v[124:127], v[146:149], v[190:193], v[124:127]
	v_mfma_f32_16x16x32_bf16 v[120:123], v[154:157], v[190:193], v[120:123]
	v_mfma_f32_16x16x32_bf16 v[116:119], v[146:149], v[198:201], v[116:119]
	v_mfma_f32_16x16x32_bf16 v[112:115], v[154:157], v[198:201], v[112:115]
	v_mfma_f32_16x16x32_bf16 v[108:111], v[146:149], v[206:209], v[108:111]
	v_mfma_f32_16x16x32_bf16 v[104:107], v[154:157], v[206:209], v[104:107]
	v_mfma_f32_16x16x32_bf16 v[100:103], v[146:149], v[214:217], v[100:103]
	v_mfma_f32_16x16x32_bf16 v[96:99], v[154:157], v[214:217], v[96:99]
	v_mfma_f32_16x16x32_bf16 v[124:127], v[150:153], v[194:197], v[124:127]
	v_mfma_f32_16x16x32_bf16 v[120:123], v[170:173], v[194:197], v[120:123]
	v_mfma_f32_16x16x32_bf16 v[116:119], v[150:153], v[202:205], v[116:119]
	v_mfma_f32_16x16x32_bf16 v[112:115], v[170:173], v[202:205], v[112:115]
	v_mfma_f32_16x16x32_bf16 v[108:111], v[150:153], v[210:213], v[108:111]
	v_mfma_f32_16x16x32_bf16 v[104:107], v[170:173], v[210:213], v[104:107]
	v_mfma_f32_16x16x32_bf16 v[100:103], v[150:153], v[218:221], v[100:103]
	v_mfma_f32_16x16x32_bf16 v[96:99], v[170:173], v[218:221], v[96:99]
	v_mfma_f32_16x16x32_bf16 v[68:71], v[174:177], v[190:193], v[68:71]
	v_mfma_f32_16x16x32_bf16 v[60:63], v[182:185], v[190:193], v[60:63]
	v_mfma_f32_16x16x32_bf16 v[52:55], v[174:177], v[198:201], v[52:55]
	v_mfma_f32_16x16x32_bf16 v[48:51], v[182:185], v[198:201], v[48:51]
	v_mfma_f32_16x16x32_bf16 v[44:47], v[174:177], v[206:209], v[44:47]
	v_mfma_f32_16x16x32_bf16 v[40:43], v[182:185], v[206:209], v[40:43]
	v_mfma_f32_16x16x32_bf16 v[36:39], v[174:177], v[214:217], v[36:39]
	v_mfma_f32_16x16x32_bf16 v[32:35], v[182:185], v[214:217], v[32:35]
	v_mfma_f32_16x16x32_bf16 v[68:71], v[178:181], v[194:197], v[68:71]
	v_mfma_f32_16x16x32_bf16 v[60:63], v[186:189], v[194:197], v[60:63]
	v_mfma_f32_16x16x32_bf16 v[52:55], v[178:181], v[202:205], v[52:55]
	v_mfma_f32_16x16x32_bf16 v[48:51], v[186:189], v[202:205], v[48:51]
	v_mfma_f32_16x16x32_bf16 v[44:47], v[178:181], v[210:213], v[44:47]
	v_mfma_f32_16x16x32_bf16 v[40:43], v[186:189], v[210:213], v[40:43]
	v_mfma_f32_16x16x32_bf16 v[36:39], v[178:181], v[218:221], v[36:39]
	v_mfma_f32_16x16x32_bf16 v[32:35], v[186:189], v[218:221], v[32:35]
	s_barrier
	s_mov_b64 s[98:99], s[38:39]
	s_add_i32 s38, s59, s16
	s_mov_b32 m0, s38
	ds_read_b128 v[190:193], v169 offset:49152
	ds_read_b128 v[194:197], v169 offset:50176
	ds_read_b128 v[198:201], v169 offset:51200
	ds_read_b128 v[202:205], v169 offset:52224
	ds_read_b128 v[206:209], v169 offset:53248
	ds_read_b128 v[210:213], v169 offset:54272
	ds_read_b128 v[214:217], v169 offset:55296
	ds_read_b128 v[218:221], v169 offset:56320
	s_add_u32 s100, s34, 0x80
	s_addc_u32 s101, s35, 0
	global_load_lds_dwordx4 v130, s[100:101]
	s_add_i32 m0, s38, 0x2000
	s_add_u32 s34, s34, 0x160080
	s_addc_u32 s35, s35, 0
	s_add_i32 s38, s60, s16
	global_load_lds_dwordx4 v134, s[100:101]
	s_mov_b32 m0, s38
	s_nop 0
	global_load_lds_dwordx4 v130, s[34:35]
	s_add_i32 m0, s38, 0x2000
	s_nop 0
	global_load_lds_dwordx4 v134, s[34:35]
	s_mov_b32 m0, s23
	s_add_u32 s100, s98, 0xffea0080
	s_addc_u32 s101, s99, -1
	global_load_lds_dwordx4 v128, s[100:101]
	s_mov_b32 m0, s33
	s_nop 0
	global_load_lds_dwordx4 v132, s[100:101]
	s_waitcnt vmcnt(8) lgkmcnt(0)
	s_barrier
	v_mfma_f32_16x16x32_bf16 v[92:95], v[146:149], v[190:193], v[92:95]
	v_mfma_f32_16x16x32_bf16 v[88:91], v[154:157], v[190:193], v[88:91]
	v_mfma_f32_16x16x32_bf16 v[84:87], v[146:149], v[198:201], v[84:87]
	v_mfma_f32_16x16x32_bf16 v[80:83], v[154:157], v[198:201], v[80:83]
	v_mfma_f32_16x16x32_bf16 v[76:79], v[146:149], v[206:209], v[76:79]
	v_mfma_f32_16x16x32_bf16 v[72:75], v[154:157], v[206:209], v[72:75]
	v_mfma_f32_16x16x32_bf16 v[64:67], v[146:149], v[214:217], v[64:67]
	v_mfma_f32_16x16x32_bf16 v[56:59], v[154:157], v[214:217], v[56:59]
	v_mfma_f32_16x16x32_bf16 v[92:95], v[150:153], v[194:197], v[92:95]
	v_mfma_f32_16x16x32_bf16 v[88:91], v[170:173], v[194:197], v[88:91]
	v_mfma_f32_16x16x32_bf16 v[84:87], v[150:153], v[202:205], v[84:87]
	v_mfma_f32_16x16x32_bf16 v[80:83], v[170:173], v[202:205], v[80:83]
	v_mfma_f32_16x16x32_bf16 v[76:79], v[150:153], v[210:213], v[76:79]
	v_mfma_f32_16x16x32_bf16 v[72:75], v[170:173], v[210:213], v[72:75]
	v_mfma_f32_16x16x32_bf16 v[64:67], v[150:153], v[218:221], v[64:67]
	v_mfma_f32_16x16x32_bf16 v[56:59], v[170:173], v[218:221], v[56:59]
	v_mfma_f32_16x16x32_bf16 v[28:31], v[174:177], v[190:193], v[28:31]
	v_mfma_f32_16x16x32_bf16 v[24:27], v[182:185], v[190:193], v[24:27]
	v_mfma_f32_16x16x32_bf16 v[20:23], v[174:177], v[198:201], v[20:23]
	v_mfma_f32_16x16x32_bf16 v[16:19], v[182:185], v[198:201], v[16:19]
	v_mfma_f32_16x16x32_bf16 v[12:15], v[174:177], v[206:209], v[12:15]
	v_mfma_f32_16x16x32_bf16 v[8:11], v[182:185], v[206:209], v[8:11]
	v_mfma_f32_16x16x32_bf16 v[4:7], v[174:177], v[214:217], v[4:7]
	v_mfma_f32_16x16x32_bf16 v[0:3], v[182:185], v[214:217], v[0:3]
	v_mfma_f32_16x16x32_bf16 v[28:31], v[178:181], v[194:197], v[28:31]
	v_mfma_f32_16x16x32_bf16 v[24:27], v[186:189], v[194:197], v[24:27]
	v_mfma_f32_16x16x32_bf16 v[20:23], v[178:181], v[202:205], v[20:23]
	v_mfma_f32_16x16x32_bf16 v[16:19], v[186:189], v[202:205], v[16:19]
	v_mfma_f32_16x16x32_bf16 v[12:15], v[178:181], v[210:213], v[12:15]
	v_mfma_f32_16x16x32_bf16 v[8:11], v[186:189], v[210:213], v[8:11]
	v_mfma_f32_16x16x32_bf16 v[4:7], v[178:181], v[218:221], v[4:7]
	v_mfma_f32_16x16x32_bf16 v[0:3], v[186:189], v[218:221], v[0:3]
	s_barrier
	s_add_u32 s30, s30, 0x100
	s_addc_u32 s31, s31, 0
	s_add_u32 s56, s56, 0x100
	s_addc_u32 s57, s57, 0
	s_cmp_ge_u32 s58, s54
	s_mov_b64 s[98:99], s[34:35]
	s_mov_b32 s34, s58
	s_cbranch_scc0 .LBB0_264

; #define PG8_STAGE(bufoff, gbase, voff) do { _Pragma("unroll") for (int _i = 0; _i < 2; ++_i) \
;         __builtin_amdgcn_global_load_lds((const unsigned*)((const char*)(gbase) + (voff)[_i]), (LAS unsigned*)(lds + (bufoff) + ldsw + _i * 8192), 16, 0, 0); } while (0)
; #define PG8_LDA(dst, b, h) do { _Pragma("unroll") for (int m = 0; m < 4; ++m) _Pragma("unroll") for (int k = 0; k < 2; ++k) dst[m][k] = *(const LAS bf16x8*)(lds + PG8_SA(b, h) + aoff + m * 2048 + k * 1024); } while (0)
; #define PG8_LDB(dst, b, h) do { _Pragma("unroll") for (int n = 0; n < 2; ++n) _Pragma("unroll") for (int k = 0; k < 2; ++k) dst[n][k] = *(const LAS bf16x8*)(lds + PG8_SB(b, h) + boff + n * 2048 + k * 1024); } while (0)
; #define PG8_WAIT_V(n) asm volatile("s_waitcnt vmcnt(" #n ")" ::: "memory")
; #define PG8_WAIT_L(n) asm volatile("s_waitcnt lgkmcnt(" #n ")" ::: "memory")
; #define PG8_BAR __builtin_amdgcn_s_barrier()
; __device__ __forceinline__ void gemm_phase(LAS unsigned char* lds, const Params& p, const bf16_t* gA, const bf16_t* gBt, const int gM, const int gN, const int gK, const int epi, const int perm, bf16_t* const Hp, const int goff, const float coef) {
;     ...
;         const bool has_next = S.next(ui + 1, nxt);
;         const char* nA = has_next ? (const char*)gA + (size_t)nxt.pm * tstep + (nxt.ks > 0 ? nxt.ks * ksl : 0) : cA; const char* nB = has_next ? (const char*)gBt + (size_t)nxt.pn * tstep + (nxt.ks > 0 ? nxt.ks * ksl : 0) : cB;
;         const int nt = cur.ks >= 0 ? ntf / 4 : ntf;
;         for (int t = 0; t < nt; t += 2) {
;             const bool last = (t == nt - 2);
;             const char* a1 = cA + (size_t)(t + 1) * kstep;
;             const char* a2 = last ? nA : cA + (size_t)(t + 2) * kstep; const char* b2 = last ? nB : cB + (size_t)(t + 2) * kstep;
;             const char* a3 = a2 + kstep; const char* b3 = b2 + kstep;
;             PG8_LDB(B0, 0, 0); PG8_LDB(B1, 0, 1); PG8_SCHED; PG8_LDA(At, 0, 0); PG8_STAGE(PG8_SA(1, 1), a1 + hstep, voffA);
;             PG8_WAIT_V(8); PG8_WAIT_L(0); PG8_BAR; PG8_MMA(0, 0, At, B0); PG8_MMA(0, 1, At, B1); PG8_BAR; PG8_SCHED;
;             PG8_LDA(At, 0, 1); PG8_STAGE(PG8_SB(0, 0), b2, voffB); PG8_STAGE(PG8_SB(0, 1), b2 + hstep, voffB); PG8_STAGE(PG8_SA(0, 0), a2, voffA);
;             PG8_WAIT_V(8); PG8_WAIT_L(0); PG8_BAR; PG8_MMA(1, 0, At, B0); PG8_MMA(1, 1, At, B1); PG8_BAR; PG8_SCHED;
.LBB0_435:
	s_ashr_i32 s35, s34, 31
	s_lshl_b64 s[14:15], s[34:35], 20
	s_add_u32 s16, s3, s14
	s_addc_u32 s17, s27, s15
	s_lshl_b64 s[14:15], s[6:7], 10
	s_cmp_gt_i32 s6, 0
	s_cselect_b32 s33, s14, 0
	s_cselect_b32 s23, s15, 0
	s_add_u32 s40, s16, s33
	s_addc_u32 s41, s17, s23
	s_and_b64 s[14:15], s[38:39], exec
	s_cselect_b32 s14, s41, s1
	s_cselect_b32 s15, s40, s0
	s_ashr_i32 s37, s36, 31
	s_lshl_b64 s[16:17], s[36:37], 20
	s_add_u32 s16, s29, s16
	s_addc_u32 s17, s31, s17
	s_add_u32 s42, s16, s33
	s_addc_u32 s43, s17, s23
	s_and_b64 s[16:17], s[38:39], exec
	s_cselect_b32 s16, s43, s5
	s_cselect_b32 s17, s42, s4
	s_cmp_gt_i32 s22, -1
	s_cselect_b32 s22, 8, 32
	s_add_i32 s23, s22, -2
	s_add_u32 s0, s0, 0x80080
	s_addc_u32 s1, s1, 0
	s_add_u32 s33, s4, 0x100
	s_mov_b32 s45, 0
	s_addc_u32 s35, s5, 0
	v_add_u32_e32 v168, 0x18000, v171
	v_add_u32_e32 v169, 0x1c000, v171
	ds_read_b128 v[128:131], v180
	ds_read_b128 v[132:135], v180 offset:1024
	ds_read_b128 v[136:139], v180 offset:2048
	ds_read_b128 v[184:187], v180 offset:3072
	ds_read_b128 v[188:191], v181
	ds_read_b128 v[192:195], v181 offset:1024
	ds_read_b128 v[196:199], v181 offset:2048
	ds_read_b128 v[200:203], v181 offset:3072
	s_add_i32 s37, s45, 2
	s_add_u32 s4, s0, 0xfff80080
	s_addc_u32 s5, s1, -1
	s_cmp_eq_u32 s23, s45
	s_cselect_b32 s49, s14, s5
	s_cselect_b32 s48, s15, s4
	s_cselect_b32 s5, s16, s35
	s_cselect_b32 s4, s17, s33
	s_add_i32 m0, s47, 0xc000
	ds_read_b128 v[204:207], v182
	ds_read_b128 v[208:211], v182 offset:1024
	ds_read_b128 v[212:215], v182 offset:2048
	ds_read_b128 v[216:219], v182 offset:3072
	ds_read_b128 v[220:223], v182 offset:4096
	ds_read_b128 v[224:227], v182 offset:5120
	ds_read_b128 v[228:231], v182 offset:6144
	ds_read_b128 v[232:235], v182 offset:7168
	global_load_lds_dwordx4 v160, s[0:1]
	s_add_i32 m0, s47, 0xe000
	s_nop 0
	global_load_lds_dwordx4 v162, s[0:1]
	s_waitcnt vmcnt(8) lgkmcnt(0)
	s_barrier
	v_mfma_f32_16x16x32_bf16 v[124:127], v[128:131], v[204:207], 0
	v_mfma_f32_16x16x32_bf16 v[120:123], v[136:139], v[204:207], 0
	v_mfma_f32_16x16x32_bf16 v[108:111], v[128:131], v[212:215], 0
	v_mfma_f32_16x16x32_bf16 v[104:107], v[136:139], v[212:215], 0
	v_mfma_f32_16x16x32_bf16 v[92:95], v[128:131], v[220:223], 0
	v_mfma_f32_16x16x32_bf16 v[88:91], v[136:139], v[220:223], 0
	v_mfma_f32_16x16x32_bf16 v[76:79], v[128:131], v[228:231], 0
	v_mfma_f32_16x16x32_bf16 v[72:75], v[136:139], v[228:231], 0
	v_mfma_f32_16x16x32_bf16 v[124:127], v[132:135], v[208:211], v[124:127]
	v_mfma_f32_16x16x32_bf16 v[120:123], v[184:187], v[208:211], v[120:123]
	v_mfma_f32_16x16x32_bf16 v[108:111], v[132:135], v[216:219], v[108:111]
	v_mfma_f32_16x16x32_bf16 v[104:107], v[184:187], v[216:219], v[104:107]
	v_mfma_f32_16x16x32_bf16 v[92:95], v[132:135], v[224:227], v[92:95]
	v_mfma_f32_16x16x32_bf16 v[88:91], v[184:187], v[224:227], v[88:91]
	v_mfma_f32_16x16x32_bf16 v[76:79], v[132:135], v[232:235], v[76:79]
	v_mfma_f32_16x16x32_bf16 v[72:75], v[184:187], v[232:235], v[72:75]
	v_mfma_f32_16x16x32_bf16 v[116:119], v[188:191], v[204:207], 0
	v_mfma_f32_16x16x32_bf16 v[112:115], v[196:199], v[204:207], 0
	v_mfma_f32_16x16x32_bf16 v[100:103], v[188:191], v[212:215], 0
	v_mfma_f32_16x16x32_bf16 v[96:99], v[196:199], v[212:215], 0
	v_mfma_f32_16x16x32_bf16 v[84:87], v[188:191], v[220:223], 0
	v_mfma_f32_16x16x32_bf16 v[80:83], v[196:199], v[220:223], 0
	v_mfma_f32_16x16x32_bf16 v[68:71], v[188:191], v[228:231], 0
	v_mfma_f32_16x16x32_bf16 v[64:67], v[196:199], v[228:231], 0
	v_mfma_f32_16x16x32_bf16 v[116:119], v[192:195], v[208:211], v[116:119]
	v_mfma_f32_16x16x32_bf16 v[112:115], v[200:203], v[208:211], v[112:115]
	v_mfma_f32_16x16x32_bf16 v[100:103], v[192:195], v[216:219], v[100:103]
	v_mfma_f32_16x16x32_bf16 v[96:99], v[200:203], v[216:219], v[96:99]
	v_mfma_f32_16x16x32_bf16 v[84:87], v[192:195], v[224:227], v[84:87]
	v_mfma_f32_16x16x32_bf16 v[80:83], v[200:203], v[224:227], v[80:83]
	v_mfma_f32_16x16x32_bf16 v[68:71], v[192:195], v[232:235], v[68:71]
	v_mfma_f32_16x16x32_bf16 v[64:67], v[200:203], v[232:235], v[64:67]
	s_barrier
	s_add_i32 s45, s19, s52
	s_mov_b32 m0, s45
	ds_read_b128 v[204:207], v182 offset:16384
	ds_read_b128 v[208:211], v182 offset:17408
	ds_read_b128 v[212:215], v182 offset:18432
	ds_read_b128 v[216:219], v182 offset:19456
	ds_read_b128 v[220:223], v182 offset:20480
	ds_read_b128 v[224:227], v182 offset:21504
	ds_read_b128 v[228:231], v182 offset:22528
	ds_read_b128 v[232:235], v182 offset:23552
	global_load_lds_dwordx4 v144, s[4:5]
	s_add_i32 m0, s45, 0x2000
	s_add_u32 s50, s4, 0x80000
	s_addc_u32 s51, s5, 0
	s_add_i32 s45, s21, s52
	global_load_lds_dwordx4 v148, s[4:5]
	s_mov_b32 m0, s45
	s_nop 0
	global_load_lds_dwordx4 v144, s[50:51]
	s_add_i32 m0, s45, 0x2000
	s_nop 0
	global_load_lds_dwordx4 v148, s[50:51]
	s_mov_b32 m0, s47
	s_nop 0
	global_load_lds_dwordx4 v142, s[48:49]
	s_mov_b32 m0, s53
	s_nop 0
	global_load_lds_dwordx4 v146, s[48:49]
	s_waitcnt vmcnt(8) lgkmcnt(0)
	s_barrier
; #define PG8_STAGE(bufoff, gbase, voff) do { _Pragma("unroll") for (int _i = 0; _i < 2; ++_i) \
;         __builtin_amdgcn_global_load_lds((const unsigned*)((const char*)(gbase) + (voff)[_i]), (LAS unsigned*)(lds + (bufoff) + ldsw + _i * 8192), 16, 0, 0); } while (0)
; #define PG8_LDA(dst, b, h) do { _Pragma("unroll") for (int m = 0; m < 4; ++m) _Pragma("unroll") for (int k = 0; k < 2; ++k) dst[m][k] = *(const LAS bf16x8*)(lds + PG8_SA(b, h) + aoff + m * 2048 + k * 1024); } while (0)
; #define PG8_LDB(dst, b, h) do { _Pragma("unroll") for (int n = 0; n < 2; ++n) _Pragma("unroll") for (int k = 0; k < 2; ++k) dst[n][k] = *(const LAS bf16x8*)(lds + PG8_SB(b, h) + boff + n * 2048 + k * 1024); } while (0)
; #define PG8_MMA(ai, bj, At, Bt) do { __builtin_amdgcn_s_setprio(1); _Pragma("unroll") for (int m = 0; m < 4; ++m) _Pragma("unroll") for (int n = 0; n < 2; ++n) _Pragma("unroll") for (int k = 0; k < 2; ++k) \
;         acc[ai][bj][m][n] = __builtin_amdgcn_mfma_f32_16x16x32_bf16(Bt[n][k], At[m][k], acc[ai][bj][m][n], 0, 0, 0); __builtin_amdgcn_s_setprio(0); } while (0)
; #define PG8_WAIT_V(n) asm volatile("s_waitcnt vmcnt(" #n ")" ::: "memory")
; #define PG8_WAIT_L(n) asm volatile("s_waitcnt lgkmcnt(" #n ")" ::: "memory")
; #define PG8_BAR __builtin_amdgcn_s_barrier()
; #define PG8_SCHED __builtin_amdgcn_sched_barrier(0)
; __device__ __forceinline__ void gemm_phase(LAS unsigned char* lds, const Params& p, const bf16_t* gA, const bf16_t* gBt, const int gM, const int gN, const int gK, const int epi, const int perm, bf16_t* const Hp, const int goff, const float coef) {
;     ...
;             PG8_WAIT_V(8); PG8_WAIT_L(0); PG8_BAR; PG8_MMA(1, 0, At, B0); PG8_MMA(1, 1, At, B1); PG8_BAR; PG8_SCHED;
;             PG8_LDB(B0, 1, 0); PG8_LDB(B1, 1, 1); PG8_SCHED; PG8_LDA(At, 1, 0); PG8_STAGE(PG8_SA(0, 1), a2 + hstep, voffA);
;             PG8_WAIT_V(8); PG8_WAIT_L(0); PG8_BAR; PG8_MMA(0, 0, At, B0); PG8_MMA(0, 1, At, B1); PG8_BAR; PG8_SCHED;
	v_mfma_f32_16x16x32_bf16 v[60:63], v[128:131], v[204:207], 0
	v_mfma_f32_16x16x32_bf16 v[56:59], v[136:139], v[204:207], 0
	v_mfma_f32_16x16x32_bf16 v[44:47], v[128:131], v[212:215], 0
	v_mfma_f32_16x16x32_bf16 v[40:43], v[136:139], v[212:215], 0
	v_mfma_f32_16x16x32_bf16 v[28:31], v[128:131], v[220:223], 0
	v_mfma_f32_16x16x32_bf16 v[24:27], v[136:139], v[220:223], 0
	v_mfma_f32_16x16x32_bf16 v[12:15], v[128:131], v[228:231], 0
	v_mfma_f32_16x16x32_bf16 v[8:11], v[136:139], v[228:231], 0
	v_mfma_f32_16x16x32_bf16 v[60:63], v[132:135], v[208:211], v[60:63]
	v_mfma_f32_16x16x32_bf16 v[56:59], v[184:187], v[208:211], v[56:59]
	v_mfma_f32_16x16x32_bf16 v[44:47], v[132:135], v[216:219], v[44:47]
	v_mfma_f32_16x16x32_bf16 v[40:43], v[184:187], v[216:219], v[40:43]
	v_mfma_f32_16x16x32_bf16 v[28:31], v[132:135], v[224:227], v[28:31]
	v_mfma_f32_16x16x32_bf16 v[24:27], v[184:187], v[224:227], v[24:27]
	v_mfma_f32_16x16x32_bf16 v[12:15], v[132:135], v[232:235], v[12:15]
	v_mfma_f32_16x16x32_bf16 v[8:11], v[184:187], v[232:235], v[8:11]
	v_mfma_f32_16x16x32_bf16 v[52:55], v[188:191], v[204:207], 0
	v_mfma_f32_16x16x32_bf16 v[48:51], v[196:199], v[204:207], 0
	v_mfma_f32_16x16x32_bf16 v[36:39], v[188:191], v[212:215], 0
	v_mfma_f32_16x16x32_bf16 v[32:35], v[196:199], v[212:215], 0
	v_mfma_f32_16x16x32_bf16 v[20:23], v[188:191], v[220:223], 0
	v_mfma_f32_16x16x32_bf16 v[16:19], v[196:199], v[220:223], 0
	v_mfma_f32_16x16x32_bf16 v[4:7], v[188:191], v[228:231], 0
	v_mfma_f32_16x16x32_bf16 v[0:3], v[196:199], v[228:231], 0
	v_mfma_f32_16x16x32_bf16 v[52:55], v[192:195], v[208:211], v[52:55]
	v_mfma_f32_16x16x32_bf16 v[48:51], v[200:203], v[208:211], v[48:51]
	v_mfma_f32_16x16x32_bf16 v[36:39], v[192:195], v[216:219], v[36:39]
	v_mfma_f32_16x16x32_bf16 v[32:35], v[200:203], v[216:219], v[32:35]
	v_mfma_f32_16x16x32_bf16 v[20:23], v[192:195], v[224:227], v[20:23]
	v_mfma_f32_16x16x32_bf16 v[16:19], v[200:203], v[224:227], v[16:19]
	v_mfma_f32_16x16x32_bf16 v[4:7], v[192:195], v[232:235], v[4:7]
	v_mfma_f32_16x16x32_bf16 v[0:3], v[200:203], v[232:235], v[0:3]
	s_barrier
	s_add_i32 s45, 0, 0x18000
	s_add_i32 s50, 0, 0x1c000
	ds_read_b128 v[128:131], v168
	ds_read_b128 v[132:135], v168 offset:1024
	ds_read_b128 v[136:139], v168 offset:2048
	ds_read_b128 v[184:187], v168 offset:3072
	ds_read_b128 v[188:191], v169
	ds_read_b128 v[192:195], v169 offset:1024
	ds_read_b128 v[196:199], v169 offset:2048
	ds_read_b128 v[200:203], v169 offset:3072
	s_add_u32 s48, s48, 0x80000
	s_addc_u32 s49, s49, 0
	s_mov_b32 m0, s54
	ds_read_b128 v[204:207], v182 offset:32768
	ds_read_b128 v[208:211], v182 offset:33792
	ds_read_b128 v[212:215], v182 offset:34816
	ds_read_b128 v[216:219], v182 offset:35840
	ds_read_b128 v[220:223], v182 offset:36864
	ds_read_b128 v[224:227], v182 offset:37888
	ds_read_b128 v[228:231], v182 offset:38912
	ds_read_b128 v[232:235], v182 offset:39936
	global_load_lds_dwordx4 v142, s[48:49]
	s_mov_b32 m0, s55
	s_nop 0
	global_load_lds_dwordx4 v146, s[48:49]
	s_waitcnt vmcnt(8) lgkmcnt(0)
	s_barrier
	v_mfma_f32_16x16x32_bf16 v[124:127], v[128:131], v[204:207], v[124:127]
	v_mfma_f32_16x16x32_bf16 v[120:123], v[136:139], v[204:207], v[120:123]
	v_mfma_f32_16x16x32_bf16 v[108:111], v[128:131], v[212:215], v[108:111]
	v_mfma_f32_16x16x32_bf16 v[104:107], v[136:139], v[212:215], v[104:107]
	v_mfma_f32_16x16x32_bf16 v[92:95], v[128:131], v[220:223], v[92:95]
	v_mfma_f32_16x16x32_bf16 v[88:91], v[136:139], v[220:223], v[88:91]
	v_mfma_f32_16x16x32_bf16 v[76:79], v[128:131], v[228:231], v[76:79]
	v_mfma_f32_16x16x32_bf16 v[72:75], v[136:139], v[228:231], v[72:75]
	v_mfma_f32_16x16x32_bf16 v[124:127], v[132:135], v[208:211], v[124:127]
	v_mfma_f32_16x16x32_bf16 v[120:123], v[184:187], v[208:211], v[120:123]
	v_mfma_f32_16x16x32_bf16 v[108:111], v[132:135], v[216:219], v[108:111]
	v_mfma_f32_16x16x32_bf16 v[104:107], v[184:187], v[216:219], v[104:107]
	v_mfma_f32_16x16x32_bf16 v[92:95], v[132:135], v[224:227], v[92:95]
	v_mfma_f32_16x16x32_bf16 v[88:91], v[184:187], v[224:227], v[88:91]
	v_mfma_f32_16x16x32_bf16 v[76:79], v[132:135], v[232:235], v[76:79]
	v_mfma_f32_16x16x32_bf16 v[72:75], v[184:187], v[232:235], v[72:75]
	v_mfma_f32_16x16x32_bf16 v[116:119], v[188:191], v[204:207], v[116:119]
	v_mfma_f32_16x16x32_bf16 v[112:115], v[196:199], v[204:207], v[112:115]
	v_mfma_f32_16x16x32_bf16 v[100:103], v[188:191], v[212:215], v[100:103]
	v_mfma_f32_16x16x32_bf16 v[96:99], v[196:199], v[212:215], v[96:99]
	v_mfma_f32_16x16x32_bf16 v[84:87], v[188:191], v[220:223], v[84:87]
	v_mfma_f32_16x16x32_bf16 v[80:83], v[196:199], v[220:223], v[80:83]
	v_mfma_f32_16x16x32_bf16 v[68:71], v[188:191], v[228:231], v[68:71]
	v_mfma_f32_16x16x32_bf16 v[64:67], v[196:199], v[228:231], v[64:67]
	v_mfma_f32_16x16x32_bf16 v[116:119], v[192:195], v[208:211], v[116:119]
	v_mfma_f32_16x16x32_bf16 v[112:115], v[200:203], v[208:211], v[112:115]
	v_mfma_f32_16x16x32_bf16 v[100:103], v[192:195], v[216:219], v[100:103]
	v_mfma_f32_16x16x32_bf16 v[96:99], v[200:203], v[216:219], v[96:99]
	v_mfma_f32_16x16x32_bf16 v[84:87], v[192:195], v[224:227], v[84:87]
	v_mfma_f32_16x16x32_bf16 v[80:83], v[200:203], v[224:227], v[80:83]
	v_mfma_f32_16x16x32_bf16 v[68:71], v[192:195], v[232:235], v[68:71]
	v_mfma_f32_16x16x32_bf16 v[64:67], v[200:203], v[232:235], v[64:67]
	s_barrier
; #define PG8_STAGE(bufoff, gbase, voff) do { _Pragma("unroll") for (int _i = 0; _i < 2; ++_i) \
;         __builtin_amdgcn_global_load_lds((const unsigned*)((const char*)(gbase) + (voff)[_i]), (LAS unsigned*)(lds + (bufoff) + ldsw + _i * 8192), 16, 0, 0); } while (0)
; #define PG8_LDA(dst, b, h) do { _Pragma("unroll") for (int m = 0; m < 4; ++m) _Pragma("unroll") for (int k = 0; k < 2; ++k) dst[m][k] = *(const LAS bf16x8*)(lds + PG8_SA(b, h) + aoff + m * 2048 + k * 1024); } while (0)
; #define PG8_LDB(dst, b, h) do { _Pragma("unroll") for (int n = 0; n < 2; ++n) _Pragma("unroll") for (int k = 0; k < 2; ++k) dst[n][k] = *(const LAS bf16x8*)(lds + PG8_SB(b, h) + boff + n * 2048 + k * 1024); } while (0)
; #define PG8_BAR __builtin_amdgcn_s_barrier()
; __device__ __forceinline__ void gemm_phase(LAS unsigned char* lds, const Params& p, const bf16_t* gA, const bf16_t* gBt, const int gM, const int gN, const int gK, const int epi, const int perm, bf16_t* const Hp, const int goff, const float coef) {
;     ...
;         for (int t = 0; t < nt; t += 2) {
;             const bool last = (t == nt - 2);
;             const char* a1 = cA + (size_t)(t + 1) * kstep;
;             const char* a2 = last ? nA : cA + (size_t)(t + 2) * kstep; const char* b2 = last ? nB : cB + (size_t)(t + 2) * kstep;
;             const char* a3 = a2 + kstep; const char* b3 = b2 + kstep;
;             PG8_LDB(B0, 0, 0); PG8_LDB(B1, 0, 1); PG8_SCHED; PG8_LDA(At, 0, 0); PG8_STAGE(PG8_SA(1, 1), a1 + hstep, voffA);
;             PG8_WAIT_V(8); PG8_WAIT_L(0); PG8_BAR; PG8_MMA(0, 0, At, B0); PG8_MMA(0, 1, At, B1); PG8_BAR; PG8_SCHED;
;             PG8_LDA(At, 0, 1); PG8_STAGE(PG8_SB(0, 0), b2, voffB); PG8_STAGE(PG8_SB(0, 1), b2 + hstep, voffB); PG8_STAGE(PG8_SA(0, 0), a2, voffA);
;             PG8_WAIT_V(8); PG8_WAIT_L(0); PG8_BAR; PG8_MMA(1, 0, At, B0); PG8_MMA(1, 1, At, B1); PG8_BAR; PG8_SCHED;
;             PG8_LDB(B0, 1, 0); PG8_LDB(B1, 1, 1); PG8_SCHED; PG8_LDA(At, 1, 0); PG8_STAGE(PG8_SA(0, 1), a2 + hstep, voffA);
;             PG8_WAIT_V(8); PG8_WAIT_L(0); PG8_BAR; PG8_MMA(0, 0, At, B0); PG8_MMA(0, 1, At, B1); PG8_BAR; PG8_SCHED;
;             PG8_LDA(At, 1, 1); PG8_STAGE(PG8_SB(1, 0), b3, voffB); PG8_STAGE(PG8_SB(1, 1), b3 + hstep, voffB); PG8_STAGE(PG8_SA(1, 0), a3, voffA);
;             PG8_WAIT_V(8); PG8_WAIT_L(0); PG8_BAR; PG8_MMA(1, 0, At, B0); PG8_MMA(1, 1, At, B1); PG8_BAR; PG8_SCHED;
	s_add_i32 s45, s45, s52
	s_mov_b32 m0, s45
	ds_read_b128 v[204:207], v182 offset:49152
	ds_read_b128 v[208:211], v182 offset:50176
	ds_read_b128 v[212:215], v182 offset:51200
	ds_read_b128 v[216:219], v182 offset:52224
	ds_read_b128 v[220:223], v182 offset:53248
	ds_read_b128 v[224:227], v182 offset:54272
	ds_read_b128 v[228:231], v182 offset:55296
	ds_read_b128 v[232:235], v182 offset:56320
	s_add_u32 s98, s4, 0x80
	s_addc_u32 s99, s5, 0
	global_load_lds_dwordx4 v144, s[98:99]
	s_add_i32 m0, s45, 0x2000
	s_add_u32 s4, s4, 0x80080
	s_addc_u32 s5, s5, 0
	s_add_i32 s45, s50, s52
	global_load_lds_dwordx4 v148, s[98:99]
	s_mov_b32 m0, s45
	s_nop 0
	global_load_lds_dwordx4 v144, s[4:5]
	s_add_i32 m0, s45, 0x2000
	s_nop 0
	global_load_lds_dwordx4 v148, s[4:5]
	s_mov_b32 m0, s57
	s_add_u32 s100, s48, 0xfff80080
	s_addc_u32 s101, s49, -1
	global_load_lds_dwordx4 v142, s[100:101]
	s_mov_b32 m0, s58
	s_nop 0
	global_load_lds_dwordx4 v146, s[100:101]
	s_waitcnt vmcnt(8) lgkmcnt(0)
	s_barrier
	v_mfma_f32_16x16x32_bf16 v[60:63], v[128:131], v[204:207], v[60:63]
	v_mfma_f32_16x16x32_bf16 v[56:59], v[136:139], v[204:207], v[56:59]
	v_mfma_f32_16x16x32_bf16 v[44:47], v[128:131], v[212:215], v[44:47]
	v_mfma_f32_16x16x32_bf16 v[40:43], v[136:139], v[212:215], v[40:43]
	v_mfma_f32_16x16x32_bf16 v[28:31], v[128:131], v[220:223], v[28:31]
	v_mfma_f32_16x16x32_bf16 v[24:27], v[136:139], v[220:223], v[24:27]
	v_mfma_f32_16x16x32_bf16 v[12:15], v[128:131], v[228:231], v[12:15]
	v_mfma_f32_16x16x32_bf16 v[8:11], v[136:139], v[228:231], v[8:11]
	v_mfma_f32_16x16x32_bf16 v[60:63], v[132:135], v[208:211], v[60:63]
	v_mfma_f32_16x16x32_bf16 v[56:59], v[184:187], v[208:211], v[56:59]
	v_mfma_f32_16x16x32_bf16 v[44:47], v[132:135], v[216:219], v[44:47]
	v_mfma_f32_16x16x32_bf16 v[40:43], v[184:187], v[216:219], v[40:43]
	v_mfma_f32_16x16x32_bf16 v[28:31], v[132:135], v[224:227], v[28:31]
	v_mfma_f32_16x16x32_bf16 v[24:27], v[184:187], v[224:227], v[24:27]
	v_mfma_f32_16x16x32_bf16 v[12:15], v[132:135], v[232:235], v[12:15]
	v_mfma_f32_16x16x32_bf16 v[8:11], v[184:187], v[232:235], v[8:11]
	v_mfma_f32_16x16x32_bf16 v[52:55], v[188:191], v[204:207], v[52:55]
	v_mfma_f32_16x16x32_bf16 v[48:51], v[196:199], v[204:207], v[48:51]
	v_mfma_f32_16x16x32_bf16 v[36:39], v[188:191], v[212:215], v[36:39]
	v_mfma_f32_16x16x32_bf16 v[32:35], v[196:199], v[212:215], v[32:35]
	v_mfma_f32_16x16x32_bf16 v[20:23], v[188:191], v[220:223], v[20:23]
	v_mfma_f32_16x16x32_bf16 v[16:19], v[196:199], v[220:223], v[16:19]
	v_mfma_f32_16x16x32_bf16 v[4:7], v[188:191], v[228:231], v[4:7]
	v_mfma_f32_16x16x32_bf16 v[0:3], v[196:199], v[228:231], v[0:3]
	v_mfma_f32_16x16x32_bf16 v[52:55], v[192:195], v[208:211], v[52:55]
	v_mfma_f32_16x16x32_bf16 v[48:51], v[200:203], v[208:211], v[48:51]
	v_mfma_f32_16x16x32_bf16 v[36:39], v[192:195], v[216:219], v[36:39]
	v_mfma_f32_16x16x32_bf16 v[32:35], v[200:203], v[216:219], v[32:35]
	v_mfma_f32_16x16x32_bf16 v[20:23], v[192:195], v[224:227], v[20:23]
	v_mfma_f32_16x16x32_bf16 v[16:19], v[200:203], v[224:227], v[16:19]
	v_mfma_f32_16x16x32_bf16 v[4:7], v[192:195], v[232:235], v[4:7]
	v_mfma_f32_16x16x32_bf16 v[0:3], v[200:203], v[232:235], v[0:3]
	s_barrier
	s_add_u32 s0, s0, 0x100
	s_addc_u32 s1, s1, 0
	s_add_u32 s33, s33, 0x100
	s_addc_u32 s35, s35, 0
	s_cmp_ge_u32 s37, s22
	s_mov_b32 s45, s37
	s_cbranch_scc1 .Lpeel_exit_2
.LBB0_436:
	ds_read_b128 v[128:131], v180
	ds_read_b128 v[132:135], v180 offset:1024
	ds_read_b128 v[136:139], v180 offset:2048
	ds_read_b128 v[184:187], v180 offset:3072
	ds_read_b128 v[188:191], v181
	ds_read_b128 v[192:195], v181 offset:1024
	ds_read_b128 v[196:199], v181 offset:2048
	ds_read_b128 v[200:203], v181 offset:3072
	s_add_i32 s37, s45, 2
	s_add_u32 s4, s0, 0xfff80080
	s_addc_u32 s5, s1, -1
	s_cmp_eq_u32 s23, s45
	s_cselect_b32 s49, s14, s5
	s_cselect_b32 s48, s15, s4
	s_cselect_b32 s5, s16, s35
	s_cselect_b32 s4, s17, s33
	s_add_i32 m0, s47, 0xc000
	ds_read_b128 v[204:207], v182
	ds_read_b128 v[208:211], v182 offset:1024
	ds_read_b128 v[212:215], v182 offset:2048
	ds_read_b128 v[216:219], v182 offset:3072
	ds_read_b128 v[220:223], v182 offset:4096
	ds_read_b128 v[224:227], v182 offset:5120
	ds_read_b128 v[228:231], v182 offset:6144
	ds_read_b128 v[232:235], v182 offset:7168
	global_load_lds_dwordx4 v160, s[0:1]
	s_add_i32 m0, s47, 0xe000
	s_nop 0
	global_load_lds_dwordx4 v162, s[0:1]
	s_waitcnt vmcnt(8) lgkmcnt(0)
	s_barrier
	v_mfma_f32_16x16x32_bf16 v[124:127], v[128:131], v[204:207], v[124:127]
	v_mfma_f32_16x16x32_bf16 v[120:123], v[136:139], v[204:207], v[120:123]
	v_mfma_f32_16x16x32_bf16 v[108:111], v[128:131], v[212:215], v[108:111]
	v_mfma_f32_16x16x32_bf16 v[104:107], v[136:139], v[212:215], v[104:107]
	v_mfma_f32_16x16x32_bf16 v[92:95], v[128:131], v[220:223], v[92:95]
	v_mfma_f32_16x16x32_bf16 v[88:91], v[136:139], v[220:223], v[88:91]
	v_mfma_f32_16x16x32_bf16 v[76:79], v[128:131], v[228:231], v[76:79]
	v_mfma_f32_16x16x32_bf16 v[72:75], v[136:139], v[228:231], v[72:75]
	v_mfma_f32_16x16x32_bf16 v[124:127], v[132:135], v[208:211], v[124:127]
	v_mfma_f32_16x16x32_bf16 v[120:123], v[184:187], v[208:211], v[120:123]
	v_mfma_f32_16x16x32_bf16 v[108:111], v[132:135], v[216:219], v[108:111]
	v_mfma_f32_16x16x32_bf16 v[104:107], v[184:187], v[216:219], v[104:107]
	v_mfma_f32_16x16x32_bf16 v[92:95], v[132:135], v[224:227], v[92:95]
	v_mfma_f32_16x16x32_bf16 v[88:91], v[184:187], v[224:227], v[88:91]
	v_mfma_f32_16x16x32_bf16 v[76:79], v[132:135], v[232:235], v[76:79]
	v_mfma_f32_16x16x32_bf16 v[72:75], v[184:187], v[232:235], v[72:75]
	v_mfma_f32_16x16x32_bf16 v[116:119], v[188:191], v[204:207], v[116:119]
	v_mfma_f32_16x16x32_bf16 v[112:115], v[196:199], v[204:207], v[112:115]
	v_mfma_f32_16x16x32_bf16 v[100:103], v[188:191], v[212:215], v[100:103]
	v_mfma_f32_16x16x32_bf16 v[96:99], v[196:199], v[212:215], v[96:99]
	v_mfma_f32_16x16x32_bf16 v[84:87], v[188:191], v[220:223], v[84:87]
	v_mfma_f32_16x16x32_bf16 v[80:83], v[196:199], v[220:223], v[80:83]
	v_mfma_f32_16x16x32_bf16 v[68:71], v[188:191], v[228:231], v[68:71]
	v_mfma_f32_16x16x32_bf16 v[64:67], v[196:199], v[228:231], v[64:67]
	v_mfma_f32_16x16x32_bf16 v[116:119], v[192:195], v[208:211], v[116:119]
	v_mfma_f32_16x16x32_bf16 v[112:115], v[200:203], v[208:211], v[112:115]
	v_mfma_f32_16x16x32_bf16 v[100:103], v[192:195], v[216:219], v[100:103]
	v_mfma_f32_16x16x32_bf16 v[96:99], v[200:203], v[216:219], v[96:99]
	v_mfma_f32_16x16x32_bf16 v[84:87], v[192:195], v[224:227], v[84:87]
	v_mfma_f32_16x16x32_bf16 v[80:83], v[200:203], v[224:227], v[80:83]
	v_mfma_f32_16x16x32_bf16 v[68:71], v[192:195], v[232:235], v[68:71]
	v_mfma_f32_16x16x32_bf16 v[64:67], v[200:203], v[232:235], v[64:67]
	s_barrier
; #define PG8_STAGE(bufoff, gbase, voff) do { _Pragma("unroll") for (int _i = 0; _i < 2; ++_i) \
;         __builtin_amdgcn_global_load_lds((const unsigned*)((const char*)(gbase) + (voff)[_i]), (LAS unsigned*)(lds + (bufoff) + ldsw + _i * 8192), 16, 0, 0); } while (0)
; #define PG8_LDA(dst, b, h) do { _Pragma("unroll") for (int m = 0; m < 4; ++m) _Pragma("unroll") for (int k = 0; k < 2; ++k) dst[m][k] = *(const LAS bf16x8*)(lds + PG8_SA(b, h) + aoff + m * 2048 + k * 1024); } while (0)
; #define PG8_LDB(dst, b, h) do { _Pragma("unroll") for (int n = 0; n < 2; ++n) _Pragma("unroll") for (int k = 0; k < 2; ++k) dst[n][k] = *(const LAS bf16x8*)(lds + PG8_SB(b, h) + boff + n * 2048 + k * 1024); } while (0)
; #define PG8_MMA(ai, bj, At, Bt) do { __builtin_amdgcn_s_setprio(1); _Pragma("unroll") for (int m = 0; m < 4; ++m) _Pragma("unroll") for (int n = 0; n < 2; ++n) _Pragma("unroll") for (int k = 0; k < 2; ++k) \
;         acc[ai][bj][m][n] = __builtin_amdgcn_mfma_f32_16x16x32_bf16(Bt[n][k], At[m][k], acc[ai][bj][m][n], 0, 0, 0); __builtin_amdgcn_s_setprio(0); } while (0)
; #define PG8_WAIT_V(n) asm volatile("s_waitcnt vmcnt(" #n ")" ::: "memory")
; #define PG8_WAIT_L(n) asm volatile("s_waitcnt lgkmcnt(" #n ")" ::: "memory")
; #define PG8_BAR __builtin_amdgcn_s_barrier()
; #define PG8_SCHED __builtin_amdgcn_sched_barrier(0)
; __device__ __forceinline__ void gemm_phase(LAS unsigned char* lds, const Params& p, const bf16_t* gA, const bf16_t* gBt, const int gM, const int gN, const int gK, const int epi, const int perm, bf16_t* const Hp, const int goff, const float coef) {
;     ...
;             PG8_LDA(At, 0, 1); PG8_STAGE(PG8_SB(0, 0), b2, voffB); PG8_STAGE(PG8_SB(0, 1), b2 + hstep, voffB); PG8_STAGE(PG8_SA(0, 0), a2, voffA);
;             PG8_WAIT_V(8); PG8_WAIT_L(0); PG8_BAR; PG8_MMA(1, 0, At, B0); PG8_MMA(1, 1, At, B1); PG8_BAR; PG8_SCHED;
;             PG8_LDB(B0, 1, 0); PG8_LDB(B1, 1, 1); PG8_SCHED; PG8_LDA(At, 1, 0); PG8_STAGE(PG8_SA(0, 1), a2 + hstep, voffA);
;             PG8_WAIT_V(8); PG8_WAIT_L(0); PG8_BAR; PG8_MMA(0, 0, At, B0); PG8_MMA(0, 1, At, B1); PG8_BAR; PG8_SCHED;
	s_add_i32 s45, s19, s52
	s_mov_b32 m0, s45
	ds_read_b128 v[204:207], v182 offset:16384
	ds_read_b128 v[208:211], v182 offset:17408
	ds_read_b128 v[212:215], v182 offset:18432
	ds_read_b128 v[216:219], v182 offset:19456
	ds_read_b128 v[220:223], v182 offset:20480
	ds_read_b128 v[224:227], v182 offset:21504
	ds_read_b128 v[228:231], v182 offset:22528
	ds_read_b128 v[232:235], v182 offset:23552
	global_load_lds_dwordx4 v144, s[4:5]
	s_add_i32 m0, s45, 0x2000
	s_add_u32 s50, s4, 0x80000
	s_addc_u32 s51, s5, 0
	s_add_i32 s45, s21, s52
	global_load_lds_dwordx4 v148, s[4:5]
	s_mov_b32 m0, s45
	s_nop 0
	global_load_lds_dwordx4 v144, s[50:51]
	s_add_i32 m0, s45, 0x2000
	s_nop 0
	global_load_lds_dwordx4 v148, s[50:51]
	s_mov_b32 m0, s47
	s_nop 0
	global_load_lds_dwordx4 v142, s[48:49]
	s_mov_b32 m0, s53
	s_nop 0
	global_load_lds_dwordx4 v146, s[48:49]
	s_waitcnt vmcnt(8) lgkmcnt(0)
	s_barrier
	v_mfma_f32_16x16x32_bf16 v[60:63], v[128:131], v[204:207], v[60:63]
	v_mfma_f32_16x16x32_bf16 v[56:59], v[136:139], v[204:207], v[56:59]
	v_mfma_f32_16x16x32_bf16 v[44:47], v[128:131], v[212:215], v[44:47]
	v_mfma_f32_16x16x32_bf16 v[40:43], v[136:139], v[212:215], v[40:43]
	v_mfma_f32_16x16x32_bf16 v[28:31], v[128:131], v[220:223], v[28:31]
	v_mfma_f32_16x16x32_bf16 v[24:27], v[136:139], v[220:223], v[24:27]
	v_mfma_f32_16x16x32_bf16 v[12:15], v[128:131], v[228:231], v[12:15]
	v_mfma_f32_16x16x32_bf16 v[8:11], v[136:139], v[228:231], v[8:11]
	v_mfma_f32_16x16x32_bf16 v[60:63], v[132:135], v[208:211], v[60:63]
	v_mfma_f32_16x16x32_bf16 v[56:59], v[184:187], v[208:211], v[56:59]
	v_mfma_f32_16x16x32_bf16 v[44:47], v[132:135], v[216:219], v[44:47]
	v_mfma_f32_16x16x32_bf16 v[40:43], v[184:187], v[216:219], v[40:43]
	v_mfma_f32_16x16x32_bf16 v[28:31], v[132:135], v[224:227], v[28:31]
	v_mfma_f32_16x16x32_bf16 v[24:27], v[184:187], v[224:227], v[24:27]
	v_mfma_f32_16x16x32_bf16 v[12:15], v[132:135], v[232:235], v[12:15]
	v_mfma_f32_16x16x32_bf16 v[8:11], v[184:187], v[232:235], v[8:11]
	v_mfma_f32_16x16x32_bf16 v[52:55], v[188:191], v[204:207], v[52:55]
	v_mfma_f32_16x16x32_bf16 v[48:51], v[196:199], v[204:207], v[48:51]
	v_mfma_f32_16x16x32_bf16 v[36:39], v[188:191], v[212:215], v[36:39]
	v_mfma_f32_16x16x32_bf16 v[32:35], v[196:199], v[212:215], v[32:35]
	v_mfma_f32_16x16x32_bf16 v[20:23], v[188:191], v[220:223], v[20:23]
	v_mfma_f32_16x16x32_bf16 v[16:19], v[196:199], v[220:223], v[16:19]
	v_mfma_f32_16x16x32_bf16 v[4:7], v[188:191], v[228:231], v[4:7]
	v_mfma_f32_16x16x32_bf16 v[0:3], v[196:199], v[228:231], v[0:3]
	v_mfma_f32_16x16x32_bf16 v[52:55], v[192:195], v[208:211], v[52:55]
	v_mfma_f32_16x16x32_bf16 v[48:51], v[200:203], v[208:211], v[48:51]
	v_mfma_f32_16x16x32_bf16 v[36:39], v[192:195], v[216:219], v[36:39]
	v_mfma_f32_16x16x32_bf16 v[32:35], v[200:203], v[216:219], v[32:35]
	v_mfma_f32_16x16x32_bf16 v[20:23], v[192:195], v[224:227], v[20:23]
	v_mfma_f32_16x16x32_bf16 v[16:19], v[200:203], v[224:227], v[16:19]
	v_mfma_f32_16x16x32_bf16 v[4:7], v[192:195], v[232:235], v[4:7]
	v_mfma_f32_16x16x32_bf16 v[0:3], v[200:203], v[232:235], v[0:3]
	s_barrier
	s_add_i32 s45, 0, 0x18000
	s_add_i32 s50, 0, 0x1c000
	ds_read_b128 v[128:131], v168
	ds_read_b128 v[132:135], v168 offset:1024
	ds_read_b128 v[136:139], v168 offset:2048
	ds_read_b128 v[184:187], v168 offset:3072
	ds_read_b128 v[188:191], v169
	ds_read_b128 v[192:195], v169 offset:1024
	ds_read_b128 v[196:199], v169 offset:2048
	ds_read_b128 v[200:203], v169 offset:3072
	s_add_u32 s48, s48, 0x80000
	s_addc_u32 s49, s49, 0
	s_mov_b32 m0, s54
	ds_read_b128 v[204:207], v182 offset:32768
	ds_read_b128 v[208:211], v182 offset:33792
	ds_read_b128 v[212:215], v182 offset:34816
	ds_read_b128 v[216:219], v182 offset:35840
	ds_read_b128 v[220:223], v182 offset:36864
	ds_read_b128 v[224:227], v182 offset:37888
	ds_read_b128 v[228:231], v182 offset:38912
	ds_read_b128 v[232:235], v182 offset:39936
	global_load_lds_dwordx4 v142, s[48:49]
	s_mov_b32 m0, s55
	s_nop 0
	global_load_lds_dwordx4 v146, s[48:49]
	s_waitcnt vmcnt(8) lgkmcnt(0)
	s_barrier
; #define PG8_STAGE(bufoff, gbase, voff) do { _Pragma("unroll") for (int _i = 0; _i < 2; ++_i) \
;         __builtin_amdgcn_global_load_lds((const unsigned*)((const char*)(gbase) + (voff)[_i]), (LAS unsigned*)(lds + (bufoff) + ldsw + _i * 8192), 16, 0, 0); } while (0)
; #define PG8_LDA(dst, b, h) do { _Pragma("unroll") for (int m = 0; m < 4; ++m) _Pragma("unroll") for (int k = 0; k < 2; ++k) dst[m][k] = *(const LAS bf16x8*)(lds + PG8_SA(b, h) + aoff + m * 2048 + k * 1024); } while (0)
; #define PG8_MMA(ai, bj, At, Bt) do { __builtin_amdgcn_s_setprio(1); _Pragma("unroll") for (int m = 0; m < 4; ++m) _Pragma("unroll") for (int n = 0; n < 2; ++n) _Pragma("unroll") for (int k = 0; k < 2; ++k) \
;         acc[ai][bj][m][n] = __builtin_amdgcn_mfma_f32_16x16x32_bf16(Bt[n][k], At[m][k], acc[ai][bj][m][n], 0, 0, 0); __builtin_amdgcn_s_setprio(0); } while (0)
; #define PG8_WAIT_V(n) asm volatile("s_waitcnt vmcnt(" #n ")" ::: "memory")
; #define PG8_WAIT_L(n) asm volatile("s_waitcnt lgkmcnt(" #n ")" ::: "memory")
; #define PG8_BAR __builtin_amdgcn_s_barrier()
; #define PG8_SCHED __builtin_amdgcn_sched_barrier(0)
; __device__ __forceinline__ void gemm_phase(LAS unsigned char* lds, const Params& p, const bf16_t* gA, const bf16_t* gBt, const int gM, const int gN, const int gK, const int epi, const int perm, bf16_t* const Hp, const int goff, const float coef) {
;     ...
;             PG8_WAIT_V(8); PG8_WAIT_L(0); PG8_BAR; PG8_MMA(0, 0, At, B0); PG8_MMA(0, 1, At, B1); PG8_BAR; PG8_SCHED;
;             PG8_LDA(At, 1, 1); PG8_STAGE(PG8_SB(1, 0), b3, voffB); PG8_STAGE(PG8_SB(1, 1), b3 + hstep, voffB); PG8_STAGE(PG8_SA(1, 0), a3, voffA);
;             PG8_WAIT_V(8); PG8_WAIT_L(0); PG8_BAR; PG8_MMA(1, 0, At, B0); PG8_MMA(1, 1, At, B1); PG8_BAR; PG8_SCHED;
;         }
	v_mfma_f32_16x16x32_bf16 v[124:127], v[128:131], v[204:207], v[124:127]
	v_mfma_f32_16x16x32_bf16 v[120:123], v[136:139], v[204:207], v[120:123]
	v_mfma_f32_16x16x32_bf16 v[108:111], v[128:131], v[212:215], v[108:111]
	v_mfma_f32_16x16x32_bf16 v[104:107], v[136:139], v[212:215], v[104:107]
	v_mfma_f32_16x16x32_bf16 v[92:95], v[128:131], v[220:223], v[92:95]
	v_mfma_f32_16x16x32_bf16 v[88:91], v[136:139], v[220:223], v[88:91]
	v_mfma_f32_16x16x32_bf16 v[76:79], v[128:131], v[228:231], v[76:79]
	v_mfma_f32_16x16x32_bf16 v[72:75], v[136:139], v[228:231], v[72:75]
	v_mfma_f32_16x16x32_bf16 v[124:127], v[132:135], v[208:211], v[124:127]
	v_mfma_f32_16x16x32_bf16 v[120:123], v[184:187], v[208:211], v[120:123]
	v_mfma_f32_16x16x32_bf16 v[108:111], v[132:135], v[216:219], v[108:111]
	v_mfma_f32_16x16x32_bf16 v[104:107], v[184:187], v[216:219], v[104:107]
	v_mfma_f32_16x16x32_bf16 v[92:95], v[132:135], v[224:227], v[92:95]
	v_mfma_f32_16x16x32_bf16 v[88:91], v[184:187], v[224:227], v[88:91]
	v_mfma_f32_16x16x32_bf16 v[76:79], v[132:135], v[232:235], v[76:79]
	v_mfma_f32_16x16x32_bf16 v[72:75], v[184:187], v[232:235], v[72:75]
	v_mfma_f32_16x16x32_bf16 v[116:119], v[188:191], v[204:207], v[116:119]
	v_mfma_f32_16x16x32_bf16 v[112:115], v[196:199], v[204:207], v[112:115]
	v_mfma_f32_16x16x32_bf16 v[100:103], v[188:191], v[212:215], v[100:103]
	v_mfma_f32_16x16x32_bf16 v[96:99], v[196:199], v[212:215], v[96:99]
	v_mfma_f32_16x16x32_bf16 v[84:87], v[188:191], v[220:223], v[84:87]
	v_mfma_f32_16x16x32_bf16 v[80:83], v[196:199], v[220:223], v[80:83]
	v_mfma_f32_16x16x32_bf16 v[68:71], v[188:191], v[228:231], v[68:71]
	v_mfma_f32_16x16x32_bf16 v[64:67], v[196:199], v[228:231], v[64:67]
	v_mfma_f32_16x16x32_bf16 v[116:119], v[192:195], v[208:211], v[116:119]
	v_mfma_f32_16x16x32_bf16 v[112:115], v[200:203], v[208:211], v[112:115]
	v_mfma_f32_16x16x32_bf16 v[100:103], v[192:195], v[216:219], v[100:103]
	v_mfma_f32_16x16x32_bf16 v[96:99], v[200:203], v[216:219], v[96:99]
	v_mfma_f32_16x16x32_bf16 v[84:87], v[192:195], v[224:227], v[84:87]
	v_mfma_f32_16x16x32_bf16 v[80:83], v[200:203], v[224:227], v[80:83]
	v_mfma_f32_16x16x32_bf16 v[68:71], v[192:195], v[232:235], v[68:71]
	v_mfma_f32_16x16x32_bf16 v[64:67], v[200:203], v[232:235], v[64:67]
	s_barrier
	s_add_i32 s45, s45, s52
	s_mov_b32 m0, s45
	ds_read_b128 v[204:207], v182 offset:49152
	ds_read_b128 v[208:211], v182 offset:50176
	ds_read_b128 v[212:215], v182 offset:51200
	ds_read_b128 v[216:219], v182 offset:52224
	ds_read_b128 v[220:223], v182 offset:53248
	ds_read_b128 v[224:227], v182 offset:54272
	ds_read_b128 v[228:231], v182 offset:55296
	ds_read_b128 v[232:235], v182 offset:56320
	s_add_u32 s98, s4, 0x80
	s_addc_u32 s99, s5, 0
	global_load_lds_dwordx4 v144, s[98:99]
	s_add_i32 m0, s45, 0x2000
	s_add_u32 s4, s4, 0x80080
	s_addc_u32 s5, s5, 0
	s_add_i32 s45, s50, s52
	global_load_lds_dwordx4 v148, s[98:99]
	s_mov_b32 m0, s45
	s_nop 0
	global_load_lds_dwordx4 v144, s[4:5]
	s_add_i32 m0, s45, 0x2000
	s_nop 0
	global_load_lds_dwordx4 v148, s[4:5]
	s_mov_b32 m0, s57
	s_add_u32 s100, s48, 0xfff80080
	s_addc_u32 s101, s49, -1
	global_load_lds_dwordx4 v142, s[100:101]
	s_mov_b32 m0, s58
	s_nop 0
	global_load_lds_dwordx4 v146, s[100:101]
	s_waitcnt vmcnt(8) lgkmcnt(0)
	s_barrier
	v_mfma_f32_16x16x32_bf16 v[60:63], v[128:131], v[204:207], v[60:63]
	v_mfma_f32_16x16x32_bf16 v[56:59], v[136:139], v[204:207], v[56:59]
	v_mfma_f32_16x16x32_bf16 v[44:47], v[128:131], v[212:215], v[44:47]
	v_mfma_f32_16x16x32_bf16 v[40:43], v[136:139], v[212:215], v[40:43]
	v_mfma_f32_16x16x32_bf16 v[28:31], v[128:131], v[220:223], v[28:31]
	v_mfma_f32_16x16x32_bf16 v[24:27], v[136:139], v[220:223], v[24:27]
	v_mfma_f32_16x16x32_bf16 v[12:15], v[128:131], v[228:231], v[12:15]
	v_mfma_f32_16x16x32_bf16 v[8:11], v[136:139], v[228:231], v[8:11]
	v_mfma_f32_16x16x32_bf16 v[60:63], v[132:135], v[208:211], v[60:63]
	v_mfma_f32_16x16x32_bf16 v[56:59], v[184:187], v[208:211], v[56:59]
	v_mfma_f32_16x16x32_bf16 v[44:47], v[132:135], v[216:219], v[44:47]
	v_mfma_f32_16x16x32_bf16 v[40:43], v[184:187], v[216:219], v[40:43]
	v_mfma_f32_16x16x32_bf16 v[28:31], v[132:135], v[224:227], v[28:31]
	v_mfma_f32_16x16x32_bf16 v[24:27], v[184:187], v[224:227], v[24:27]
	v_mfma_f32_16x16x32_bf16 v[12:15], v[132:135], v[232:235], v[12:15]
	v_mfma_f32_16x16x32_bf16 v[8:11], v[184:187], v[232:235], v[8:11]
	v_mfma_f32_16x16x32_bf16 v[52:55], v[188:191], v[204:207], v[52:55]
	v_mfma_f32_16x16x32_bf16 v[48:51], v[196:199], v[204:207], v[48:51]
	v_mfma_f32_16x16x32_bf16 v[36:39], v[188:191], v[212:215], v[36:39]
	v_mfma_f32_16x16x32_bf16 v[32:35], v[196:199], v[212:215], v[32:35]
	v_mfma_f32_16x16x32_bf16 v[20:23], v[188:191], v[220:223], v[20:23]
	v_mfma_f32_16x16x32_bf16 v[16:19], v[196:199], v[220:223], v[16:19]
	v_mfma_f32_16x16x32_bf16 v[4:7], v[188:191], v[228:231], v[4:7]
	v_mfma_f32_16x16x32_bf16 v[0:3], v[196:199], v[228:231], v[0:3]
	v_mfma_f32_16x16x32_bf16 v[52:55], v[192:195], v[208:211], v[52:55]
	v_mfma_f32_16x16x32_bf16 v[48:51], v[200:203], v[208:211], v[48:51]
	v_mfma_f32_16x16x32_bf16 v[36:39], v[192:195], v[216:219], v[36:39]
	v_mfma_f32_16x16x32_bf16 v[32:35], v[200:203], v[216:219], v[32:35]
	v_mfma_f32_16x16x32_bf16 v[20:23], v[192:195], v[224:227], v[20:23]
	v_mfma_f32_16x16x32_bf16 v[16:19], v[200:203], v[224:227], v[16:19]
	v_mfma_f32_16x16x32_bf16 v[4:7], v[192:195], v[232:235], v[4:7]
	v_mfma_f32_16x16x32_bf16 v[0:3], v[200:203], v[232:235], v[0:3]
	s_barrier
	s_add_u32 s0, s0, 0x100
	s_addc_u32 s1, s1, 0
	s_add_u32 s33, s33, 0x100
	s_addc_u32 s35, s35, 0
	s_cmp_ge_u32 s37, s22
	s_mov_b32 s45, s37
	s_cbranch_scc0 .LBB0_436

; #define PG8_STAGE(bufoff, gbase, voff) do { _Pragma("unroll") for (int _i = 0; _i < 2; ++_i) \
;         __builtin_amdgcn_global_load_lds((const unsigned*)((const char*)(gbase) + (voff)[_i]), (LAS unsigned*)(lds + (bufoff) + ldsw + _i * 8192), 16, 0, 0); } while (0)
; #define PG8_LDA(dst, b, h) do { _Pragma("unroll") for (int m = 0; m < 4; ++m) _Pragma("unroll") for (int k = 0; k < 2; ++k) dst[m][k] = *(const LAS bf16x8*)(lds + PG8_SA(b, h) + aoff + m * 2048 + k * 1024); } while (0)
; #define PG8_WAIT_V(n) asm volatile("s_waitcnt vmcnt(" #n ")" ::: "memory")
; #define PG8_WAIT_L(n) asm volatile("s_waitcnt lgkmcnt(" #n ")" ::: "memory")
; #define PG8_BAR __builtin_amdgcn_s_barrier()
; __device__ __forceinline__ void gemm_phase(LAS unsigned char* lds, const Params& p, const bf16_t* gA, const bf16_t* gBt, const int gM, const int gN, const int gK, const int epi, const int perm, bf16_t* const Hp, const int goff, const float coef) {
;     ...
;         const bool has_next = S.next(ui + 1, nxt);
;         const char* nA = has_next ? (const char*)gA + (size_t)nxt.pm * tstep + (nxt.ks > 0 ? nxt.ks * ksl : 0) : cA; const char* nB = has_next ? (const char*)gBt + (size_t)nxt.pn * tstep + (nxt.ks > 0 ? nxt.ks * ksl : 0) : cB;
;         const int nt = cur.ks >= 0 ? ntf / 4 : ntf;
;         for (int t = 0; t < nt; t += 2) {
;             const bool last = (t == nt - 2);
;             const char* a1 = cA + (size_t)(t + 1) * kstep;
;             const char* a2 = last ? nA : cA + (size_t)(t + 2) * kstep; const char* b2 = last ? nB : cB + (size_t)(t + 2) * kstep;
;             const char* a3 = a2 + kstep; const char* b3 = b2 + kstep;
;             PG8_LDB(B0, 0, 0); PG8_LDB(B1, 0, 1); PG8_SCHED; PG8_LDA(At, 0, 0); PG8_STAGE(PG8_SA(1, 1), a1 + hstep, voffA);
;             PG8_WAIT_V(8); PG8_WAIT_L(0); PG8_BAR; PG8_MMA(0, 0, At, B0); PG8_MMA(0, 1, At, B1); PG8_BAR; PG8_SCHED;
;             PG8_LDA(At, 0, 1); PG8_STAGE(PG8_SB(0, 0), b2, voffB); PG8_STAGE(PG8_SB(0, 1), b2 + hstep, voffB); PG8_STAGE(PG8_SA(0, 0), a2, voffA);
;             PG8_WAIT_V(8); PG8_WAIT_L(0); PG8_BAR; PG8_MMA(1, 0, At, B0); PG8_MMA(1, 1, At, B1); PG8_BAR; PG8_SCHED;
;             PG8_LDB(B0, 1, 0); PG8_LDB(B1, 1, 1); PG8_SCHED; PG8_LDA(At, 1, 0); PG8_STAGE(PG8_SA(0, 1), a2 + hstep, voffA);
;             PG8_WAIT_V(8); PG8_WAIT_L(0); PG8_BAR; PG8_MMA(0, 0, At, B0); PG8_MMA(0, 1, At, B1); PG8_BAR; PG8_SCHED;
.LBB0_1592:
	s_ashr_i32 s13, s12, 31
	s_lshl_b64 s[0:1], s[12:13], 20
	s_add_u32 s13, s3, s0
	s_mov_b32 s19, s5
	s_addc_u32 s15, s33, s1
	s_lshl_b64 s[0:1], s[18:19], 10
	s_cmp_gt_i32 s18, 0
	s_cselect_b32 s22, s0, 0
	s_cselect_b32 s23, s1, 0
	s_add_u32 s20, s13, s22
	s_addc_u32 s21, s15, s23
	s_and_b64 s[0:1], s[16:17], exec
	s_cselect_b32 s13, s21, s27
	s_cselect_b32 s19, s20, s26
	s_ashr_i32 s15, s14, 31
	s_lshl_b64 s[0:1], s[14:15], 20
	s_add_u32 s0, s34, s0
	s_addc_u32 s1, s35, s1
	s_add_u32 s22, s0, s22
	s_addc_u32 s23, s1, s23
	s_and_b64 s[0:1], s[16:17], exec
	s_cselect_b32 s15, s23, s29
	s_cselect_b32 s25, s22, s28
	s_cmp_gt_i32 s4, -1
	s_cselect_b64 s[0:1], -1, 0
	s_and_b64 s[52:53], s[0:1], exec
	s_cselect_b32 s52, 8, 32
	s_add_i32 s53, s52, -2
	s_add_u32 s26, s26, 0x80080
	s_addc_u32 s27, s27, 0
	s_add_u32 s54, s28, 0x100
	s_mov_b32 s30, 0
	s_addc_u32 s55, s29, 0
	v_add_u32_e32 v222, 0x18000, v165
	v_add_u32_e32 v223, 0x1c000, v165
	ds_read_b128 v[128:131], v174
	ds_read_b128 v[132:135], v174 offset:1024
	ds_read_b128 v[152:155], v174 offset:2048
	ds_read_b128 v[156:159], v174 offset:3072
	ds_read_b128 v[160:163], v175
	ds_read_b128 v[178:181], v175 offset:1024
	ds_read_b128 v[182:185], v175 offset:2048
	ds_read_b128 v[186:189], v175 offset:3072
	s_add_i32 s56, s30, 2
	s_add_u32 s28, s26, 0xfff80080
	s_addc_u32 s29, s27, -1
	s_cmp_eq_u32 s53, s30
	s_cselect_b32 s30, s19, s28
	s_cselect_b32 s31, s13, s29
	s_cselect_b32 s29, s15, s55
	s_cselect_b32 s28, s25, s54
	s_add_i32 m0, s37, 0xc000
	ds_read_b128 v[190:193], v176
	ds_read_b128 v[194:197], v176 offset:1024
	ds_read_b128 v[198:201], v176 offset:2048
	ds_read_b128 v[202:205], v176 offset:3072
	ds_read_b128 v[206:209], v176 offset:4096
	ds_read_b128 v[210:213], v176 offset:5120
	ds_read_b128 v[214:217], v176 offset:6144
	ds_read_b128 v[218:221], v176 offset:7168
	global_load_lds_dwordx4 v146, s[26:27]
	s_add_i32 m0, s37, 0xe000
	s_nop 0
	global_load_lds_dwordx4 v148, s[26:27]
	s_waitcnt vmcnt(8) lgkmcnt(0)
	s_barrier
	v_mfma_f32_16x16x32_bf16 v[124:127], v[128:131], v[190:193], 0
	v_mfma_f32_16x16x32_bf16 v[120:123], v[152:155], v[190:193], 0
	v_mfma_f32_16x16x32_bf16 v[116:119], v[128:131], v[198:201], 0
	v_mfma_f32_16x16x32_bf16 v[112:115], v[152:155], v[198:201], 0
	v_mfma_f32_16x16x32_bf16 v[108:111], v[128:131], v[206:209], 0
	v_mfma_f32_16x16x32_bf16 v[104:107], v[152:155], v[206:209], 0
	v_mfma_f32_16x16x32_bf16 v[100:103], v[128:131], v[214:217], 0
	v_mfma_f32_16x16x32_bf16 v[96:99], v[152:155], v[214:217], 0
	v_mfma_f32_16x16x32_bf16 v[124:127], v[132:135], v[194:197], v[124:127]
	v_mfma_f32_16x16x32_bf16 v[120:123], v[156:159], v[194:197], v[120:123]
	v_mfma_f32_16x16x32_bf16 v[116:119], v[132:135], v[202:205], v[116:119]
	v_mfma_f32_16x16x32_bf16 v[112:115], v[156:159], v[202:205], v[112:115]
	v_mfma_f32_16x16x32_bf16 v[108:111], v[132:135], v[210:213], v[108:111]
	v_mfma_f32_16x16x32_bf16 v[104:107], v[156:159], v[210:213], v[104:107]
	v_mfma_f32_16x16x32_bf16 v[100:103], v[132:135], v[218:221], v[100:103]
	v_mfma_f32_16x16x32_bf16 v[96:99], v[156:159], v[218:221], v[96:99]
	v_mfma_f32_16x16x32_bf16 v[68:71], v[160:163], v[190:193], 0
	v_mfma_f32_16x16x32_bf16 v[64:67], v[182:185], v[190:193], 0
	v_mfma_f32_16x16x32_bf16 v[52:55], v[160:163], v[198:201], 0
	v_mfma_f32_16x16x32_bf16 v[48:51], v[182:185], v[198:201], 0
	v_mfma_f32_16x16x32_bf16 v[44:47], v[160:163], v[206:209], 0
	v_mfma_f32_16x16x32_bf16 v[40:43], v[182:185], v[206:209], 0
	v_mfma_f32_16x16x32_bf16 v[36:39], v[160:163], v[214:217], 0
	v_mfma_f32_16x16x32_bf16 v[32:35], v[182:185], v[214:217], 0
	v_mfma_f32_16x16x32_bf16 v[68:71], v[178:181], v[194:197], v[68:71]
	v_mfma_f32_16x16x32_bf16 v[64:67], v[186:189], v[194:197], v[64:67]
	v_mfma_f32_16x16x32_bf16 v[52:55], v[178:181], v[202:205], v[52:55]
	v_mfma_f32_16x16x32_bf16 v[48:51], v[186:189], v[202:205], v[48:51]
	v_mfma_f32_16x16x32_bf16 v[44:47], v[178:181], v[210:213], v[44:47]
	v_mfma_f32_16x16x32_bf16 v[40:43], v[186:189], v[210:213], v[40:43]
	v_mfma_f32_16x16x32_bf16 v[36:39], v[178:181], v[218:221], v[36:39]
	v_mfma_f32_16x16x32_bf16 v[32:35], v[186:189], v[218:221], v[32:35]
	s_barrier
	s_add_i32 s57, s48, s36
	s_mov_b32 m0, s57
	ds_read_b128 v[190:193], v176 offset:16384
	ds_read_b128 v[194:197], v176 offset:17408
	ds_read_b128 v[198:201], v176 offset:18432
	ds_read_b128 v[202:205], v176 offset:19456
	ds_read_b128 v[206:209], v176 offset:20480
	ds_read_b128 v[210:213], v176 offset:21504
	ds_read_b128 v[214:217], v176 offset:22528
	ds_read_b128 v[218:221], v176 offset:23552
	global_load_lds_dwordx4 v138, s[28:29]
	s_add_i32 m0, s57, 0x2000
	s_add_u32 s58, s28, 0x80000
	s_addc_u32 s59, s29, 0
	s_add_i32 s57, s49, s36
	global_load_lds_dwordx4 v144, s[28:29]
	s_mov_b32 m0, s57
	s_nop 0
	global_load_lds_dwordx4 v138, s[58:59]
	s_add_i32 m0, s57, 0x2000
	s_nop 0
	global_load_lds_dwordx4 v144, s[58:59]
	s_mov_b32 m0, s37
	s_nop 0
	global_load_lds_dwordx4 v136, s[30:31]
	s_mov_b32 m0, s38
	s_nop 0
	global_load_lds_dwordx4 v142, s[30:31]
	s_waitcnt vmcnt(8) lgkmcnt(0)
	s_barrier
; #define PG8_STAGE(bufoff, gbase, voff) do { _Pragma("unroll") for (int _i = 0; _i < 2; ++_i) \
;         __builtin_amdgcn_global_load_lds((const unsigned*)((const char*)(gbase) + (voff)[_i]), (LAS unsigned*)(lds + (bufoff) + ldsw + _i * 8192), 16, 0, 0); } while (0)
; #define PG8_LDA(dst, b, h) do { _Pragma("unroll") for (int m = 0; m < 4; ++m) _Pragma("unroll") for (int k = 0; k < 2; ++k) dst[m][k] = *(const LAS bf16x8*)(lds + PG8_SA(b, h) + aoff + m * 2048 + k * 1024); } while (0)
; #define PG8_LDB(dst, b, h) do { _Pragma("unroll") for (int n = 0; n < 2; ++n) _Pragma("unroll") for (int k = 0; k < 2; ++k) dst[n][k] = *(const LAS bf16x8*)(lds + PG8_SB(b, h) + boff + n * 2048 + k * 1024); } while (0)
; #define PG8_MMA(ai, bj, At, Bt) do { __builtin_amdgcn_s_setprio(1); _Pragma("unroll") for (int m = 0; m < 4; ++m) _Pragma("unroll") for (int n = 0; n < 2; ++n) _Pragma("unroll") for (int k = 0; k < 2; ++k) \
;         acc[ai][bj][m][n] = __builtin_amdgcn_mfma_f32_16x16x32_bf16(Bt[n][k], At[m][k], acc[ai][bj][m][n], 0, 0, 0); __builtin_amdgcn_s_setprio(0); } while (0)
; #define PG8_WAIT_V(n) asm volatile("s_waitcnt vmcnt(" #n ")" ::: "memory")
; #define PG8_WAIT_L(n) asm volatile("s_waitcnt lgkmcnt(" #n ")" ::: "memory")
; #define PG8_BAR __builtin_amdgcn_s_barrier()
; #define PG8_SCHED __builtin_amdgcn_sched_barrier(0)
; __device__ __forceinline__ void gemm_phase(LAS unsigned char* lds, const Params& p, const bf16_t* gA, const bf16_t* gBt, const int gM, const int gN, const int gK, const int epi, const int perm, bf16_t* const Hp, const int goff, const float coef) {
;     ...
;             PG8_WAIT_V(8); PG8_WAIT_L(0); PG8_BAR; PG8_MMA(1, 0, At, B0); PG8_MMA(1, 1, At, B1); PG8_BAR; PG8_SCHED;
;             PG8_LDB(B0, 1, 0); PG8_LDB(B1, 1, 1); PG8_SCHED; PG8_LDA(At, 1, 0); PG8_STAGE(PG8_SA(0, 1), a2 + hstep, voffA);
;             PG8_WAIT_V(8); PG8_WAIT_L(0); PG8_BAR; PG8_MMA(0, 0, At, B0); PG8_MMA(0, 1, At, B1); PG8_BAR; PG8_SCHED;
;             PG8_LDA(At, 1, 1); PG8_STAGE(PG8_SB(1, 0), b3, voffB); PG8_STAGE(PG8_SB(1, 1), b3 + hstep, voffB); PG8_STAGE(PG8_SA(1, 0), a3, voffA);
;             PG8_WAIT_V(8); PG8_WAIT_L(0); PG8_BAR; PG8_MMA(1, 0, At, B0); PG8_MMA(1, 1, At, B1); PG8_BAR; PG8_SCHED;
	v_mfma_f32_16x16x32_bf16 v[92:95], v[128:131], v[190:193], 0
	v_mfma_f32_16x16x32_bf16 v[88:91], v[152:155], v[190:193], 0
	v_mfma_f32_16x16x32_bf16 v[84:87], v[128:131], v[198:201], 0
	v_mfma_f32_16x16x32_bf16 v[80:83], v[152:155], v[198:201], 0
	v_mfma_f32_16x16x32_bf16 v[76:79], v[128:131], v[206:209], 0
	v_mfma_f32_16x16x32_bf16 v[72:75], v[152:155], v[206:209], 0
	v_mfma_f32_16x16x32_bf16 v[60:63], v[128:131], v[214:217], 0
	v_mfma_f32_16x16x32_bf16 v[56:59], v[152:155], v[214:217], 0
	v_mfma_f32_16x16x32_bf16 v[92:95], v[132:135], v[194:197], v[92:95]
	v_mfma_f32_16x16x32_bf16 v[88:91], v[156:159], v[194:197], v[88:91]
	v_mfma_f32_16x16x32_bf16 v[84:87], v[132:135], v[202:205], v[84:87]
	v_mfma_f32_16x16x32_bf16 v[80:83], v[156:159], v[202:205], v[80:83]
	v_mfma_f32_16x16x32_bf16 v[76:79], v[132:135], v[210:213], v[76:79]
	v_mfma_f32_16x16x32_bf16 v[72:75], v[156:159], v[210:213], v[72:75]
	v_mfma_f32_16x16x32_bf16 v[60:63], v[132:135], v[218:221], v[60:63]
	v_mfma_f32_16x16x32_bf16 v[56:59], v[156:159], v[218:221], v[56:59]
	v_mfma_f32_16x16x32_bf16 v[28:31], v[160:163], v[190:193], 0
	v_mfma_f32_16x16x32_bf16 v[24:27], v[182:185], v[190:193], 0
	v_mfma_f32_16x16x32_bf16 v[20:23], v[160:163], v[198:201], 0
	v_mfma_f32_16x16x32_bf16 v[16:19], v[182:185], v[198:201], 0
	v_mfma_f32_16x16x32_bf16 v[12:15], v[160:163], v[206:209], 0
	v_mfma_f32_16x16x32_bf16 v[8:11], v[182:185], v[206:209], 0
	v_mfma_f32_16x16x32_bf16 v[4:7], v[160:163], v[214:217], 0
	v_mfma_f32_16x16x32_bf16 v[0:3], v[182:185], v[214:217], 0
	v_mfma_f32_16x16x32_bf16 v[28:31], v[178:181], v[194:197], v[28:31]
	v_mfma_f32_16x16x32_bf16 v[24:27], v[186:189], v[194:197], v[24:27]
	v_mfma_f32_16x16x32_bf16 v[20:23], v[178:181], v[202:205], v[20:23]
	v_mfma_f32_16x16x32_bf16 v[16:19], v[186:189], v[202:205], v[16:19]
	v_mfma_f32_16x16x32_bf16 v[12:15], v[178:181], v[210:213], v[12:15]
	v_mfma_f32_16x16x32_bf16 v[8:11], v[186:189], v[210:213], v[8:11]
	v_mfma_f32_16x16x32_bf16 v[4:7], v[178:181], v[218:221], v[4:7]
	v_mfma_f32_16x16x32_bf16 v[0:3], v[186:189], v[218:221], v[0:3]
	s_barrier
	s_add_i32 s57, 0, 0x18000
	s_add_i32 s58, 0, 0x1c000
	ds_read_b128 v[128:131], v222
	ds_read_b128 v[132:135], v222 offset:1024
	ds_read_b128 v[152:155], v222 offset:2048
	ds_read_b128 v[156:159], v222 offset:3072
	ds_read_b128 v[160:163], v223
	ds_read_b128 v[178:181], v223 offset:1024
	ds_read_b128 v[182:185], v223 offset:2048
	ds_read_b128 v[186:189], v223 offset:3072
	s_add_u32 s30, s30, 0x80000
	s_addc_u32 s31, s31, 0
	s_mov_b32 m0, s39
	ds_read_b128 v[190:193], v176 offset:32768
	ds_read_b128 v[194:197], v176 offset:33792
	ds_read_b128 v[198:201], v176 offset:34816
	ds_read_b128 v[202:205], v176 offset:35840
	ds_read_b128 v[206:209], v176 offset:36864
	ds_read_b128 v[210:213], v176 offset:37888
	ds_read_b128 v[214:217], v176 offset:38912
	ds_read_b128 v[218:221], v176 offset:39936
	global_load_lds_dwordx4 v136, s[30:31]
	s_mov_b32 m0, s40
	s_nop 0
	global_load_lds_dwordx4 v142, s[30:31]
	s_waitcnt vmcnt(8) lgkmcnt(0)
	s_barrier
	v_mfma_f32_16x16x32_bf16 v[124:127], v[128:131], v[190:193], v[124:127]
	v_mfma_f32_16x16x32_bf16 v[120:123], v[152:155], v[190:193], v[120:123]
	v_mfma_f32_16x16x32_bf16 v[116:119], v[128:131], v[198:201], v[116:119]
	v_mfma_f32_16x16x32_bf16 v[112:115], v[152:155], v[198:201], v[112:115]
	v_mfma_f32_16x16x32_bf16 v[108:111], v[128:131], v[206:209], v[108:111]
	v_mfma_f32_16x16x32_bf16 v[104:107], v[152:155], v[206:209], v[104:107]
	v_mfma_f32_16x16x32_bf16 v[100:103], v[128:131], v[214:217], v[100:103]
	v_mfma_f32_16x16x32_bf16 v[96:99], v[152:155], v[214:217], v[96:99]
	v_mfma_f32_16x16x32_bf16 v[124:127], v[132:135], v[194:197], v[124:127]
	v_mfma_f32_16x16x32_bf16 v[120:123], v[156:159], v[194:197], v[120:123]
	v_mfma_f32_16x16x32_bf16 v[116:119], v[132:135], v[202:205], v[116:119]
	v_mfma_f32_16x16x32_bf16 v[112:115], v[156:159], v[202:205], v[112:115]
	v_mfma_f32_16x16x32_bf16 v[108:111], v[132:135], v[210:213], v[108:111]
	v_mfma_f32_16x16x32_bf16 v[104:107], v[156:159], v[210:213], v[104:107]
	v_mfma_f32_16x16x32_bf16 v[100:103], v[132:135], v[218:221], v[100:103]
	v_mfma_f32_16x16x32_bf16 v[96:99], v[156:159], v[218:221], v[96:99]
	v_mfma_f32_16x16x32_bf16 v[68:71], v[160:163], v[190:193], v[68:71]
	v_mfma_f32_16x16x32_bf16 v[64:67], v[182:185], v[190:193], v[64:67]
	v_mfma_f32_16x16x32_bf16 v[52:55], v[160:163], v[198:201], v[52:55]
	v_mfma_f32_16x16x32_bf16 v[48:51], v[182:185], v[198:201], v[48:51]
	v_mfma_f32_16x16x32_bf16 v[44:47], v[160:163], v[206:209], v[44:47]
	v_mfma_f32_16x16x32_bf16 v[40:43], v[182:185], v[206:209], v[40:43]
	v_mfma_f32_16x16x32_bf16 v[36:39], v[160:163], v[214:217], v[36:39]
	v_mfma_f32_16x16x32_bf16 v[32:35], v[182:185], v[214:217], v[32:35]
	v_mfma_f32_16x16x32_bf16 v[68:71], v[178:181], v[194:197], v[68:71]
	v_mfma_f32_16x16x32_bf16 v[64:67], v[186:189], v[194:197], v[64:67]
	v_mfma_f32_16x16x32_bf16 v[52:55], v[178:181], v[202:205], v[52:55]
	v_mfma_f32_16x16x32_bf16 v[48:51], v[186:189], v[202:205], v[48:51]
	v_mfma_f32_16x16x32_bf16 v[44:47], v[178:181], v[210:213], v[44:47]
	v_mfma_f32_16x16x32_bf16 v[40:43], v[186:189], v[210:213], v[40:43]
	v_mfma_f32_16x16x32_bf16 v[36:39], v[178:181], v[218:221], v[36:39]
	v_mfma_f32_16x16x32_bf16 v[32:35], v[186:189], v[218:221], v[32:35]
	s_barrier
; #define PG8_STAGE(bufoff, gbase, voff) do { _Pragma("unroll") for (int _i = 0; _i < 2; ++_i) \
;         __builtin_amdgcn_global_load_lds((const unsigned*)((const char*)(gbase) + (voff)[_i]), (LAS unsigned*)(lds + (bufoff) + ldsw + _i * 8192), 16, 0, 0); } while (0)
; #define PG8_LDA(dst, b, h) do { _Pragma("unroll") for (int m = 0; m < 4; ++m) _Pragma("unroll") for (int k = 0; k < 2; ++k) dst[m][k] = *(const LAS bf16x8*)(lds + PG8_SA(b, h) + aoff + m * 2048 + k * 1024); } while (0)
; #define PG8_LDB(dst, b, h) do { _Pragma("unroll") for (int n = 0; n < 2; ++n) _Pragma("unroll") for (int k = 0; k < 2; ++k) dst[n][k] = *(const LAS bf16x8*)(lds + PG8_SB(b, h) + boff + n * 2048 + k * 1024); } while (0)
; #define PG8_MMA(ai, bj, At, Bt) do { __builtin_amdgcn_s_setprio(1); _Pragma("unroll") for (int m = 0; m < 4; ++m) _Pragma("unroll") for (int n = 0; n < 2; ++n) _Pragma("unroll") for (int k = 0; k < 2; ++k) \
;         acc[ai][bj][m][n] = __builtin_amdgcn_mfma_f32_16x16x32_bf16(Bt[n][k], At[m][k], acc[ai][bj][m][n], 0, 0, 0); __builtin_amdgcn_s_setprio(0); } while (0)
; #define PG8_WAIT_V(n) asm volatile("s_waitcnt vmcnt(" #n ")" ::: "memory")
; #define PG8_WAIT_L(n) asm volatile("s_waitcnt lgkmcnt(" #n ")" ::: "memory")
; #define PG8_BAR __builtin_amdgcn_s_barrier()
; #define PG8_SCHED __builtin_amdgcn_sched_barrier(0)
; __device__ __forceinline__ void gemm_phase(LAS unsigned char* lds, const Params& p, const bf16_t* gA, const bf16_t* gBt, const int gM, const int gN, const int gK, const int epi, const int perm, bf16_t* const Hp, const int goff, const float coef) {
;     ...
;             PG8_LDB(B0, 0, 0); PG8_LDB(B1, 0, 1); PG8_SCHED; PG8_LDA(At, 0, 0); PG8_STAGE(PG8_SA(1, 1), a1 + hstep, voffA);
;             PG8_WAIT_V(8); PG8_WAIT_L(0); PG8_BAR; PG8_MMA(0, 0, At, B0); PG8_MMA(0, 1, At, B1); PG8_BAR; PG8_SCHED;
;     ...
;             PG8_LDA(At, 1, 1); PG8_STAGE(PG8_SB(1, 0), b3, voffB); PG8_STAGE(PG8_SB(1, 1), b3 + hstep, voffB); PG8_STAGE(PG8_SA(1, 0), a3, voffA);
;             PG8_WAIT_V(8); PG8_WAIT_L(0); PG8_BAR; PG8_MMA(1, 0, At, B0); PG8_MMA(1, 1, At, B1); PG8_BAR; PG8_SCHED;
	s_mov_b64 s[98:99], s[30:31]
	s_add_i32 s30, s57, s36
	s_mov_b32 m0, s30
	ds_read_b128 v[190:193], v176 offset:49152
	ds_read_b128 v[194:197], v176 offset:50176
	ds_read_b128 v[198:201], v176 offset:51200
	ds_read_b128 v[202:205], v176 offset:52224
	ds_read_b128 v[206:209], v176 offset:53248
	ds_read_b128 v[210:213], v176 offset:54272
	ds_read_b128 v[214:217], v176 offset:55296
	ds_read_b128 v[218:221], v176 offset:56320
	s_add_u32 s100, s28, 0x80
	s_addc_u32 s101, s29, 0
	global_load_lds_dwordx4 v138, s[100:101]
	s_add_i32 m0, s30, 0x2000
	s_add_u32 s28, s28, 0x80080
	s_addc_u32 s29, s29, 0
	s_add_i32 s30, s58, s36
	global_load_lds_dwordx4 v144, s[100:101]
	s_mov_b32 m0, s30
	s_nop 0
	global_load_lds_dwordx4 v138, s[28:29]
	s_add_i32 m0, s30, 0x2000
	s_nop 0
	global_load_lds_dwordx4 v144, s[28:29]
	s_mov_b32 m0, s44
	s_add_u32 s100, s98, 0xfff80080
	s_addc_u32 s101, s99, -1
	global_load_lds_dwordx4 v136, s[100:101]
	s_mov_b32 m0, s45
	s_nop 0
	global_load_lds_dwordx4 v142, s[100:101]
	s_waitcnt vmcnt(8) lgkmcnt(0)
	s_barrier
	v_mfma_f32_16x16x32_bf16 v[92:95], v[128:131], v[190:193], v[92:95]
	v_mfma_f32_16x16x32_bf16 v[88:91], v[152:155], v[190:193], v[88:91]
	v_mfma_f32_16x16x32_bf16 v[84:87], v[128:131], v[198:201], v[84:87]
	v_mfma_f32_16x16x32_bf16 v[80:83], v[152:155], v[198:201], v[80:83]
	v_mfma_f32_16x16x32_bf16 v[76:79], v[128:131], v[206:209], v[76:79]
	v_mfma_f32_16x16x32_bf16 v[72:75], v[152:155], v[206:209], v[72:75]
	v_mfma_f32_16x16x32_bf16 v[60:63], v[128:131], v[214:217], v[60:63]
	v_mfma_f32_16x16x32_bf16 v[56:59], v[152:155], v[214:217], v[56:59]
	v_mfma_f32_16x16x32_bf16 v[92:95], v[132:135], v[194:197], v[92:95]
	v_mfma_f32_16x16x32_bf16 v[88:91], v[156:159], v[194:197], v[88:91]
	v_mfma_f32_16x16x32_bf16 v[84:87], v[132:135], v[202:205], v[84:87]
	v_mfma_f32_16x16x32_bf16 v[80:83], v[156:159], v[202:205], v[80:83]
	v_mfma_f32_16x16x32_bf16 v[76:79], v[132:135], v[210:213], v[76:79]
	v_mfma_f32_16x16x32_bf16 v[72:75], v[156:159], v[210:213], v[72:75]
	v_mfma_f32_16x16x32_bf16 v[60:63], v[132:135], v[218:221], v[60:63]
	v_mfma_f32_16x16x32_bf16 v[56:59], v[156:159], v[218:221], v[56:59]
	v_mfma_f32_16x16x32_bf16 v[28:31], v[160:163], v[190:193], v[28:31]
	v_mfma_f32_16x16x32_bf16 v[24:27], v[182:185], v[190:193], v[24:27]
	v_mfma_f32_16x16x32_bf16 v[20:23], v[160:163], v[198:201], v[20:23]
	v_mfma_f32_16x16x32_bf16 v[16:19], v[182:185], v[198:201], v[16:19]
	v_mfma_f32_16x16x32_bf16 v[12:15], v[160:163], v[206:209], v[12:15]
	v_mfma_f32_16x16x32_bf16 v[8:11], v[182:185], v[206:209], v[8:11]
	v_mfma_f32_16x16x32_bf16 v[4:7], v[160:163], v[214:217], v[4:7]
	v_mfma_f32_16x16x32_bf16 v[0:3], v[182:185], v[214:217], v[0:3]
	v_mfma_f32_16x16x32_bf16 v[28:31], v[178:181], v[194:197], v[28:31]
	v_mfma_f32_16x16x32_bf16 v[24:27], v[186:189], v[194:197], v[24:27]
	v_mfma_f32_16x16x32_bf16 v[20:23], v[178:181], v[202:205], v[20:23]
	v_mfma_f32_16x16x32_bf16 v[16:19], v[186:189], v[202:205], v[16:19]
	v_mfma_f32_16x16x32_bf16 v[12:15], v[178:181], v[210:213], v[12:15]
	v_mfma_f32_16x16x32_bf16 v[8:11], v[186:189], v[210:213], v[8:11]
	v_mfma_f32_16x16x32_bf16 v[4:7], v[178:181], v[218:221], v[4:7]
	v_mfma_f32_16x16x32_bf16 v[0:3], v[186:189], v[218:221], v[0:3]
	s_barrier
	s_add_u32 s26, s26, 0x100
	s_addc_u32 s27, s27, 0
	s_add_u32 s54, s54, 0x100
	s_addc_u32 s55, s55, 0
	s_cmp_ge_u32 s56, s52
	s_mov_b32 s30, s56
	s_cbranch_scc1 .Lpeel_exit_3
.LBB0_1593:
	ds_read_b128 v[128:131], v174
	ds_read_b128 v[132:135], v174 offset:1024
	ds_read_b128 v[152:155], v174 offset:2048
	ds_read_b128 v[156:159], v174 offset:3072
	ds_read_b128 v[160:163], v175
	ds_read_b128 v[178:181], v175 offset:1024
	ds_read_b128 v[182:185], v175 offset:2048
	ds_read_b128 v[186:189], v175 offset:3072
	s_add_i32 s56, s30, 2
	s_add_u32 s28, s26, 0xfff80080
	s_addc_u32 s29, s27, -1
	s_cmp_eq_u32 s53, s30
	s_cselect_b32 s30, s19, s28
	s_cselect_b32 s31, s13, s29
	s_cselect_b32 s29, s15, s55
	s_cselect_b32 s28, s25, s54
	s_add_i32 m0, s37, 0xc000
	ds_read_b128 v[190:193], v176
	ds_read_b128 v[194:197], v176 offset:1024
	ds_read_b128 v[198:201], v176 offset:2048
	ds_read_b128 v[202:205], v176 offset:3072
	ds_read_b128 v[206:209], v176 offset:4096
	ds_read_b128 v[210:213], v176 offset:5120
	ds_read_b128 v[214:217], v176 offset:6144
	ds_read_b128 v[218:221], v176 offset:7168
	global_load_lds_dwordx4 v146, s[26:27]
	s_add_i32 m0, s37, 0xe000
	s_nop 0
	global_load_lds_dwordx4 v148, s[26:27]
	s_waitcnt vmcnt(8) lgkmcnt(0)
	s_barrier
	v_mfma_f32_16x16x32_bf16 v[124:127], v[128:131], v[190:193], v[124:127]
	v_mfma_f32_16x16x32_bf16 v[120:123], v[152:155], v[190:193], v[120:123]
	v_mfma_f32_16x16x32_bf16 v[116:119], v[128:131], v[198:201], v[116:119]
	v_mfma_f32_16x16x32_bf16 v[112:115], v[152:155], v[198:201], v[112:115]
	v_mfma_f32_16x16x32_bf16 v[108:111], v[128:131], v[206:209], v[108:111]
	v_mfma_f32_16x16x32_bf16 v[104:107], v[152:155], v[206:209], v[104:107]
	v_mfma_f32_16x16x32_bf16 v[100:103], v[128:131], v[214:217], v[100:103]
	v_mfma_f32_16x16x32_bf16 v[96:99], v[152:155], v[214:217], v[96:99]
	v_mfma_f32_16x16x32_bf16 v[124:127], v[132:135], v[194:197], v[124:127]
	v_mfma_f32_16x16x32_bf16 v[120:123], v[156:159], v[194:197], v[120:123]
	v_mfma_f32_16x16x32_bf16 v[116:119], v[132:135], v[202:205], v[116:119]
	v_mfma_f32_16x16x32_bf16 v[112:115], v[156:159], v[202:205], v[112:115]
	v_mfma_f32_16x16x32_bf16 v[108:111], v[132:135], v[210:213], v[108:111]
	v_mfma_f32_16x16x32_bf16 v[104:107], v[156:159], v[210:213], v[104:107]
	v_mfma_f32_16x16x32_bf16 v[100:103], v[132:135], v[218:221], v[100:103]
	v_mfma_f32_16x16x32_bf16 v[96:99], v[156:159], v[218:221], v[96:99]
	v_mfma_f32_16x16x32_bf16 v[68:71], v[160:163], v[190:193], v[68:71]
	v_mfma_f32_16x16x32_bf16 v[64:67], v[182:185], v[190:193], v[64:67]
	v_mfma_f32_16x16x32_bf16 v[52:55], v[160:163], v[198:201], v[52:55]
	v_mfma_f32_16x16x32_bf16 v[48:51], v[182:185], v[198:201], v[48:51]
	v_mfma_f32_16x16x32_bf16 v[44:47], v[160:163], v[206:209], v[44:47]
	v_mfma_f32_16x16x32_bf16 v[40:43], v[182:185], v[206:209], v[40:43]
	v_mfma_f32_16x16x32_bf16 v[36:39], v[160:163], v[214:217], v[36:39]
	v_mfma_f32_16x16x32_bf16 v[32:35], v[182:185], v[214:217], v[32:35]
	v_mfma_f32_16x16x32_bf16 v[68:71], v[178:181], v[194:197], v[68:71]
	v_mfma_f32_16x16x32_bf16 v[64:67], v[186:189], v[194:197], v[64:67]
	v_mfma_f32_16x16x32_bf16 v[52:55], v[178:181], v[202:205], v[52:55]
	v_mfma_f32_16x16x32_bf16 v[48:51], v[186:189], v[202:205], v[48:51]
	v_mfma_f32_16x16x32_bf16 v[44:47], v[178:181], v[210:213], v[44:47]
	v_mfma_f32_16x16x32_bf16 v[40:43], v[186:189], v[210:213], v[40:43]
	v_mfma_f32_16x16x32_bf16 v[36:39], v[178:181], v[218:221], v[36:39]
	v_mfma_f32_16x16x32_bf16 v[32:35], v[186:189], v[218:221], v[32:35]
	s_barrier
; #define PG8_STAGE(bufoff, gbase, voff) do { _Pragma("unroll") for (int _i = 0; _i < 2; ++_i) \
;         __builtin_amdgcn_global_load_lds((const unsigned*)((const char*)(gbase) + (voff)[_i]), (LAS unsigned*)(lds + (bufoff) + ldsw + _i * 8192), 16, 0, 0); } while (0)
; #define PG8_LDA(dst, b, h) do { _Pragma("unroll") for (int m = 0; m < 4; ++m) _Pragma("unroll") for (int k = 0; k < 2; ++k) dst[m][k] = *(const LAS bf16x8*)(lds + PG8_SA(b, h) + aoff + m * 2048 + k * 1024); } while (0)
; #define PG8_LDB(dst, b, h) do { _Pragma("unroll") for (int n = 0; n < 2; ++n) _Pragma("unroll") for (int k = 0; k < 2; ++k) dst[n][k] = *(const LAS bf16x8*)(lds + PG8_SB(b, h) + boff + n * 2048 + k * 1024); } while (0)
; #define PG8_MMA(ai, bj, At, Bt) do { __builtin_amdgcn_s_setprio(1); _Pragma("unroll") for (int m = 0; m < 4; ++m) _Pragma("unroll") for (int n = 0; n < 2; ++n) _Pragma("unroll") for (int k = 0; k < 2; ++k) \
;         acc[ai][bj][m][n] = __builtin_amdgcn_mfma_f32_16x16x32_bf16(Bt[n][k], At[m][k], acc[ai][bj][m][n], 0, 0, 0); __builtin_amdgcn_s_setprio(0); } while (0)
; #define PG8_WAIT_V(n) asm volatile("s_waitcnt vmcnt(" #n ")" ::: "memory")
; #define PG8_WAIT_L(n) asm volatile("s_waitcnt lgkmcnt(" #n ")" ::: "memory")
; #define PG8_BAR __builtin_amdgcn_s_barrier()
; #define PG8_SCHED __builtin_amdgcn_sched_barrier(0)
; __device__ __forceinline__ void gemm_phase(LAS unsigned char* lds, const Params& p, const bf16_t* gA, const bf16_t* gBt, const int gM, const int gN, const int gK, const int epi, const int perm, bf16_t* const Hp, const int goff, const float coef) {
;     ...
;             PG8_LDA(At, 0, 1); PG8_STAGE(PG8_SB(0, 0), b2, voffB); PG8_STAGE(PG8_SB(0, 1), b2 + hstep, voffB); PG8_STAGE(PG8_SA(0, 0), a2, voffA);
;             PG8_WAIT_V(8); PG8_WAIT_L(0); PG8_BAR; PG8_MMA(1, 0, At, B0); PG8_MMA(1, 1, At, B1); PG8_BAR; PG8_SCHED;
;             PG8_LDB(B0, 1, 0); PG8_LDB(B1, 1, 1); PG8_SCHED; PG8_LDA(At, 1, 0); PG8_STAGE(PG8_SA(0, 1), a2 + hstep, voffA);
;             PG8_WAIT_V(8); PG8_WAIT_L(0); PG8_BAR; PG8_MMA(0, 0, At, B0); PG8_MMA(0, 1, At, B1); PG8_BAR; PG8_SCHED;
	s_add_i32 s57, s48, s36
	s_mov_b32 m0, s57
	ds_read_b128 v[190:193], v176 offset:16384
	ds_read_b128 v[194:197], v176 offset:17408
	ds_read_b128 v[198:201], v176 offset:18432
	ds_read_b128 v[202:205], v176 offset:19456
	ds_read_b128 v[206:209], v176 offset:20480
	ds_read_b128 v[210:213], v176 offset:21504
	ds_read_b128 v[214:217], v176 offset:22528
	ds_read_b128 v[218:221], v176 offset:23552
	global_load_lds_dwordx4 v138, s[28:29]
	s_add_i32 m0, s57, 0x2000
	s_add_u32 s58, s28, 0x80000
	s_addc_u32 s59, s29, 0
	s_add_i32 s57, s49, s36
	global_load_lds_dwordx4 v144, s[28:29]
	s_mov_b32 m0, s57
	s_nop 0
	global_load_lds_dwordx4 v138, s[58:59]
	s_add_i32 m0, s57, 0x2000
	s_nop 0
	global_load_lds_dwordx4 v144, s[58:59]
	s_mov_b32 m0, s37
	s_nop 0
	global_load_lds_dwordx4 v136, s[30:31]
	s_mov_b32 m0, s38
	s_nop 0
	global_load_lds_dwordx4 v142, s[30:31]
	s_waitcnt vmcnt(8) lgkmcnt(0)
	s_barrier
	v_mfma_f32_16x16x32_bf16 v[92:95], v[128:131], v[190:193], v[92:95]
	v_mfma_f32_16x16x32_bf16 v[88:91], v[152:155], v[190:193], v[88:91]
	v_mfma_f32_16x16x32_bf16 v[84:87], v[128:131], v[198:201], v[84:87]
	v_mfma_f32_16x16x32_bf16 v[80:83], v[152:155], v[198:201], v[80:83]
	v_mfma_f32_16x16x32_bf16 v[76:79], v[128:131], v[206:209], v[76:79]
	v_mfma_f32_16x16x32_bf16 v[72:75], v[152:155], v[206:209], v[72:75]
	v_mfma_f32_16x16x32_bf16 v[60:63], v[128:131], v[214:217], v[60:63]
	v_mfma_f32_16x16x32_bf16 v[56:59], v[152:155], v[214:217], v[56:59]
	v_mfma_f32_16x16x32_bf16 v[92:95], v[132:135], v[194:197], v[92:95]
	v_mfma_f32_16x16x32_bf16 v[88:91], v[156:159], v[194:197], v[88:91]
	v_mfma_f32_16x16x32_bf16 v[84:87], v[132:135], v[202:205], v[84:87]
	v_mfma_f32_16x16x32_bf16 v[80:83], v[156:159], v[202:205], v[80:83]
	v_mfma_f32_16x16x32_bf16 v[76:79], v[132:135], v[210:213], v[76:79]
	v_mfma_f32_16x16x32_bf16 v[72:75], v[156:159], v[210:213], v[72:75]
	v_mfma_f32_16x16x32_bf16 v[60:63], v[132:135], v[218:221], v[60:63]
	v_mfma_f32_16x16x32_bf16 v[56:59], v[156:159], v[218:221], v[56:59]
	v_mfma_f32_16x16x32_bf16 v[28:31], v[160:163], v[190:193], v[28:31]
	v_mfma_f32_16x16x32_bf16 v[24:27], v[182:185], v[190:193], v[24:27]
	v_mfma_f32_16x16x32_bf16 v[20:23], v[160:163], v[198:201], v[20:23]
	v_mfma_f32_16x16x32_bf16 v[16:19], v[182:185], v[198:201], v[16:19]
	v_mfma_f32_16x16x32_bf16 v[12:15], v[160:163], v[206:209], v[12:15]
	v_mfma_f32_16x16x32_bf16 v[8:11], v[182:185], v[206:209], v[8:11]
	v_mfma_f32_16x16x32_bf16 v[4:7], v[160:163], v[214:217], v[4:7]
	v_mfma_f32_16x16x32_bf16 v[0:3], v[182:185], v[214:217], v[0:3]
	v_mfma_f32_16x16x32_bf16 v[28:31], v[178:181], v[194:197], v[28:31]
	v_mfma_f32_16x16x32_bf16 v[24:27], v[186:189], v[194:197], v[24:27]
	v_mfma_f32_16x16x32_bf16 v[20:23], v[178:181], v[202:205], v[20:23]
	v_mfma_f32_16x16x32_bf16 v[16:19], v[186:189], v[202:205], v[16:19]
	v_mfma_f32_16x16x32_bf16 v[12:15], v[178:181], v[210:213], v[12:15]
	v_mfma_f32_16x16x32_bf16 v[8:11], v[186:189], v[210:213], v[8:11]
	v_mfma_f32_16x16x32_bf16 v[4:7], v[178:181], v[218:221], v[4:7]
	v_mfma_f32_16x16x32_bf16 v[0:3], v[186:189], v[218:221], v[0:3]
	s_barrier
	s_add_i32 s57, 0, 0x18000
	s_add_i32 s58, 0, 0x1c000
	ds_read_b128 v[128:131], v222
	ds_read_b128 v[132:135], v222 offset:1024
	ds_read_b128 v[152:155], v222 offset:2048
	ds_read_b128 v[156:159], v222 offset:3072
	ds_read_b128 v[160:163], v223
	ds_read_b128 v[178:181], v223 offset:1024
	ds_read_b128 v[182:185], v223 offset:2048
	ds_read_b128 v[186:189], v223 offset:3072
	s_add_u32 s30, s30, 0x80000
	s_addc_u32 s31, s31, 0
	s_mov_b32 m0, s39
	ds_read_b128 v[190:193], v176 offset:32768
	ds_read_b128 v[194:197], v176 offset:33792
	ds_read_b128 v[198:201], v176 offset:34816
	ds_read_b128 v[202:205], v176 offset:35840
	ds_read_b128 v[206:209], v176 offset:36864
	ds_read_b128 v[210:213], v176 offset:37888
	ds_read_b128 v[214:217], v176 offset:38912
	ds_read_b128 v[218:221], v176 offset:39936
	global_load_lds_dwordx4 v136, s[30:31]
	s_mov_b32 m0, s40
	s_nop 0
	global_load_lds_dwordx4 v142, s[30:31]
	s_waitcnt vmcnt(8) lgkmcnt(0)
	s_barrier
; #define PG8_STAGE(bufoff, gbase, voff) do { _Pragma("unroll") for (int _i = 0; _i < 2; ++_i) \
;         __builtin_amdgcn_global_load_lds((const unsigned*)((const char*)(gbase) + (voff)[_i]), (LAS unsigned*)(lds + (bufoff) + ldsw + _i * 8192), 16, 0, 0); } while (0)
; #define PG8_LDA(dst, b, h) do { _Pragma("unroll") for (int m = 0; m < 4; ++m) _Pragma("unroll") for (int k = 0; k < 2; ++k) dst[m][k] = *(const LAS bf16x8*)(lds + PG8_SA(b, h) + aoff + m * 2048 + k * 1024); } while (0)
; #define PG8_MMA(ai, bj, At, Bt) do { __builtin_amdgcn_s_setprio(1); _Pragma("unroll") for (int m = 0; m < 4; ++m) _Pragma("unroll") for (int n = 0; n < 2; ++n) _Pragma("unroll") for (int k = 0; k < 2; ++k) \
;         acc[ai][bj][m][n] = __builtin_amdgcn_mfma_f32_16x16x32_bf16(Bt[n][k], At[m][k], acc[ai][bj][m][n], 0, 0, 0); __builtin_amdgcn_s_setprio(0); } while (0)
; #define PG8_WAIT_V(n) asm volatile("s_waitcnt vmcnt(" #n ")" ::: "memory")
; #define PG8_WAIT_L(n) asm volatile("s_waitcnt lgkmcnt(" #n ")" ::: "memory")
; #define PG8_BAR __builtin_amdgcn_s_barrier()
; #define PG8_SCHED __builtin_amdgcn_sched_barrier(0)
; __device__ __forceinline__ void gemm_phase(LAS unsigned char* lds, const Params& p, const bf16_t* gA, const bf16_t* gBt, const int gM, const int gN, const int gK, const int epi, const int perm, bf16_t* const Hp, const int goff, const float coef) {
;     ...
;             PG8_WAIT_V(8); PG8_WAIT_L(0); PG8_BAR; PG8_MMA(0, 0, At, B0); PG8_MMA(0, 1, At, B1); PG8_BAR; PG8_SCHED;
;             PG8_LDA(At, 1, 1); PG8_STAGE(PG8_SB(1, 0), b3, voffB); PG8_STAGE(PG8_SB(1, 1), b3 + hstep, voffB); PG8_STAGE(PG8_SA(1, 0), a3, voffA);
;             PG8_WAIT_V(8); PG8_WAIT_L(0); PG8_BAR; PG8_MMA(1, 0, At, B0); PG8_MMA(1, 1, At, B1); PG8_BAR; PG8_SCHED;
;         }
	v_mfma_f32_16x16x32_bf16 v[124:127], v[128:131], v[190:193], v[124:127]
	v_mfma_f32_16x16x32_bf16 v[120:123], v[152:155], v[190:193], v[120:123]
	v_mfma_f32_16x16x32_bf16 v[116:119], v[128:131], v[198:201], v[116:119]
	v_mfma_f32_16x16x32_bf16 v[112:115], v[152:155], v[198:201], v[112:115]
	v_mfma_f32_16x16x32_bf16 v[108:111], v[128:131], v[206:209], v[108:111]
	v_mfma_f32_16x16x32_bf16 v[104:107], v[152:155], v[206:209], v[104:107]
	v_mfma_f32_16x16x32_bf16 v[100:103], v[128:131], v[214:217], v[100:103]
	v_mfma_f32_16x16x32_bf16 v[96:99], v[152:155], v[214:217], v[96:99]
	v_mfma_f32_16x16x32_bf16 v[124:127], v[132:135], v[194:197], v[124:127]
	v_mfma_f32_16x16x32_bf16 v[120:123], v[156:159], v[194:197], v[120:123]
	v_mfma_f32_16x16x32_bf16 v[116:119], v[132:135], v[202:205], v[116:119]
	v_mfma_f32_16x16x32_bf16 v[112:115], v[156:159], v[202:205], v[112:115]
	v_mfma_f32_16x16x32_bf16 v[108:111], v[132:135], v[210:213], v[108:111]
	v_mfma_f32_16x16x32_bf16 v[104:107], v[156:159], v[210:213], v[104:107]
	v_mfma_f32_16x16x32_bf16 v[100:103], v[132:135], v[218:221], v[100:103]
	v_mfma_f32_16x16x32_bf16 v[96:99], v[156:159], v[218:221], v[96:99]
	v_mfma_f32_16x16x32_bf16 v[68:71], v[160:163], v[190:193], v[68:71]
	v_mfma_f32_16x16x32_bf16 v[64:67], v[182:185], v[190:193], v[64:67]
	v_mfma_f32_16x16x32_bf16 v[52:55], v[160:163], v[198:201], v[52:55]
	v_mfma_f32_16x16x32_bf16 v[48:51], v[182:185], v[198:201], v[48:51]
	v_mfma_f32_16x16x32_bf16 v[44:47], v[160:163], v[206:209], v[44:47]
	v_mfma_f32_16x16x32_bf16 v[40:43], v[182:185], v[206:209], v[40:43]
	v_mfma_f32_16x16x32_bf16 v[36:39], v[160:163], v[214:217], v[36:39]
	v_mfma_f32_16x16x32_bf16 v[32:35], v[182:185], v[214:217], v[32:35]
	v_mfma_f32_16x16x32_bf16 v[68:71], v[178:181], v[194:197], v[68:71]
	v_mfma_f32_16x16x32_bf16 v[64:67], v[186:189], v[194:197], v[64:67]
	v_mfma_f32_16x16x32_bf16 v[52:55], v[178:181], v[202:205], v[52:55]
	v_mfma_f32_16x16x32_bf16 v[48:51], v[186:189], v[202:205], v[48:51]
	v_mfma_f32_16x16x32_bf16 v[44:47], v[178:181], v[210:213], v[44:47]
	v_mfma_f32_16x16x32_bf16 v[40:43], v[186:189], v[210:213], v[40:43]
	v_mfma_f32_16x16x32_bf16 v[36:39], v[178:181], v[218:221], v[36:39]
	v_mfma_f32_16x16x32_bf16 v[32:35], v[186:189], v[218:221], v[32:35]
	s_barrier
	s_mov_b64 s[98:99], s[30:31]
	s_add_i32 s30, s57, s36
	s_mov_b32 m0, s30
	ds_read_b128 v[190:193], v176 offset:49152
	ds_read_b128 v[194:197], v176 offset:50176
	ds_read_b128 v[198:201], v176 offset:51200
	ds_read_b128 v[202:205], v176 offset:52224
	ds_read_b128 v[206:209], v176 offset:53248
	ds_read_b128 v[210:213], v176 offset:54272
	ds_read_b128 v[214:217], v176 offset:55296
	ds_read_b128 v[218:221], v176 offset:56320
	s_add_u32 s100, s28, 0x80
	s_addc_u32 s101, s29, 0
	global_load_lds_dwordx4 v138, s[100:101]
	s_add_i32 m0, s30, 0x2000
	s_add_u32 s28, s28, 0x80080
	s_addc_u32 s29, s29, 0
	s_add_i32 s30, s58, s36
	global_load_lds_dwordx4 v144, s[100:101]
	s_mov_b32 m0, s30
	s_nop 0
	global_load_lds_dwordx4 v138, s[28:29]
	s_add_i32 m0, s30, 0x2000
	s_nop 0
	global_load_lds_dwordx4 v144, s[28:29]
	s_mov_b32 m0, s44
	s_add_u32 s100, s98, 0xfff80080
	s_addc_u32 s101, s99, -1
	global_load_lds_dwordx4 v136, s[100:101]
	s_mov_b32 m0, s45
	s_nop 0
	global_load_lds_dwordx4 v142, s[100:101]
	s_waitcnt vmcnt(8) lgkmcnt(0)
	s_barrier
	v_mfma_f32_16x16x32_bf16 v[92:95], v[128:131], v[190:193], v[92:95]
	v_mfma_f32_16x16x32_bf16 v[88:91], v[152:155], v[190:193], v[88:91]
	v_mfma_f32_16x16x32_bf16 v[84:87], v[128:131], v[198:201], v[84:87]
	v_mfma_f32_16x16x32_bf16 v[80:83], v[152:155], v[198:201], v[80:83]
	v_mfma_f32_16x16x32_bf16 v[76:79], v[128:131], v[206:209], v[76:79]
	v_mfma_f32_16x16x32_bf16 v[72:75], v[152:155], v[206:209], v[72:75]
	v_mfma_f32_16x16x32_bf16 v[60:63], v[128:131], v[214:217], v[60:63]
	v_mfma_f32_16x16x32_bf16 v[56:59], v[152:155], v[214:217], v[56:59]
	v_mfma_f32_16x16x32_bf16 v[92:95], v[132:135], v[194:197], v[92:95]
	v_mfma_f32_16x16x32_bf16 v[88:91], v[156:159], v[194:197], v[88:91]
	v_mfma_f32_16x16x32_bf16 v[84:87], v[132:135], v[202:205], v[84:87]
	v_mfma_f32_16x16x32_bf16 v[80:83], v[156:159], v[202:205], v[80:83]
	v_mfma_f32_16x16x32_bf16 v[76:79], v[132:135], v[210:213], v[76:79]
	v_mfma_f32_16x16x32_bf16 v[72:75], v[156:159], v[210:213], v[72:75]
	v_mfma_f32_16x16x32_bf16 v[60:63], v[132:135], v[218:221], v[60:63]
	v_mfma_f32_16x16x32_bf16 v[56:59], v[156:159], v[218:221], v[56:59]
	v_mfma_f32_16x16x32_bf16 v[28:31], v[160:163], v[190:193], v[28:31]
	v_mfma_f32_16x16x32_bf16 v[24:27], v[182:185], v[190:193], v[24:27]
	v_mfma_f32_16x16x32_bf16 v[20:23], v[160:163], v[198:201], v[20:23]
	v_mfma_f32_16x16x32_bf16 v[16:19], v[182:185], v[198:201], v[16:19]
	v_mfma_f32_16x16x32_bf16 v[12:15], v[160:163], v[206:209], v[12:15]
	v_mfma_f32_16x16x32_bf16 v[8:11], v[182:185], v[206:209], v[8:11]
	v_mfma_f32_16x16x32_bf16 v[4:7], v[160:163], v[214:217], v[4:7]
	v_mfma_f32_16x16x32_bf16 v[0:3], v[182:185], v[214:217], v[0:3]
	v_mfma_f32_16x16x32_bf16 v[28:31], v[178:181], v[194:197], v[28:31]
	v_mfma_f32_16x16x32_bf16 v[24:27], v[186:189], v[194:197], v[24:27]
	v_mfma_f32_16x16x32_bf16 v[20:23], v[178:181], v[202:205], v[20:23]
	v_mfma_f32_16x16x32_bf16 v[16:19], v[186:189], v[202:205], v[16:19]
	v_mfma_f32_16x16x32_bf16 v[12:15], v[178:181], v[210:213], v[12:15]
	v_mfma_f32_16x16x32_bf16 v[8:11], v[186:189], v[210:213], v[8:11]
	v_mfma_f32_16x16x32_bf16 v[4:7], v[178:181], v[218:221], v[4:7]
	v_mfma_f32_16x16x32_bf16 v[0:3], v[186:189], v[218:221], v[0:3]
	s_barrier
	s_add_u32 s26, s26, 0x100
	s_addc_u32 s27, s27, 0
	s_add_u32 s54, s54, 0x100
	s_addc_u32 s55, s55, 0
	s_cmp_ge_u32 s56, s52
	s_mov_b32 s30, s56
	s_cbranch_scc0 .LBB0_1593

; #define PG8_STAGE(bufoff, gbase, voff) do { _Pragma("unroll") for (int _i = 0; _i < 2; ++_i) \
;         __builtin_amdgcn_global_load_lds((const unsigned*)((const char*)(gbase) + (voff)[_i]), (LAS unsigned*)(lds + (bufoff) + ldsw + _i * 8192), 16, 0, 0); } while (0)
; #define PG8_LDA(dst, b, h) do { _Pragma("unroll") for (int m = 0; m < 4; ++m) _Pragma("unroll") for (int k = 0; k < 2; ++k) dst[m][k] = *(const LAS bf16x8*)(lds + PG8_SA(b, h) + aoff + m * 2048 + k * 1024); } while (0)
; #define PG8_WAIT_V(n) asm volatile("s_waitcnt vmcnt(" #n ")" ::: "memory")
; #define PG8_WAIT_L(n) asm volatile("s_waitcnt lgkmcnt(" #n ")" ::: "memory")
; #define PG8_BAR __builtin_amdgcn_s_barrier()
; __device__ __forceinline__ void gemm_phase(LAS unsigned char* lds, const Params& p, const bf16_t* gA, const bf16_t* gBt, const int gM, const int gN, const int gK, const int epi, const int perm, bf16_t* const Hp, const int goff, const float coef) {
;     ...
;         const bool has_next = S.next(ui + 1, nxt);
;         const char* nA = has_next ? (const char*)gA + (size_t)nxt.pm * tstep + (nxt.ks > 0 ? nxt.ks * ksl : 0) : cA; const char* nB = has_next ? (const char*)gBt + (size_t)nxt.pn * tstep + (nxt.ks > 0 ? nxt.ks * ksl : 0) : cB;
;         const int nt = cur.ks >= 0 ? ntf / 4 : ntf;
;         for (int t = 0; t < nt; t += 2) {
;             const bool last = (t == nt - 2);
;             const char* a1 = cA + (size_t)(t + 1) * kstep;
;             const char* a2 = last ? nA : cA + (size_t)(t + 2) * kstep; const char* b2 = last ? nB : cB + (size_t)(t + 2) * kstep;
;             const char* a3 = a2 + kstep; const char* b3 = b2 + kstep;
;             PG8_LDB(B0, 0, 0); PG8_LDB(B1, 0, 1); PG8_SCHED; PG8_LDA(At, 0, 0); PG8_STAGE(PG8_SA(1, 1), a1 + hstep, voffA);
;             PG8_WAIT_V(8); PG8_WAIT_L(0); PG8_BAR; PG8_MMA(0, 0, At, B0); PG8_MMA(0, 1, At, B1); PG8_BAR; PG8_SCHED;
;             PG8_LDA(At, 0, 1); PG8_STAGE(PG8_SB(0, 0), b2, voffB); PG8_STAGE(PG8_SB(0, 1), b2 + hstep, voffB); PG8_STAGE(PG8_SA(0, 0), a2, voffA);
;             PG8_WAIT_V(8); PG8_WAIT_L(0); PG8_BAR; PG8_MMA(1, 0, At, B0); PG8_MMA(1, 1, At, B1); PG8_BAR; PG8_SCHED;
;             PG8_LDB(B0, 1, 0); PG8_LDB(B1, 1, 1); PG8_SCHED; PG8_LDA(At, 1, 0); PG8_STAGE(PG8_SA(0, 1), a2 + hstep, voffA);
;             PG8_WAIT_V(8); PG8_WAIT_L(0); PG8_BAR; PG8_MMA(0, 0, At, B0); PG8_MMA(0, 1, At, B1); PG8_BAR; PG8_SCHED;
.LBB0_1736:
	s_ashr_i32 s13, s12, 31
	s_lshl_b64 s[18:19], s[12:13], 20
	s_add_u32 s13, s3, s18
	s_addc_u32 s15, s33, s19
	s_lshl_b64 s[18:19], s[0:1], 10
	s_cmp_gt_i32 s0, 0
	s_cselect_b32 s50, s18, 0
	s_cselect_b32 s49, s19, 0
	s_add_u32 s18, s13, s50
	s_addc_u32 s19, s15, s49
	s_and_b64 s[20:21], s[16:17], exec
	s_cselect_b32 s13, s19, s27
	s_cselect_b32 s48, s18, s26
	s_ashr_i32 s15, s14, 31
	s_lshl_b64 s[20:21], s[14:15], 20
	s_add_u32 s15, s34, s20
	s_addc_u32 s21, s35, s21
	s_add_u32 s20, s15, s50
	s_addc_u32 s21, s21, s49
	s_and_b64 s[50:51], s[16:17], exec
	s_cselect_b32 s15, s21, s29
	s_cselect_b32 s49, s20, s28
	s_cmp_gt_i32 s31, -1
	s_cselect_b32 s50, 8, 32
	s_add_i32 s51, s50, -2
	s_add_u32 s26, s26, 0x80080
	s_addc_u32 s27, s27, 0
	s_add_u32 s52, s28, 0x100
	s_mov_b32 s30, 0
	s_addc_u32 s53, s29, 0
	v_add_u32_e32 v224, 0x18000, v147
	v_add_u32_e32 v225, 0x1c000, v147
	ds_read_b128 v[160:163], v156
	ds_read_b128 v[164:167], v156 offset:1024
	ds_read_b128 v[168:171], v156 offset:2048
	ds_read_b128 v[172:175], v156 offset:3072
	ds_read_b128 v[176:179], v157
	ds_read_b128 v[180:183], v157 offset:1024
	ds_read_b128 v[184:187], v157 offset:2048
	ds_read_b128 v[188:191], v157 offset:3072
	s_add_i32 s54, s30, 2
	s_add_u32 s28, s26, 0xfff80080
	s_addc_u32 s29, s27, -1
	s_cmp_eq_u32 s51, s30
	s_cselect_b32 s30, s48, s28
	s_cselect_b32 s31, s13, s29
	s_cselect_b32 s29, s15, s53
	s_cselect_b32 s28, s49, s52
	s_add_i32 m0, s23, 0xc000
	ds_read_b128 v[192:195], v158
	ds_read_b128 v[196:199], v158 offset:1024
	ds_read_b128 v[200:203], v158 offset:2048
	ds_read_b128 v[204:207], v158 offset:3072
	ds_read_b128 v[208:211], v158 offset:4096
	ds_read_b128 v[212:215], v158 offset:5120
	ds_read_b128 v[216:219], v158 offset:6144
	ds_read_b128 v[220:223], v158 offset:7168
	global_load_lds_dwordx4 v136, s[26:27]
	s_add_i32 m0, s23, 0xe000
	s_nop 0
	global_load_lds_dwordx4 v138, s[26:27]
	s_waitcnt vmcnt(8) lgkmcnt(0)
	s_barrier
	v_mfma_f32_16x16x32_bf16 v[124:127], v[160:163], v[192:195], 0
	v_mfma_f32_16x16x32_bf16 v[120:123], v[168:171], v[192:195], 0
	v_mfma_f32_16x16x32_bf16 v[108:111], v[160:163], v[200:203], 0
	v_mfma_f32_16x16x32_bf16 v[104:107], v[168:171], v[200:203], 0
	v_mfma_f32_16x16x32_bf16 v[92:95], v[160:163], v[208:211], 0
	v_mfma_f32_16x16x32_bf16 v[88:91], v[168:171], v[208:211], 0
	v_mfma_f32_16x16x32_bf16 v[76:79], v[160:163], v[216:219], 0
	v_mfma_f32_16x16x32_bf16 v[72:75], v[168:171], v[216:219], 0
	v_mfma_f32_16x16x32_bf16 v[124:127], v[164:167], v[196:199], v[124:127]
	v_mfma_f32_16x16x32_bf16 v[120:123], v[172:175], v[196:199], v[120:123]
	v_mfma_f32_16x16x32_bf16 v[108:111], v[164:167], v[204:207], v[108:111]
	v_mfma_f32_16x16x32_bf16 v[104:107], v[172:175], v[204:207], v[104:107]
	v_mfma_f32_16x16x32_bf16 v[92:95], v[164:167], v[212:215], v[92:95]
	v_mfma_f32_16x16x32_bf16 v[88:91], v[172:175], v[212:215], v[88:91]
	v_mfma_f32_16x16x32_bf16 v[76:79], v[164:167], v[220:223], v[76:79]
	v_mfma_f32_16x16x32_bf16 v[72:75], v[172:175], v[220:223], v[72:75]
	v_mfma_f32_16x16x32_bf16 v[116:119], v[176:179], v[192:195], 0
	v_mfma_f32_16x16x32_bf16 v[112:115], v[184:187], v[192:195], 0
	v_mfma_f32_16x16x32_bf16 v[100:103], v[176:179], v[200:203], 0
	v_mfma_f32_16x16x32_bf16 v[96:99], v[184:187], v[200:203], 0
	v_mfma_f32_16x16x32_bf16 v[84:87], v[176:179], v[208:211], 0
	v_mfma_f32_16x16x32_bf16 v[80:83], v[184:187], v[208:211], 0
	v_mfma_f32_16x16x32_bf16 v[68:71], v[176:179], v[216:219], 0
	v_mfma_f32_16x16x32_bf16 v[64:67], v[184:187], v[216:219], 0
	v_mfma_f32_16x16x32_bf16 v[116:119], v[180:183], v[196:199], v[116:119]
	v_mfma_f32_16x16x32_bf16 v[112:115], v[188:191], v[196:199], v[112:115]
	v_mfma_f32_16x16x32_bf16 v[100:103], v[180:183], v[204:207], v[100:103]
	v_mfma_f32_16x16x32_bf16 v[96:99], v[188:191], v[204:207], v[96:99]
	v_mfma_f32_16x16x32_bf16 v[84:87], v[180:183], v[212:215], v[84:87]
	v_mfma_f32_16x16x32_bf16 v[80:83], v[188:191], v[212:215], v[80:83]
	v_mfma_f32_16x16x32_bf16 v[68:71], v[180:183], v[220:223], v[68:71]
	v_mfma_f32_16x16x32_bf16 v[64:67], v[188:191], v[220:223], v[64:67]
	s_barrier
	s_add_i32 s55, s44, s36
	s_mov_b32 m0, s55
	ds_read_b128 v[192:195], v158 offset:16384
	ds_read_b128 v[196:199], v158 offset:17408
	ds_read_b128 v[200:203], v158 offset:18432
	ds_read_b128 v[204:207], v158 offset:19456
	ds_read_b128 v[208:211], v158 offset:20480
	ds_read_b128 v[212:215], v158 offset:21504
	ds_read_b128 v[216:219], v158 offset:22528
	ds_read_b128 v[220:223], v158 offset:23552
	global_load_lds_dwordx4 v130, s[28:29]
	s_add_i32 m0, s55, 0x2000
	s_add_u32 s56, s28, 0x80000
	s_addc_u32 s57, s29, 0
	s_add_i32 s55, s45, s36
	global_load_lds_dwordx4 v134, s[28:29]
	s_mov_b32 m0, s55
	s_nop 0
	global_load_lds_dwordx4 v130, s[56:57]
	s_add_i32 m0, s55, 0x2000
	s_nop 0
	global_load_lds_dwordx4 v134, s[56:57]
	s_mov_b32 m0, s23
	s_nop 0
	global_load_lds_dwordx4 v128, s[30:31]
	s_mov_b32 m0, s25
	s_nop 0
	global_load_lds_dwordx4 v132, s[30:31]
	s_waitcnt vmcnt(8) lgkmcnt(0)
	s_barrier
; #define PG8_STAGE(bufoff, gbase, voff) do { _Pragma("unroll") for (int _i = 0; _i < 2; ++_i) \
;         __builtin_amdgcn_global_load_lds((const unsigned*)((const char*)(gbase) + (voff)[_i]), (LAS unsigned*)(lds + (bufoff) + ldsw + _i * 8192), 16, 0, 0); } while (0)
; #define PG8_LDA(dst, b, h) do { _Pragma("unroll") for (int m = 0; m < 4; ++m) _Pragma("unroll") for (int k = 0; k < 2; ++k) dst[m][k] = *(const LAS bf16x8*)(lds + PG8_SA(b, h) + aoff + m * 2048 + k * 1024); } while (0)
; #define PG8_LDB(dst, b, h) do { _Pragma("unroll") for (int n = 0; n < 2; ++n) _Pragma("unroll") for (int k = 0; k < 2; ++k) dst[n][k] = *(const LAS bf16x8*)(lds + PG8_SB(b, h) + boff + n * 2048 + k * 1024); } while (0)
; #define PG8_MMA(ai, bj, At, Bt) do { __builtin_amdgcn_s_setprio(1); _Pragma("unroll") for (int m = 0; m < 4; ++m) _Pragma("unroll") for (int n = 0; n < 2; ++n) _Pragma("unroll") for (int k = 0; k < 2; ++k) \
;         acc[ai][bj][m][n] = __builtin_amdgcn_mfma_f32_16x16x32_bf16(Bt[n][k], At[m][k], acc[ai][bj][m][n], 0, 0, 0); __builtin_amdgcn_s_setprio(0); } while (0)
; #define PG8_WAIT_V(n) asm volatile("s_waitcnt vmcnt(" #n ")" ::: "memory")
; #define PG8_WAIT_L(n) asm volatile("s_waitcnt lgkmcnt(" #n ")" ::: "memory")
; #define PG8_BAR __builtin_amdgcn_s_barrier()
; #define PG8_SCHED __builtin_amdgcn_sched_barrier(0)
; __device__ __forceinline__ void gemm_phase(LAS unsigned char* lds, const Params& p, const bf16_t* gA, const bf16_t* gBt, const int gM, const int gN, const int gK, const int epi, const int perm, bf16_t* const Hp, const int goff, const float coef) {
;     ...
;             PG8_WAIT_V(8); PG8_WAIT_L(0); PG8_BAR; PG8_MMA(1, 0, At, B0); PG8_MMA(1, 1, At, B1); PG8_BAR; PG8_SCHED;
;             PG8_LDB(B0, 1, 0); PG8_LDB(B1, 1, 1); PG8_SCHED; PG8_LDA(At, 1, 0); PG8_STAGE(PG8_SA(0, 1), a2 + hstep, voffA);
;             PG8_WAIT_V(8); PG8_WAIT_L(0); PG8_BAR; PG8_MMA(0, 0, At, B0); PG8_MMA(0, 1, At, B1); PG8_BAR; PG8_SCHED;
;             PG8_LDA(At, 1, 1); PG8_STAGE(PG8_SB(1, 0), b3, voffB); PG8_STAGE(PG8_SB(1, 1), b3 + hstep, voffB); PG8_STAGE(PG8_SA(1, 0), a3, voffA);
;             PG8_WAIT_V(8); PG8_WAIT_L(0); PG8_BAR; PG8_MMA(1, 0, At, B0); PG8_MMA(1, 1, At, B1); PG8_BAR; PG8_SCHED;
	v_mfma_f32_16x16x32_bf16 v[60:63], v[160:163], v[192:195], 0
	v_mfma_f32_16x16x32_bf16 v[56:59], v[168:171], v[192:195], 0
	v_mfma_f32_16x16x32_bf16 v[44:47], v[160:163], v[200:203], 0
	v_mfma_f32_16x16x32_bf16 v[40:43], v[168:171], v[200:203], 0
	v_mfma_f32_16x16x32_bf16 v[28:31], v[160:163], v[208:211], 0
	v_mfma_f32_16x16x32_bf16 v[24:27], v[168:171], v[208:211], 0
	v_mfma_f32_16x16x32_bf16 v[12:15], v[160:163], v[216:219], 0
	v_mfma_f32_16x16x32_bf16 v[8:11], v[168:171], v[216:219], 0
	v_mfma_f32_16x16x32_bf16 v[60:63], v[164:167], v[196:199], v[60:63]
	v_mfma_f32_16x16x32_bf16 v[56:59], v[172:175], v[196:199], v[56:59]
	v_mfma_f32_16x16x32_bf16 v[44:47], v[164:167], v[204:207], v[44:47]
	v_mfma_f32_16x16x32_bf16 v[40:43], v[172:175], v[204:207], v[40:43]
	v_mfma_f32_16x16x32_bf16 v[28:31], v[164:167], v[212:215], v[28:31]
	v_mfma_f32_16x16x32_bf16 v[24:27], v[172:175], v[212:215], v[24:27]
	v_mfma_f32_16x16x32_bf16 v[12:15], v[164:167], v[220:223], v[12:15]
	v_mfma_f32_16x16x32_bf16 v[8:11], v[172:175], v[220:223], v[8:11]
	v_mfma_f32_16x16x32_bf16 v[52:55], v[176:179], v[192:195], 0
	v_mfma_f32_16x16x32_bf16 v[48:51], v[184:187], v[192:195], 0
	v_mfma_f32_16x16x32_bf16 v[36:39], v[176:179], v[200:203], 0
	v_mfma_f32_16x16x32_bf16 v[32:35], v[184:187], v[200:203], 0
	v_mfma_f32_16x16x32_bf16 v[20:23], v[176:179], v[208:211], 0
	v_mfma_f32_16x16x32_bf16 v[16:19], v[184:187], v[208:211], 0
	v_mfma_f32_16x16x32_bf16 v[4:7], v[176:179], v[216:219], 0
	v_mfma_f32_16x16x32_bf16 v[0:3], v[184:187], v[216:219], 0
	v_mfma_f32_16x16x32_bf16 v[52:55], v[180:183], v[196:199], v[52:55]
	v_mfma_f32_16x16x32_bf16 v[48:51], v[188:191], v[196:199], v[48:51]
	v_mfma_f32_16x16x32_bf16 v[36:39], v[180:183], v[204:207], v[36:39]
	v_mfma_f32_16x16x32_bf16 v[32:35], v[188:191], v[204:207], v[32:35]
	v_mfma_f32_16x16x32_bf16 v[20:23], v[180:183], v[212:215], v[20:23]
	v_mfma_f32_16x16x32_bf16 v[16:19], v[188:191], v[212:215], v[16:19]
	v_mfma_f32_16x16x32_bf16 v[4:7], v[180:183], v[220:223], v[4:7]
	v_mfma_f32_16x16x32_bf16 v[0:3], v[188:191], v[220:223], v[0:3]
	s_barrier
	s_add_i32 s55, 0, 0x18000
	s_add_i32 s56, 0, 0x1c000
	ds_read_b128 v[160:163], v224
	ds_read_b128 v[164:167], v224 offset:1024
	ds_read_b128 v[168:171], v224 offset:2048
	ds_read_b128 v[172:175], v224 offset:3072
	ds_read_b128 v[176:179], v225
	ds_read_b128 v[180:183], v225 offset:1024
	ds_read_b128 v[184:187], v225 offset:2048
	ds_read_b128 v[188:191], v225 offset:3072
	s_add_u32 s30, s30, 0x80000
	s_addc_u32 s31, s31, 0
	s_mov_b32 m0, s37
	ds_read_b128 v[192:195], v158 offset:32768
	ds_read_b128 v[196:199], v158 offset:33792
	ds_read_b128 v[200:203], v158 offset:34816
	ds_read_b128 v[204:207], v158 offset:35840
	ds_read_b128 v[208:211], v158 offset:36864
	ds_read_b128 v[212:215], v158 offset:37888
	ds_read_b128 v[216:219], v158 offset:38912
	ds_read_b128 v[220:223], v158 offset:39936
	global_load_lds_dwordx4 v128, s[30:31]
	s_mov_b32 m0, s38
	s_nop 0
	global_load_lds_dwordx4 v132, s[30:31]
	s_waitcnt vmcnt(8) lgkmcnt(0)
	s_barrier
	v_mfma_f32_16x16x32_bf16 v[124:127], v[160:163], v[192:195], v[124:127]
	v_mfma_f32_16x16x32_bf16 v[120:123], v[168:171], v[192:195], v[120:123]
	v_mfma_f32_16x16x32_bf16 v[108:111], v[160:163], v[200:203], v[108:111]
	v_mfma_f32_16x16x32_bf16 v[104:107], v[168:171], v[200:203], v[104:107]
	v_mfma_f32_16x16x32_bf16 v[92:95], v[160:163], v[208:211], v[92:95]
	v_mfma_f32_16x16x32_bf16 v[88:91], v[168:171], v[208:211], v[88:91]
	v_mfma_f32_16x16x32_bf16 v[76:79], v[160:163], v[216:219], v[76:79]
	v_mfma_f32_16x16x32_bf16 v[72:75], v[168:171], v[216:219], v[72:75]
	v_mfma_f32_16x16x32_bf16 v[124:127], v[164:167], v[196:199], v[124:127]
	v_mfma_f32_16x16x32_bf16 v[120:123], v[172:175], v[196:199], v[120:123]
	v_mfma_f32_16x16x32_bf16 v[108:111], v[164:167], v[204:207], v[108:111]
	v_mfma_f32_16x16x32_bf16 v[104:107], v[172:175], v[204:207], v[104:107]
	v_mfma_f32_16x16x32_bf16 v[92:95], v[164:167], v[212:215], v[92:95]
	v_mfma_f32_16x16x32_bf16 v[88:91], v[172:175], v[212:215], v[88:91]
	v_mfma_f32_16x16x32_bf16 v[76:79], v[164:167], v[220:223], v[76:79]
	v_mfma_f32_16x16x32_bf16 v[72:75], v[172:175], v[220:223], v[72:75]
	v_mfma_f32_16x16x32_bf16 v[116:119], v[176:179], v[192:195], v[116:119]
	v_mfma_f32_16x16x32_bf16 v[112:115], v[184:187], v[192:195], v[112:115]
	v_mfma_f32_16x16x32_bf16 v[100:103], v[176:179], v[200:203], v[100:103]
	v_mfma_f32_16x16x32_bf16 v[96:99], v[184:187], v[200:203], v[96:99]
	v_mfma_f32_16x16x32_bf16 v[84:87], v[176:179], v[208:211], v[84:87]
	v_mfma_f32_16x16x32_bf16 v[80:83], v[184:187], v[208:211], v[80:83]
	v_mfma_f32_16x16x32_bf16 v[68:71], v[176:179], v[216:219], v[68:71]
	v_mfma_f32_16x16x32_bf16 v[64:67], v[184:187], v[216:219], v[64:67]
	v_mfma_f32_16x16x32_bf16 v[116:119], v[180:183], v[196:199], v[116:119]
	v_mfma_f32_16x16x32_bf16 v[112:115], v[188:191], v[196:199], v[112:115]
	v_mfma_f32_16x16x32_bf16 v[100:103], v[180:183], v[204:207], v[100:103]
	v_mfma_f32_16x16x32_bf16 v[96:99], v[188:191], v[204:207], v[96:99]
	v_mfma_f32_16x16x32_bf16 v[84:87], v[180:183], v[212:215], v[84:87]
	v_mfma_f32_16x16x32_bf16 v[80:83], v[188:191], v[212:215], v[80:83]
	v_mfma_f32_16x16x32_bf16 v[68:71], v[180:183], v[220:223], v[68:71]
	v_mfma_f32_16x16x32_bf16 v[64:67], v[188:191], v[220:223], v[64:67]
	s_barrier
; #define PG8_STAGE(bufoff, gbase, voff) do { _Pragma("unroll") for (int _i = 0; _i < 2; ++_i) \
;         __builtin_amdgcn_global_load_lds((const unsigned*)((const char*)(gbase) + (voff)[_i]), (LAS unsigned*)(lds + (bufoff) + ldsw + _i * 8192), 16, 0, 0); } while (0)
; #define PG8_LDA(dst, b, h) do { _Pragma("unroll") for (int m = 0; m < 4; ++m) _Pragma("unroll") for (int k = 0; k < 2; ++k) dst[m][k] = *(const LAS bf16x8*)(lds + PG8_SA(b, h) + aoff + m * 2048 + k * 1024); } while (0)
; #define PG8_LDB(dst, b, h) do { _Pragma("unroll") for (int n = 0; n < 2; ++n) _Pragma("unroll") for (int k = 0; k < 2; ++k) dst[n][k] = *(const LAS bf16x8*)(lds + PG8_SB(b, h) + boff + n * 2048 + k * 1024); } while (0)
; #define PG8_MMA(ai, bj, At, Bt) do { __builtin_amdgcn_s_setprio(1); _Pragma("unroll") for (int m = 0; m < 4; ++m) _Pragma("unroll") for (int n = 0; n < 2; ++n) _Pragma("unroll") for (int k = 0; k < 2; ++k) \
;         acc[ai][bj][m][n] = __builtin_amdgcn_mfma_f32_16x16x32_bf16(Bt[n][k], At[m][k], acc[ai][bj][m][n], 0, 0, 0); __builtin_amdgcn_s_setprio(0); } while (0)
; #define PG8_WAIT_V(n) asm volatile("s_waitcnt vmcnt(" #n ")" ::: "memory")
; #define PG8_WAIT_L(n) asm volatile("s_waitcnt lgkmcnt(" #n ")" ::: "memory")
; #define PG8_BAR __builtin_amdgcn_s_barrier()
; #define PG8_SCHED __builtin_amdgcn_sched_barrier(0)
; __device__ __forceinline__ void gemm_phase(LAS unsigned char* lds, const Params& p, const bf16_t* gA, const bf16_t* gBt, const int gM, const int gN, const int gK, const int epi, const int perm, bf16_t* const Hp, const int goff, const float coef) {
;     ...
;             PG8_LDB(B0, 0, 0); PG8_LDB(B1, 0, 1); PG8_SCHED; PG8_LDA(At, 0, 0); PG8_STAGE(PG8_SA(1, 1), a1 + hstep, voffA);
;             PG8_WAIT_V(8); PG8_WAIT_L(0); PG8_BAR; PG8_MMA(0, 0, At, B0); PG8_MMA(0, 1, At, B1); PG8_BAR; PG8_SCHED;
;     ...
;             PG8_LDA(At, 1, 1); PG8_STAGE(PG8_SB(1, 0), b3, voffB); PG8_STAGE(PG8_SB(1, 1), b3 + hstep, voffB); PG8_STAGE(PG8_SA(1, 0), a3, voffA);
;             PG8_WAIT_V(8); PG8_WAIT_L(0); PG8_BAR; PG8_MMA(1, 0, At, B0); PG8_MMA(1, 1, At, B1); PG8_BAR; PG8_SCHED;
	s_mov_b64 s[98:99], s[30:31]
	s_add_i32 s30, s55, s36
	s_mov_b32 m0, s30
	ds_read_b128 v[192:195], v158 offset:49152
	ds_read_b128 v[196:199], v158 offset:50176
	ds_read_b128 v[200:203], v158 offset:51200
	ds_read_b128 v[204:207], v158 offset:52224
	ds_read_b128 v[208:211], v158 offset:53248
	ds_read_b128 v[212:215], v158 offset:54272
	ds_read_b128 v[216:219], v158 offset:55296
	ds_read_b128 v[220:223], v158 offset:56320
	s_add_u32 s100, s28, 0x80
	s_addc_u32 s101, s29, 0
	global_load_lds_dwordx4 v130, s[100:101]
	s_add_i32 m0, s30, 0x2000
	s_add_u32 s28, s28, 0x80080
	s_addc_u32 s29, s29, 0
	s_add_i32 s30, s56, s36
	global_load_lds_dwordx4 v134, s[100:101]
	s_mov_b32 m0, s30
	s_nop 0
	global_load_lds_dwordx4 v130, s[28:29]
	s_add_i32 m0, s30, 0x2000
	s_nop 0
	global_load_lds_dwordx4 v134, s[28:29]
	s_mov_b32 m0, s40
	s_add_u32 s100, s98, 0xfff80080
	s_addc_u32 s101, s99, -1
	global_load_lds_dwordx4 v128, s[100:101]
	s_mov_b32 m0, s41
	s_nop 0
	global_load_lds_dwordx4 v132, s[100:101]
	s_waitcnt vmcnt(8) lgkmcnt(0)
	s_barrier
	v_mfma_f32_16x16x32_bf16 v[60:63], v[160:163], v[192:195], v[60:63]
	v_mfma_f32_16x16x32_bf16 v[56:59], v[168:171], v[192:195], v[56:59]
	v_mfma_f32_16x16x32_bf16 v[44:47], v[160:163], v[200:203], v[44:47]
	v_mfma_f32_16x16x32_bf16 v[40:43], v[168:171], v[200:203], v[40:43]
	v_mfma_f32_16x16x32_bf16 v[28:31], v[160:163], v[208:211], v[28:31]
	v_mfma_f32_16x16x32_bf16 v[24:27], v[168:171], v[208:211], v[24:27]
	v_mfma_f32_16x16x32_bf16 v[12:15], v[160:163], v[216:219], v[12:15]
	v_mfma_f32_16x16x32_bf16 v[8:11], v[168:171], v[216:219], v[8:11]
	v_mfma_f32_16x16x32_bf16 v[60:63], v[164:167], v[196:199], v[60:63]
	v_mfma_f32_16x16x32_bf16 v[56:59], v[172:175], v[196:199], v[56:59]
	v_mfma_f32_16x16x32_bf16 v[44:47], v[164:167], v[204:207], v[44:47]
	v_mfma_f32_16x16x32_bf16 v[40:43], v[172:175], v[204:207], v[40:43]
	v_mfma_f32_16x16x32_bf16 v[28:31], v[164:167], v[212:215], v[28:31]
	v_mfma_f32_16x16x32_bf16 v[24:27], v[172:175], v[212:215], v[24:27]
	v_mfma_f32_16x16x32_bf16 v[12:15], v[164:167], v[220:223], v[12:15]
	v_mfma_f32_16x16x32_bf16 v[8:11], v[172:175], v[220:223], v[8:11]
	v_mfma_f32_16x16x32_bf16 v[52:55], v[176:179], v[192:195], v[52:55]
	v_mfma_f32_16x16x32_bf16 v[48:51], v[184:187], v[192:195], v[48:51]
	v_mfma_f32_16x16x32_bf16 v[36:39], v[176:179], v[200:203], v[36:39]
	v_mfma_f32_16x16x32_bf16 v[32:35], v[184:187], v[200:203], v[32:35]
	v_mfma_f32_16x16x32_bf16 v[20:23], v[176:179], v[208:211], v[20:23]
	v_mfma_f32_16x16x32_bf16 v[16:19], v[184:187], v[208:211], v[16:19]
	v_mfma_f32_16x16x32_bf16 v[4:7], v[176:179], v[216:219], v[4:7]
	v_mfma_f32_16x16x32_bf16 v[0:3], v[184:187], v[216:219], v[0:3]
	v_mfma_f32_16x16x32_bf16 v[52:55], v[180:183], v[196:199], v[52:55]
	v_mfma_f32_16x16x32_bf16 v[48:51], v[188:191], v[196:199], v[48:51]
	v_mfma_f32_16x16x32_bf16 v[36:39], v[180:183], v[204:207], v[36:39]
	v_mfma_f32_16x16x32_bf16 v[32:35], v[188:191], v[204:207], v[32:35]
	v_mfma_f32_16x16x32_bf16 v[20:23], v[180:183], v[212:215], v[20:23]
	v_mfma_f32_16x16x32_bf16 v[16:19], v[188:191], v[212:215], v[16:19]
	v_mfma_f32_16x16x32_bf16 v[4:7], v[180:183], v[220:223], v[4:7]
	v_mfma_f32_16x16x32_bf16 v[0:3], v[188:191], v[220:223], v[0:3]
	s_barrier
	s_add_u32 s26, s26, 0x100
	s_addc_u32 s27, s27, 0
	s_add_u32 s52, s52, 0x100
	s_addc_u32 s53, s53, 0
	s_cmp_ge_u32 s54, s50
	s_mov_b32 s30, s54
	s_cbranch_scc1 .Lpeel_exit_4
.LBB0_1737:
	ds_read_b128 v[160:163], v156
	ds_read_b128 v[164:167], v156 offset:1024
	ds_read_b128 v[168:171], v156 offset:2048
	ds_read_b128 v[172:175], v156 offset:3072
	ds_read_b128 v[176:179], v157
	ds_read_b128 v[180:183], v157 offset:1024
	ds_read_b128 v[184:187], v157 offset:2048
	ds_read_b128 v[188:191], v157 offset:3072
	s_add_i32 s54, s30, 2
	s_add_u32 s28, s26, 0xfff80080
	s_addc_u32 s29, s27, -1
	s_cmp_eq_u32 s51, s30
	s_cselect_b32 s30, s48, s28
	s_cselect_b32 s31, s13, s29
	s_cselect_b32 s29, s15, s53
	s_cselect_b32 s28, s49, s52
	s_add_i32 m0, s23, 0xc000
	ds_read_b128 v[192:195], v158
	ds_read_b128 v[196:199], v158 offset:1024
	ds_read_b128 v[200:203], v158 offset:2048
	ds_read_b128 v[204:207], v158 offset:3072
	ds_read_b128 v[208:211], v158 offset:4096
	ds_read_b128 v[212:215], v158 offset:5120
	ds_read_b128 v[216:219], v158 offset:6144
	ds_read_b128 v[220:223], v158 offset:7168
	global_load_lds_dwordx4 v136, s[26:27]
	s_add_i32 m0, s23, 0xe000
	s_nop 0
	global_load_lds_dwordx4 v138, s[26:27]
	s_waitcnt vmcnt(8) lgkmcnt(0)
	s_barrier
	v_mfma_f32_16x16x32_bf16 v[124:127], v[160:163], v[192:195], v[124:127]
	v_mfma_f32_16x16x32_bf16 v[120:123], v[168:171], v[192:195], v[120:123]
	v_mfma_f32_16x16x32_bf16 v[108:111], v[160:163], v[200:203], v[108:111]
	v_mfma_f32_16x16x32_bf16 v[104:107], v[168:171], v[200:203], v[104:107]
	v_mfma_f32_16x16x32_bf16 v[92:95], v[160:163], v[208:211], v[92:95]
	v_mfma_f32_16x16x32_bf16 v[88:91], v[168:171], v[208:211], v[88:91]
	v_mfma_f32_16x16x32_bf16 v[76:79], v[160:163], v[216:219], v[76:79]
	v_mfma_f32_16x16x32_bf16 v[72:75], v[168:171], v[216:219], v[72:75]
	v_mfma_f32_16x16x32_bf16 v[124:127], v[164:167], v[196:199], v[124:127]
	v_mfma_f32_16x16x32_bf16 v[120:123], v[172:175], v[196:199], v[120:123]
	v_mfma_f32_16x16x32_bf16 v[108:111], v[164:167], v[204:207], v[108:111]
	v_mfma_f32_16x16x32_bf16 v[104:107], v[172:175], v[204:207], v[104:107]
	v_mfma_f32_16x16x32_bf16 v[92:95], v[164:167], v[212:215], v[92:95]
	v_mfma_f32_16x16x32_bf16 v[88:91], v[172:175], v[212:215], v[88:91]
	v_mfma_f32_16x16x32_bf16 v[76:79], v[164:167], v[220:223], v[76:79]
	v_mfma_f32_16x16x32_bf16 v[72:75], v[172:175], v[220:223], v[72:75]
	v_mfma_f32_16x16x32_bf16 v[116:119], v[176:179], v[192:195], v[116:119]
	v_mfma_f32_16x16x32_bf16 v[112:115], v[184:187], v[192:195], v[112:115]
	v_mfma_f32_16x16x32_bf16 v[100:103], v[176:179], v[200:203], v[100:103]
	v_mfma_f32_16x16x32_bf16 v[96:99], v[184:187], v[200:203], v[96:99]
	v_mfma_f32_16x16x32_bf16 v[84:87], v[176:179], v[208:211], v[84:87]
	v_mfma_f32_16x16x32_bf16 v[80:83], v[184:187], v[208:211], v[80:83]
	v_mfma_f32_16x16x32_bf16 v[68:71], v[176:179], v[216:219], v[68:71]
	v_mfma_f32_16x16x32_bf16 v[64:67], v[184:187], v[216:219], v[64:67]
	v_mfma_f32_16x16x32_bf16 v[116:119], v[180:183], v[196:199], v[116:119]
	v_mfma_f32_16x16x32_bf16 v[112:115], v[188:191], v[196:199], v[112:115]
	v_mfma_f32_16x16x32_bf16 v[100:103], v[180:183], v[204:207], v[100:103]
	v_mfma_f32_16x16x32_bf16 v[96:99], v[188:191], v[204:207], v[96:99]
	v_mfma_f32_16x16x32_bf16 v[84:87], v[180:183], v[212:215], v[84:87]
	v_mfma_f32_16x16x32_bf16 v[80:83], v[188:191], v[212:215], v[80:83]
	v_mfma_f32_16x16x32_bf16 v[68:71], v[180:183], v[220:223], v[68:71]
	v_mfma_f32_16x16x32_bf16 v[64:67], v[188:191], v[220:223], v[64:67]
	s_barrier
; #define PG8_STAGE(bufoff, gbase, voff) do { _Pragma("unroll") for (int _i = 0; _i < 2; ++_i) \
;         __builtin_amdgcn_global_load_lds((const unsigned*)((const char*)(gbase) + (voff)[_i]), (LAS unsigned*)(lds + (bufoff) + ldsw + _i * 8192), 16, 0, 0); } while (0)
; #define PG8_LDA(dst, b, h) do { _Pragma("unroll") for (int m = 0; m < 4; ++m) _Pragma("unroll") for (int k = 0; k < 2; ++k) dst[m][k] = *(const LAS bf16x8*)(lds + PG8_SA(b, h) + aoff + m * 2048 + k * 1024); } while (0)
; #define PG8_LDB(dst, b, h) do { _Pragma("unroll") for (int n = 0; n < 2; ++n) _Pragma("unroll") for (int k = 0; k < 2; ++k) dst[n][k] = *(const LAS bf16x8*)(lds + PG8_SB(b, h) + boff + n * 2048 + k * 1024); } while (0)
; #define PG8_MMA(ai, bj, At, Bt) do { __builtin_amdgcn_s_setprio(1); _Pragma("unroll") for (int m = 0; m < 4; ++m) _Pragma("unroll") for (int n = 0; n < 2; ++n) _Pragma("unroll") for (int k = 0; k < 2; ++k) \
;         acc[ai][bj][m][n] = __builtin_amdgcn_mfma_f32_16x16x32_bf16(Bt[n][k], At[m][k], acc[ai][bj][m][n], 0, 0, 0); __builtin_amdgcn_s_setprio(0); } while (0)
; #define PG8_WAIT_V(n) asm volatile("s_waitcnt vmcnt(" #n ")" ::: "memory")
; #define PG8_WAIT_L(n) asm volatile("s_waitcnt lgkmcnt(" #n ")" ::: "memory")
; #define PG8_BAR __builtin_amdgcn_s_barrier()
; #define PG8_SCHED __builtin_amdgcn_sched_barrier(0)
; __device__ __forceinline__ void gemm_phase(LAS unsigned char* lds, const Params& p, const bf16_t* gA, const bf16_t* gBt, const int gM, const int gN, const int gK, const int epi, const int perm, bf16_t* const Hp, const int goff, const float coef) {
;     ...
;             PG8_LDA(At, 0, 1); PG8_STAGE(PG8_SB(0, 0), b2, voffB); PG8_STAGE(PG8_SB(0, 1), b2 + hstep, voffB); PG8_STAGE(PG8_SA(0, 0), a2, voffA);
;             PG8_WAIT_V(8); PG8_WAIT_L(0); PG8_BAR; PG8_MMA(1, 0, At, B0); PG8_MMA(1, 1, At, B1); PG8_BAR; PG8_SCHED;
;             PG8_LDB(B0, 1, 0); PG8_LDB(B1, 1, 1); PG8_SCHED; PG8_LDA(At, 1, 0); PG8_STAGE(PG8_SA(0, 1), a2 + hstep, voffA);
;             PG8_WAIT_V(8); PG8_WAIT_L(0); PG8_BAR; PG8_MMA(0, 0, At, B0); PG8_MMA(0, 1, At, B1); PG8_BAR; PG8_SCHED;
	s_add_i32 s55, s44, s36
	s_mov_b32 m0, s55
	ds_read_b128 v[192:195], v158 offset:16384
	ds_read_b128 v[196:199], v158 offset:17408
	ds_read_b128 v[200:203], v158 offset:18432
	ds_read_b128 v[204:207], v158 offset:19456
	ds_read_b128 v[208:211], v158 offset:20480
	ds_read_b128 v[212:215], v158 offset:21504
	ds_read_b128 v[216:219], v158 offset:22528
	ds_read_b128 v[220:223], v158 offset:23552
	global_load_lds_dwordx4 v130, s[28:29]
	s_add_i32 m0, s55, 0x2000
	s_add_u32 s56, s28, 0x80000
	s_addc_u32 s57, s29, 0
	s_add_i32 s55, s45, s36
	global_load_lds_dwordx4 v134, s[28:29]
	s_mov_b32 m0, s55
	s_nop 0
	global_load_lds_dwordx4 v130, s[56:57]
	s_add_i32 m0, s55, 0x2000
	s_nop 0
	global_load_lds_dwordx4 v134, s[56:57]
	s_mov_b32 m0, s23
	s_nop 0
	global_load_lds_dwordx4 v128, s[30:31]
	s_mov_b32 m0, s25
	s_nop 0
	global_load_lds_dwordx4 v132, s[30:31]
	s_waitcnt vmcnt(8) lgkmcnt(0)
	s_barrier
	v_mfma_f32_16x16x32_bf16 v[60:63], v[160:163], v[192:195], v[60:63]
	v_mfma_f32_16x16x32_bf16 v[56:59], v[168:171], v[192:195], v[56:59]
	v_mfma_f32_16x16x32_bf16 v[44:47], v[160:163], v[200:203], v[44:47]
	v_mfma_f32_16x16x32_bf16 v[40:43], v[168:171], v[200:203], v[40:43]
	v_mfma_f32_16x16x32_bf16 v[28:31], v[160:163], v[208:211], v[28:31]
	v_mfma_f32_16x16x32_bf16 v[24:27], v[168:171], v[208:211], v[24:27]
	v_mfma_f32_16x16x32_bf16 v[12:15], v[160:163], v[216:219], v[12:15]
	v_mfma_f32_16x16x32_bf16 v[8:11], v[168:171], v[216:219], v[8:11]
	v_mfma_f32_16x16x32_bf16 v[60:63], v[164:167], v[196:199], v[60:63]
	v_mfma_f32_16x16x32_bf16 v[56:59], v[172:175], v[196:199], v[56:59]
	v_mfma_f32_16x16x32_bf16 v[44:47], v[164:167], v[204:207], v[44:47]
	v_mfma_f32_16x16x32_bf16 v[40:43], v[172:175], v[204:207], v[40:43]
	v_mfma_f32_16x16x32_bf16 v[28:31], v[164:167], v[212:215], v[28:31]
	v_mfma_f32_16x16x32_bf16 v[24:27], v[172:175], v[212:215], v[24:27]
	v_mfma_f32_16x16x32_bf16 v[12:15], v[164:167], v[220:223], v[12:15]
	v_mfma_f32_16x16x32_bf16 v[8:11], v[172:175], v[220:223], v[8:11]
	v_mfma_f32_16x16x32_bf16 v[52:55], v[176:179], v[192:195], v[52:55]
	v_mfma_f32_16x16x32_bf16 v[48:51], v[184:187], v[192:195], v[48:51]
	v_mfma_f32_16x16x32_bf16 v[36:39], v[176:179], v[200:203], v[36:39]
	v_mfma_f32_16x16x32_bf16 v[32:35], v[184:187], v[200:203], v[32:35]
	v_mfma_f32_16x16x32_bf16 v[20:23], v[176:179], v[208:211], v[20:23]
	v_mfma_f32_16x16x32_bf16 v[16:19], v[184:187], v[208:211], v[16:19]
	v_mfma_f32_16x16x32_bf16 v[4:7], v[176:179], v[216:219], v[4:7]
	v_mfma_f32_16x16x32_bf16 v[0:3], v[184:187], v[216:219], v[0:3]
	v_mfma_f32_16x16x32_bf16 v[52:55], v[180:183], v[196:199], v[52:55]
	v_mfma_f32_16x16x32_bf16 v[48:51], v[188:191], v[196:199], v[48:51]
	v_mfma_f32_16x16x32_bf16 v[36:39], v[180:183], v[204:207], v[36:39]
	v_mfma_f32_16x16x32_bf16 v[32:35], v[188:191], v[204:207], v[32:35]
	v_mfma_f32_16x16x32_bf16 v[20:23], v[180:183], v[212:215], v[20:23]
	v_mfma_f32_16x16x32_bf16 v[16:19], v[188:191], v[212:215], v[16:19]
	v_mfma_f32_16x16x32_bf16 v[4:7], v[180:183], v[220:223], v[4:7]
	v_mfma_f32_16x16x32_bf16 v[0:3], v[188:191], v[220:223], v[0:3]
	s_barrier
	s_add_i32 s55, 0, 0x18000
	s_add_i32 s56, 0, 0x1c000
	ds_read_b128 v[160:163], v224
	ds_read_b128 v[164:167], v224 offset:1024
	ds_read_b128 v[168:171], v224 offset:2048
	ds_read_b128 v[172:175], v224 offset:3072
	ds_read_b128 v[176:179], v225
	ds_read_b128 v[180:183], v225 offset:1024
	ds_read_b128 v[184:187], v225 offset:2048
	ds_read_b128 v[188:191], v225 offset:3072
	s_add_u32 s30, s30, 0x80000
	s_addc_u32 s31, s31, 0
	s_mov_b32 m0, s37
	ds_read_b128 v[192:195], v158 offset:32768
	ds_read_b128 v[196:199], v158 offset:33792
	ds_read_b128 v[200:203], v158 offset:34816
	ds_read_b128 v[204:207], v158 offset:35840
	ds_read_b128 v[208:211], v158 offset:36864
	ds_read_b128 v[212:215], v158 offset:37888
	ds_read_b128 v[216:219], v158 offset:38912
	ds_read_b128 v[220:223], v158 offset:39936
	global_load_lds_dwordx4 v128, s[30:31]
	s_mov_b32 m0, s38
	s_nop 0
	global_load_lds_dwordx4 v132, s[30:31]
	s_waitcnt vmcnt(8) lgkmcnt(0)
	s_barrier
; #define PG8_STAGE(bufoff, gbase, voff) do { _Pragma("unroll") for (int _i = 0; _i < 2; ++_i) \
;         __builtin_amdgcn_global_load_lds((const unsigned*)((const char*)(gbase) + (voff)[_i]), (LAS unsigned*)(lds + (bufoff) + ldsw + _i * 8192), 16, 0, 0); } while (0)
; #define PG8_LDA(dst, b, h) do { _Pragma("unroll") for (int m = 0; m < 4; ++m) _Pragma("unroll") for (int k = 0; k < 2; ++k) dst[m][k] = *(const LAS bf16x8*)(lds + PG8_SA(b, h) + aoff + m * 2048 + k * 1024); } while (0)
; #define PG8_MMA(ai, bj, At, Bt) do { __builtin_amdgcn_s_setprio(1); _Pragma("unroll") for (int m = 0; m < 4; ++m) _Pragma("unroll") for (int n = 0; n < 2; ++n) _Pragma("unroll") for (int k = 0; k < 2; ++k) \
;         acc[ai][bj][m][n] = __builtin_amdgcn_mfma_f32_16x16x32_bf16(Bt[n][k], At[m][k], acc[ai][bj][m][n], 0, 0, 0); __builtin_amdgcn_s_setprio(0); } while (0)
; #define PG8_WAIT_V(n) asm volatile("s_waitcnt vmcnt(" #n ")" ::: "memory")
; #define PG8_WAIT_L(n) asm volatile("s_waitcnt lgkmcnt(" #n ")" ::: "memory")
; #define PG8_BAR __builtin_amdgcn_s_barrier()
; #define PG8_SCHED __builtin_amdgcn_sched_barrier(0)
; __device__ __forceinline__ void gemm_phase(LAS unsigned char* lds, const Params& p, const bf16_t* gA, const bf16_t* gBt, const int gM, const int gN, const int gK, const int epi, const int perm, bf16_t* const Hp, const int goff, const float coef) {
;     ...
;             PG8_WAIT_V(8); PG8_WAIT_L(0); PG8_BAR; PG8_MMA(0, 0, At, B0); PG8_MMA(0, 1, At, B1); PG8_BAR; PG8_SCHED;
;             PG8_LDA(At, 1, 1); PG8_STAGE(PG8_SB(1, 0), b3, voffB); PG8_STAGE(PG8_SB(1, 1), b3 + hstep, voffB); PG8_STAGE(PG8_SA(1, 0), a3, voffA);
;             PG8_WAIT_V(8); PG8_WAIT_L(0); PG8_BAR; PG8_MMA(1, 0, At, B0); PG8_MMA(1, 1, At, B1); PG8_BAR; PG8_SCHED;
;         }
	v_mfma_f32_16x16x32_bf16 v[124:127], v[160:163], v[192:195], v[124:127]
	v_mfma_f32_16x16x32_bf16 v[120:123], v[168:171], v[192:195], v[120:123]
	v_mfma_f32_16x16x32_bf16 v[108:111], v[160:163], v[200:203], v[108:111]
	v_mfma_f32_16x16x32_bf16 v[104:107], v[168:171], v[200:203], v[104:107]
	v_mfma_f32_16x16x32_bf16 v[92:95], v[160:163], v[208:211], v[92:95]
	v_mfma_f32_16x16x32_bf16 v[88:91], v[168:171], v[208:211], v[88:91]
	v_mfma_f32_16x16x32_bf16 v[76:79], v[160:163], v[216:219], v[76:79]
	v_mfma_f32_16x16x32_bf16 v[72:75], v[168:171], v[216:219], v[72:75]
	v_mfma_f32_16x16x32_bf16 v[124:127], v[164:167], v[196:199], v[124:127]
	v_mfma_f32_16x16x32_bf16 v[120:123], v[172:175], v[196:199], v[120:123]
	v_mfma_f32_16x16x32_bf16 v[108:111], v[164:167], v[204:207], v[108:111]
	v_mfma_f32_16x16x32_bf16 v[104:107], v[172:175], v[204:207], v[104:107]
	v_mfma_f32_16x16x32_bf16 v[92:95], v[164:167], v[212:215], v[92:95]
	v_mfma_f32_16x16x32_bf16 v[88:91], v[172:175], v[212:215], v[88:91]
	v_mfma_f32_16x16x32_bf16 v[76:79], v[164:167], v[220:223], v[76:79]
	v_mfma_f32_16x16x32_bf16 v[72:75], v[172:175], v[220:223], v[72:75]
	v_mfma_f32_16x16x32_bf16 v[116:119], v[176:179], v[192:195], v[116:119]
	v_mfma_f32_16x16x32_bf16 v[112:115], v[184:187], v[192:195], v[112:115]
	v_mfma_f32_16x16x32_bf16 v[100:103], v[176:179], v[200:203], v[100:103]
	v_mfma_f32_16x16x32_bf16 v[96:99], v[184:187], v[200:203], v[96:99]
	v_mfma_f32_16x16x32_bf16 v[84:87], v[176:179], v[208:211], v[84:87]
	v_mfma_f32_16x16x32_bf16 v[80:83], v[184:187], v[208:211], v[80:83]
	v_mfma_f32_16x16x32_bf16 v[68:71], v[176:179], v[216:219], v[68:71]
	v_mfma_f32_16x16x32_bf16 v[64:67], v[184:187], v[216:219], v[64:67]
	v_mfma_f32_16x16x32_bf16 v[116:119], v[180:183], v[196:199], v[116:119]
	v_mfma_f32_16x16x32_bf16 v[112:115], v[188:191], v[196:199], v[112:115]
	v_mfma_f32_16x16x32_bf16 v[100:103], v[180:183], v[204:207], v[100:103]
	v_mfma_f32_16x16x32_bf16 v[96:99], v[188:191], v[204:207], v[96:99]
	v_mfma_f32_16x16x32_bf16 v[84:87], v[180:183], v[212:215], v[84:87]
	v_mfma_f32_16x16x32_bf16 v[80:83], v[188:191], v[212:215], v[80:83]
	v_mfma_f32_16x16x32_bf16 v[68:71], v[180:183], v[220:223], v[68:71]
	v_mfma_f32_16x16x32_bf16 v[64:67], v[188:191], v[220:223], v[64:67]
	s_barrier
	s_mov_b64 s[98:99], s[30:31]
	s_add_i32 s30, s55, s36
	s_mov_b32 m0, s30
	ds_read_b128 v[192:195], v158 offset:49152
	ds_read_b128 v[196:199], v158 offset:50176
	ds_read_b128 v[200:203], v158 offset:51200
	ds_read_b128 v[204:207], v158 offset:52224
	ds_read_b128 v[208:211], v158 offset:53248
	ds_read_b128 v[212:215], v158 offset:54272
	ds_read_b128 v[216:219], v158 offset:55296
	ds_read_b128 v[220:223], v158 offset:56320
	s_add_u32 s100, s28, 0x80
	s_addc_u32 s101, s29, 0
	global_load_lds_dwordx4 v130, s[100:101]
	s_add_i32 m0, s30, 0x2000
	s_add_u32 s28, s28, 0x80080
	s_addc_u32 s29, s29, 0
	s_add_i32 s30, s56, s36
	global_load_lds_dwordx4 v134, s[100:101]
	s_mov_b32 m0, s30
	s_nop 0
	global_load_lds_dwordx4 v130, s[28:29]
	s_add_i32 m0, s30, 0x2000
	s_nop 0
	global_load_lds_dwordx4 v134, s[28:29]
	s_mov_b32 m0, s40
	s_add_u32 s100, s98, 0xfff80080
	s_addc_u32 s101, s99, -1
	global_load_lds_dwordx4 v128, s[100:101]
	s_mov_b32 m0, s41
	s_nop 0
	global_load_lds_dwordx4 v132, s[100:101]
	s_waitcnt vmcnt(8) lgkmcnt(0)
	s_barrier
	v_mfma_f32_16x16x32_bf16 v[60:63], v[160:163], v[192:195], v[60:63]
	v_mfma_f32_16x16x32_bf16 v[56:59], v[168:171], v[192:195], v[56:59]
	v_mfma_f32_16x16x32_bf16 v[44:47], v[160:163], v[200:203], v[44:47]
	v_mfma_f32_16x16x32_bf16 v[40:43], v[168:171], v[200:203], v[40:43]
	v_mfma_f32_16x16x32_bf16 v[28:31], v[160:163], v[208:211], v[28:31]
	v_mfma_f32_16x16x32_bf16 v[24:27], v[168:171], v[208:211], v[24:27]
	v_mfma_f32_16x16x32_bf16 v[12:15], v[160:163], v[216:219], v[12:15]
	v_mfma_f32_16x16x32_bf16 v[8:11], v[168:171], v[216:219], v[8:11]
	v_mfma_f32_16x16x32_bf16 v[60:63], v[164:167], v[196:199], v[60:63]
	v_mfma_f32_16x16x32_bf16 v[56:59], v[172:175], v[196:199], v[56:59]
	v_mfma_f32_16x16x32_bf16 v[44:47], v[164:167], v[204:207], v[44:47]
	v_mfma_f32_16x16x32_bf16 v[40:43], v[172:175], v[204:207], v[40:43]
	v_mfma_f32_16x16x32_bf16 v[28:31], v[164:167], v[212:215], v[28:31]
	v_mfma_f32_16x16x32_bf16 v[24:27], v[172:175], v[212:215], v[24:27]
	v_mfma_f32_16x16x32_bf16 v[12:15], v[164:167], v[220:223], v[12:15]
	v_mfma_f32_16x16x32_bf16 v[8:11], v[172:175], v[220:223], v[8:11]
	v_mfma_f32_16x16x32_bf16 v[52:55], v[176:179], v[192:195], v[52:55]
	v_mfma_f32_16x16x32_bf16 v[48:51], v[184:187], v[192:195], v[48:51]
	v_mfma_f32_16x16x32_bf16 v[36:39], v[176:179], v[200:203], v[36:39]
	v_mfma_f32_16x16x32_bf16 v[32:35], v[184:187], v[200:203], v[32:35]
	v_mfma_f32_16x16x32_bf16 v[20:23], v[176:179], v[208:211], v[20:23]
	v_mfma_f32_16x16x32_bf16 v[16:19], v[184:187], v[208:211], v[16:19]
	v_mfma_f32_16x16x32_bf16 v[4:7], v[176:179], v[216:219], v[4:7]
	v_mfma_f32_16x16x32_bf16 v[0:3], v[184:187], v[216:219], v[0:3]
	v_mfma_f32_16x16x32_bf16 v[52:55], v[180:183], v[196:199], v[52:55]
	v_mfma_f32_16x16x32_bf16 v[48:51], v[188:191], v[196:199], v[48:51]
	v_mfma_f32_16x16x32_bf16 v[36:39], v[180:183], v[204:207], v[36:39]
	v_mfma_f32_16x16x32_bf16 v[32:35], v[188:191], v[204:207], v[32:35]
	v_mfma_f32_16x16x32_bf16 v[20:23], v[180:183], v[212:215], v[20:23]
	v_mfma_f32_16x16x32_bf16 v[16:19], v[188:191], v[212:215], v[16:19]
	v_mfma_f32_16x16x32_bf16 v[4:7], v[180:183], v[220:223], v[4:7]
	v_mfma_f32_16x16x32_bf16 v[0:3], v[188:191], v[220:223], v[0:3]
	s_barrier
	s_add_u32 s26, s26, 0x100
	s_addc_u32 s27, s27, 0
	s_add_u32 s52, s52, 0x100
	s_addc_u32 s53, s53, 0
	s_cmp_ge_u32 s54, s50
	s_mov_b32 s30, s54
	s_cbranch_scc0 .LBB0_1737

; #define PG8_STAGE(bufoff, gbase, voff) do { _Pragma("unroll") for (int _i = 0; _i < 2; ++_i) \
;         __builtin_amdgcn_global_load_lds((const unsigned*)((const char*)(gbase) + (voff)[_i]), (LAS unsigned*)(lds + (bufoff) + ldsw + _i * 8192), 16, 0, 0); } while (0)
; #define PG8_LDA(dst, b, h) do { _Pragma("unroll") for (int m = 0; m < 4; ++m) _Pragma("unroll") for (int k = 0; k < 2; ++k) dst[m][k] = *(const LAS bf16x8*)(lds + PG8_SA(b, h) + aoff + m * 2048 + k * 1024); } while (0)
; #define PG8_LDB(dst, b, h) do { _Pragma("unroll") for (int n = 0; n < 2; ++n) _Pragma("unroll") for (int k = 0; k < 2; ++k) dst[n][k] = *(const LAS bf16x8*)(lds + PG8_SB(b, h) + boff + n * 2048 + k * 1024); } while (0)
; #define PG8_WAIT_V(n) asm volatile("s_waitcnt vmcnt(" #n ")" ::: "memory")
; #define PG8_WAIT_L(n) asm volatile("s_waitcnt lgkmcnt(" #n ")" ::: "memory")
; #define PG8_BAR __builtin_amdgcn_s_barrier()
; #define PG8_SCHED __builtin_amdgcn_sched_barrier(0)
; __device__ __forceinline__ void gemm_phase(LAS unsigned char* lds, const Params& p, const bf16_t* gA, const bf16_t* gBt, const int gM, const int gN, const int gK, const int epi, const int perm, bf16_t* const Hp, const int goff, const float coef) {
;     ...
;         const int nt = cur.ks >= 0 ? ntf / 4 : ntf;
;         for (int t = 0; t < nt; t += 2) {
;             const bool last = (t == nt - 2);
;             const char* a1 = cA + (size_t)(t + 1) * kstep;
;             const char* a2 = last ? nA : cA + (size_t)(t + 2) * kstep; const char* b2 = last ? nB : cB + (size_t)(t + 2) * kstep;
;             const char* a3 = a2 + kstep; const char* b3 = b2 + kstep;
;             PG8_LDB(B0, 0, 0); PG8_LDB(B1, 0, 1); PG8_SCHED; PG8_LDA(At, 0, 0); PG8_STAGE(PG8_SA(1, 1), a1 + hstep, voffA);
;             PG8_WAIT_V(8); PG8_WAIT_L(0); PG8_BAR; PG8_MMA(0, 0, At, B0); PG8_MMA(0, 1, At, B1); PG8_BAR; PG8_SCHED;
;             PG8_LDA(At, 0, 1); PG8_STAGE(PG8_SB(0, 0), b2, voffB); PG8_STAGE(PG8_SB(0, 1), b2 + hstep, voffB); PG8_STAGE(PG8_SA(0, 0), a2, voffA);
;             PG8_WAIT_V(8); PG8_WAIT_L(0); PG8_BAR; PG8_MMA(1, 0, At, B0); PG8_MMA(1, 1, At, B1); PG8_BAR; PG8_SCHED;
;             PG8_LDB(B0, 1, 0); PG8_LDB(B1, 1, 1); PG8_SCHED; PG8_LDA(At, 1, 0); PG8_STAGE(PG8_SA(0, 1), a2 + hstep, voffA);
;             PG8_WAIT_V(8); PG8_WAIT_L(0); PG8_BAR; PG8_MMA(0, 0, At, B0); PG8_MMA(0, 1, At, B1); PG8_BAR; PG8_SCHED;
.LBB0_1826:
	s_cmp_gt_i32 s6, -1
	s_cselect_b64 s[4:5], -1, 0
	s_and_b64 s[22:23], s[4:5], exec
	s_cselect_b32 s50, 22, 0x58
	s_add_i32 s51, s50, -2
	s_add_u32 s18, s18, 0x160080
	s_addc_u32 s19, s19, 0
	s_add_u32 s52, s20, 0x100
	s_addc_u32 s53, s21, 0
	s_mov_b32 s20, 0
	v_add_u32_e32 v222, 0x18000, v157
	v_add_u32_e32 v223, 0x1c000, v157
	ds_read_b128 v[144:147], v166
	ds_read_b128 v[148:151], v166 offset:1024
	ds_read_b128 v[152:155], v166 offset:2048
	ds_read_b128 v[170:173], v166 offset:3072
	ds_read_b128 v[174:177], v167
	ds_read_b128 v[178:181], v167 offset:1024
	ds_read_b128 v[182:185], v167 offset:2048
	ds_read_b128 v[186:189], v167 offset:3072
	s_add_i32 s54, s20, 2
	s_add_u32 s21, s18, 0xffea0080
	s_addc_u32 s22, s19, -1
	s_cmp_eq_u32 s51, s20
	s_cselect_b32 s20, s16, s52
	s_cselect_b32 s23, s15, s22
	s_cselect_b32 s22, s14, s21
	s_cselect_b32 s21, s17, s53
	s_add_i32 m0, s28, 0xc000
	ds_read_b128 v[190:193], v168
	ds_read_b128 v[194:197], v168 offset:1024
	ds_read_b128 v[198:201], v168 offset:2048
	ds_read_b128 v[202:205], v168 offset:3072
	ds_read_b128 v[206:209], v168 offset:4096
	ds_read_b128 v[210:213], v168 offset:5120
	ds_read_b128 v[214:217], v168 offset:6144
	ds_read_b128 v[218:221], v168 offset:7168
	global_load_lds_dwordx4 v136, s[18:19]
	s_add_i32 m0, s28, 0xe000
	s_nop 0
	global_load_lds_dwordx4 v138, s[18:19]
	s_waitcnt vmcnt(8) lgkmcnt(0)
	s_barrier
	v_mfma_f32_16x16x32_bf16 v[124:127], v[144:147], v[190:193], 0
	v_mfma_f32_16x16x32_bf16 v[120:123], v[152:155], v[190:193], 0
	v_mfma_f32_16x16x32_bf16 v[116:119], v[144:147], v[198:201], 0
	v_mfma_f32_16x16x32_bf16 v[112:115], v[152:155], v[198:201], 0
	v_mfma_f32_16x16x32_bf16 v[108:111], v[144:147], v[206:209], 0
	v_mfma_f32_16x16x32_bf16 v[104:107], v[152:155], v[206:209], 0
	v_mfma_f32_16x16x32_bf16 v[100:103], v[144:147], v[214:217], 0
	v_mfma_f32_16x16x32_bf16 v[96:99], v[152:155], v[214:217], 0
	v_mfma_f32_16x16x32_bf16 v[124:127], v[148:151], v[194:197], v[124:127]
	v_mfma_f32_16x16x32_bf16 v[120:123], v[170:173], v[194:197], v[120:123]
	v_mfma_f32_16x16x32_bf16 v[116:119], v[148:151], v[202:205], v[116:119]
	v_mfma_f32_16x16x32_bf16 v[112:115], v[170:173], v[202:205], v[112:115]
	v_mfma_f32_16x16x32_bf16 v[108:111], v[148:151], v[210:213], v[108:111]
	v_mfma_f32_16x16x32_bf16 v[104:107], v[170:173], v[210:213], v[104:107]
	v_mfma_f32_16x16x32_bf16 v[100:103], v[148:151], v[218:221], v[100:103]
	v_mfma_f32_16x16x32_bf16 v[96:99], v[170:173], v[218:221], v[96:99]
	v_mfma_f32_16x16x32_bf16 v[68:71], v[174:177], v[190:193], 0
	v_mfma_f32_16x16x32_bf16 v[60:63], v[182:185], v[190:193], 0
	v_mfma_f32_16x16x32_bf16 v[52:55], v[174:177], v[198:201], 0
	v_mfma_f32_16x16x32_bf16 v[48:51], v[182:185], v[198:201], 0
	v_mfma_f32_16x16x32_bf16 v[44:47], v[174:177], v[206:209], 0
	v_mfma_f32_16x16x32_bf16 v[40:43], v[182:185], v[206:209], 0
	v_mfma_f32_16x16x32_bf16 v[36:39], v[174:177], v[214:217], 0
	v_mfma_f32_16x16x32_bf16 v[32:35], v[182:185], v[214:217], 0
	v_mfma_f32_16x16x32_bf16 v[68:71], v[178:181], v[194:197], v[68:71]
	v_mfma_f32_16x16x32_bf16 v[60:63], v[186:189], v[194:197], v[60:63]
	v_mfma_f32_16x16x32_bf16 v[52:55], v[178:181], v[202:205], v[52:55]
	v_mfma_f32_16x16x32_bf16 v[48:51], v[186:189], v[202:205], v[48:51]
	v_mfma_f32_16x16x32_bf16 v[44:47], v[178:181], v[210:213], v[44:47]
	v_mfma_f32_16x16x32_bf16 v[40:43], v[186:189], v[210:213], v[40:43]
	v_mfma_f32_16x16x32_bf16 v[36:39], v[178:181], v[218:221], v[36:39]
	v_mfma_f32_16x16x32_bf16 v[32:35], v[186:189], v[218:221], v[32:35]
	s_barrier
	s_add_i32 s55, s42, s27
	s_mov_b32 m0, s55
	ds_read_b128 v[190:193], v168 offset:16384
	ds_read_b128 v[194:197], v168 offset:17408
	ds_read_b128 v[198:201], v168 offset:18432
	ds_read_b128 v[202:205], v168 offset:19456
	ds_read_b128 v[206:209], v168 offset:20480
	ds_read_b128 v[210:213], v168 offset:21504
	ds_read_b128 v[214:217], v168 offset:22528
	ds_read_b128 v[218:221], v168 offset:23552
	global_load_lds_dwordx4 v130, s[20:21]
	s_add_i32 m0, s55, 0x2000
	s_add_u32 s56, s20, 0x160000
	s_addc_u32 s57, s21, 0
	s_add_i32 s55, s43, s27
	global_load_lds_dwordx4 v134, s[20:21]
	s_mov_b32 m0, s55
	s_nop 0
	global_load_lds_dwordx4 v130, s[56:57]
	s_add_i32 m0, s55, 0x2000
	s_nop 0
	global_load_lds_dwordx4 v134, s[56:57]
	s_mov_b32 m0, s28
	s_nop 0
	global_load_lds_dwordx4 v128, s[22:23]
	s_mov_b32 m0, s29
	s_nop 0
	global_load_lds_dwordx4 v132, s[22:23]
	s_waitcnt vmcnt(8) lgkmcnt(0)
	s_barrier
	v_mfma_f32_16x16x32_bf16 v[92:95], v[144:147], v[190:193], 0
	v_mfma_f32_16x16x32_bf16 v[88:91], v[152:155], v[190:193], 0
	v_mfma_f32_16x16x32_bf16 v[84:87], v[144:147], v[198:201], 0
	v_mfma_f32_16x16x32_bf16 v[80:83], v[152:155], v[198:201], 0
	v_mfma_f32_16x16x32_bf16 v[76:79], v[144:147], v[206:209], 0
	v_mfma_f32_16x16x32_bf16 v[72:75], v[152:155], v[206:209], 0
	v_mfma_f32_16x16x32_bf16 v[64:67], v[144:147], v[214:217], 0
	v_mfma_f32_16x16x32_bf16 v[56:59], v[152:155], v[214:217], 0
	v_mfma_f32_16x16x32_bf16 v[92:95], v[148:151], v[194:197], v[92:95]
	v_mfma_f32_16x16x32_bf16 v[88:91], v[170:173], v[194:197], v[88:91]
	v_mfma_f32_16x16x32_bf16 v[84:87], v[148:151], v[202:205], v[84:87]
	v_mfma_f32_16x16x32_bf16 v[80:83], v[170:173], v[202:205], v[80:83]
	v_mfma_f32_16x16x32_bf16 v[76:79], v[148:151], v[210:213], v[76:79]
	v_mfma_f32_16x16x32_bf16 v[72:75], v[170:173], v[210:213], v[72:75]
	v_mfma_f32_16x16x32_bf16 v[64:67], v[148:151], v[218:221], v[64:67]
	v_mfma_f32_16x16x32_bf16 v[56:59], v[170:173], v[218:221], v[56:59]
	v_mfma_f32_16x16x32_bf16 v[28:31], v[174:177], v[190:193], 0
	v_mfma_f32_16x16x32_bf16 v[24:27], v[182:185], v[190:193], 0
	v_mfma_f32_16x16x32_bf16 v[20:23], v[174:177], v[198:201], 0
	v_mfma_f32_16x16x32_bf16 v[16:19], v[182:185], v[198:201], 0
	v_mfma_f32_16x16x32_bf16 v[12:15], v[174:177], v[206:209], 0
	v_mfma_f32_16x16x32_bf16 v[8:11], v[182:185], v[206:209], 0
	v_mfma_f32_16x16x32_bf16 v[4:7], v[174:177], v[214:217], 0
	v_mfma_f32_16x16x32_bf16 v[0:3], v[182:185], v[214:217], 0
	v_mfma_f32_16x16x32_bf16 v[28:31], v[178:181], v[194:197], v[28:31]
	v_mfma_f32_16x16x32_bf16 v[24:27], v[186:189], v[194:197], v[24:27]
	v_mfma_f32_16x16x32_bf16 v[20:23], v[178:181], v[202:205], v[20:23]
	v_mfma_f32_16x16x32_bf16 v[16:19], v[186:189], v[202:205], v[16:19]
	v_mfma_f32_16x16x32_bf16 v[12:15], v[178:181], v[210:213], v[12:15]
	v_mfma_f32_16x16x32_bf16 v[8:11], v[186:189], v[210:213], v[8:11]
	v_mfma_f32_16x16x32_bf16 v[4:7], v[178:181], v[218:221], v[4:7]
	v_mfma_f32_16x16x32_bf16 v[0:3], v[186:189], v[218:221], v[0:3]
	s_barrier
; #define PG8_STAGE(bufoff, gbase, voff) do { _Pragma("unroll") for (int _i = 0; _i < 2; ++_i) \
;         __builtin_amdgcn_global_load_lds((const unsigned*)((const char*)(gbase) + (voff)[_i]), (LAS unsigned*)(lds + (bufoff) + ldsw + _i * 8192), 16, 0, 0); } while (0)
; #define PG8_LDA(dst, b, h) do { _Pragma("unroll") for (int m = 0; m < 4; ++m) _Pragma("unroll") for (int k = 0; k < 2; ++k) dst[m][k] = *(const LAS bf16x8*)(lds + PG8_SA(b, h) + aoff + m * 2048 + k * 1024); } while (0)
; #define PG8_LDB(dst, b, h) do { _Pragma("unroll") for (int n = 0; n < 2; ++n) _Pragma("unroll") for (int k = 0; k < 2; ++k) dst[n][k] = *(const LAS bf16x8*)(lds + PG8_SB(b, h) + boff + n * 2048 + k * 1024); } while (0)
; #define PG8_MMA(ai, bj, At, Bt) do { __builtin_amdgcn_s_setprio(1); _Pragma("unroll") for (int m = 0; m < 4; ++m) _Pragma("unroll") for (int n = 0; n < 2; ++n) _Pragma("unroll") for (int k = 0; k < 2; ++k) \
;         acc[ai][bj][m][n] = __builtin_amdgcn_mfma_f32_16x16x32_bf16(Bt[n][k], At[m][k], acc[ai][bj][m][n], 0, 0, 0); __builtin_amdgcn_s_setprio(0); } while (0)
; #define PG8_WAIT_V(n) asm volatile("s_waitcnt vmcnt(" #n ")" ::: "memory")
; #define PG8_WAIT_L(n) asm volatile("s_waitcnt lgkmcnt(" #n ")" ::: "memory")
; #define PG8_BAR __builtin_amdgcn_s_barrier()
; #define PG8_SCHED __builtin_amdgcn_sched_barrier(0)
; __device__ __forceinline__ void gemm_phase(LAS unsigned char* lds, const Params& p, const bf16_t* gA, const bf16_t* gBt, const int gM, const int gN, const int gK, const int epi, const int perm, bf16_t* const Hp, const int goff, const float coef) {
;     ...
;             PG8_LDB(B0, 1, 0); PG8_LDB(B1, 1, 1); PG8_SCHED; PG8_LDA(At, 1, 0); PG8_STAGE(PG8_SA(0, 1), a2 + hstep, voffA);
;             PG8_WAIT_V(8); PG8_WAIT_L(0); PG8_BAR; PG8_MMA(0, 0, At, B0); PG8_MMA(0, 1, At, B1); PG8_BAR; PG8_SCHED;
;             PG8_LDA(At, 1, 1); PG8_STAGE(PG8_SB(1, 0), b3, voffB); PG8_STAGE(PG8_SB(1, 1), b3 + hstep, voffB); PG8_STAGE(PG8_SA(1, 0), a3, voffA);
;             PG8_WAIT_V(8); PG8_WAIT_L(0); PG8_BAR; PG8_MMA(1, 0, At, B0); PG8_MMA(1, 1, At, B1); PG8_BAR; PG8_SCHED;
;         }
	s_add_i32 s55, 0, 0x18000
	s_add_i32 s56, 0, 0x1c000
	ds_read_b128 v[144:147], v222
	ds_read_b128 v[148:151], v222 offset:1024
	ds_read_b128 v[152:155], v222 offset:2048
	ds_read_b128 v[170:173], v222 offset:3072
	ds_read_b128 v[174:177], v223
	ds_read_b128 v[178:181], v223 offset:1024
	ds_read_b128 v[182:185], v223 offset:2048
	ds_read_b128 v[186:189], v223 offset:3072
	s_add_u32 s22, s22, 0x160000
	s_addc_u32 s23, s23, 0
	s_mov_b32 m0, s30
	ds_read_b128 v[190:193], v168 offset:32768
	ds_read_b128 v[194:197], v168 offset:33792
	ds_read_b128 v[198:201], v168 offset:34816
	ds_read_b128 v[202:205], v168 offset:35840
	ds_read_b128 v[206:209], v168 offset:36864
	ds_read_b128 v[210:213], v168 offset:37888
	ds_read_b128 v[214:217], v168 offset:38912
	ds_read_b128 v[218:221], v168 offset:39936
	global_load_lds_dwordx4 v128, s[22:23]
	s_mov_b32 m0, s31
	s_nop 0
	global_load_lds_dwordx4 v132, s[22:23]
	s_waitcnt vmcnt(8) lgkmcnt(0)
	s_barrier
	v_mfma_f32_16x16x32_bf16 v[124:127], v[144:147], v[190:193], v[124:127]
	v_mfma_f32_16x16x32_bf16 v[120:123], v[152:155], v[190:193], v[120:123]
	v_mfma_f32_16x16x32_bf16 v[116:119], v[144:147], v[198:201], v[116:119]
	v_mfma_f32_16x16x32_bf16 v[112:115], v[152:155], v[198:201], v[112:115]
	v_mfma_f32_16x16x32_bf16 v[108:111], v[144:147], v[206:209], v[108:111]
	v_mfma_f32_16x16x32_bf16 v[104:107], v[152:155], v[206:209], v[104:107]
	v_mfma_f32_16x16x32_bf16 v[100:103], v[144:147], v[214:217], v[100:103]
	v_mfma_f32_16x16x32_bf16 v[96:99], v[152:155], v[214:217], v[96:99]
	v_mfma_f32_16x16x32_bf16 v[124:127], v[148:151], v[194:197], v[124:127]
	v_mfma_f32_16x16x32_bf16 v[120:123], v[170:173], v[194:197], v[120:123]
	v_mfma_f32_16x16x32_bf16 v[116:119], v[148:151], v[202:205], v[116:119]
	v_mfma_f32_16x16x32_bf16 v[112:115], v[170:173], v[202:205], v[112:115]
	v_mfma_f32_16x16x32_bf16 v[108:111], v[148:151], v[210:213], v[108:111]
	v_mfma_f32_16x16x32_bf16 v[104:107], v[170:173], v[210:213], v[104:107]
	v_mfma_f32_16x16x32_bf16 v[100:103], v[148:151], v[218:221], v[100:103]
	v_mfma_f32_16x16x32_bf16 v[96:99], v[170:173], v[218:221], v[96:99]
	v_mfma_f32_16x16x32_bf16 v[68:71], v[174:177], v[190:193], v[68:71]
	v_mfma_f32_16x16x32_bf16 v[60:63], v[182:185], v[190:193], v[60:63]
	v_mfma_f32_16x16x32_bf16 v[52:55], v[174:177], v[198:201], v[52:55]
	v_mfma_f32_16x16x32_bf16 v[48:51], v[182:185], v[198:201], v[48:51]
	v_mfma_f32_16x16x32_bf16 v[44:47], v[174:177], v[206:209], v[44:47]
	v_mfma_f32_16x16x32_bf16 v[40:43], v[182:185], v[206:209], v[40:43]
	v_mfma_f32_16x16x32_bf16 v[36:39], v[174:177], v[214:217], v[36:39]
	v_mfma_f32_16x16x32_bf16 v[32:35], v[182:185], v[214:217], v[32:35]
	v_mfma_f32_16x16x32_bf16 v[68:71], v[178:181], v[194:197], v[68:71]
	v_mfma_f32_16x16x32_bf16 v[60:63], v[186:189], v[194:197], v[60:63]
	v_mfma_f32_16x16x32_bf16 v[52:55], v[178:181], v[202:205], v[52:55]
	v_mfma_f32_16x16x32_bf16 v[48:51], v[186:189], v[202:205], v[48:51]
	v_mfma_f32_16x16x32_bf16 v[44:47], v[178:181], v[210:213], v[44:47]
	v_mfma_f32_16x16x32_bf16 v[40:43], v[186:189], v[210:213], v[40:43]
	v_mfma_f32_16x16x32_bf16 v[36:39], v[178:181], v[218:221], v[36:39]
	v_mfma_f32_16x16x32_bf16 v[32:35], v[186:189], v[218:221], v[32:35]
	s_barrier
	s_mov_b64 s[98:99], s[22:23]
	s_add_i32 s22, s55, s27
	s_mov_b32 m0, s22
	ds_read_b128 v[190:193], v168 offset:49152
	ds_read_b128 v[194:197], v168 offset:50176
	ds_read_b128 v[198:201], v168 offset:51200
	ds_read_b128 v[202:205], v168 offset:52224
	ds_read_b128 v[206:209], v168 offset:53248
	ds_read_b128 v[210:213], v168 offset:54272
	ds_read_b128 v[214:217], v168 offset:55296
	ds_read_b128 v[218:221], v168 offset:56320
	s_add_u32 s100, s20, 0x80
	s_addc_u32 s101, s21, 0
	global_load_lds_dwordx4 v130, s[100:101]
	s_add_i32 m0, s22, 0x2000
	s_add_u32 s20, s20, 0x160080
	s_addc_u32 s21, s21, 0
	s_add_i32 s22, s56, s27
	global_load_lds_dwordx4 v134, s[100:101]
	s_mov_b32 m0, s22
	s_nop 0
	global_load_lds_dwordx4 v130, s[20:21]
	s_add_i32 m0, s22, 0x2000
	s_nop 0
	global_load_lds_dwordx4 v134, s[20:21]
	s_mov_b32 m0, s36
	s_add_u32 s100, s98, 0xffea0080
	s_addc_u32 s101, s99, -1
	global_load_lds_dwordx4 v128, s[100:101]
	s_mov_b32 m0, s37
	s_nop 0
	global_load_lds_dwordx4 v132, s[100:101]
	s_waitcnt vmcnt(8) lgkmcnt(0)
	s_barrier
	v_mfma_f32_16x16x32_bf16 v[92:95], v[144:147], v[190:193], v[92:95]
	v_mfma_f32_16x16x32_bf16 v[88:91], v[152:155], v[190:193], v[88:91]
	v_mfma_f32_16x16x32_bf16 v[84:87], v[144:147], v[198:201], v[84:87]
	v_mfma_f32_16x16x32_bf16 v[80:83], v[152:155], v[198:201], v[80:83]
	v_mfma_f32_16x16x32_bf16 v[76:79], v[144:147], v[206:209], v[76:79]
	v_mfma_f32_16x16x32_bf16 v[72:75], v[152:155], v[206:209], v[72:75]
	v_mfma_f32_16x16x32_bf16 v[64:67], v[144:147], v[214:217], v[64:67]
	v_mfma_f32_16x16x32_bf16 v[56:59], v[152:155], v[214:217], v[56:59]
	v_mfma_f32_16x16x32_bf16 v[92:95], v[148:151], v[194:197], v[92:95]
	v_mfma_f32_16x16x32_bf16 v[88:91], v[170:173], v[194:197], v[88:91]
	v_mfma_f32_16x16x32_bf16 v[84:87], v[148:151], v[202:205], v[84:87]
	v_mfma_f32_16x16x32_bf16 v[80:83], v[170:173], v[202:205], v[80:83]
	v_mfma_f32_16x16x32_bf16 v[76:79], v[148:151], v[210:213], v[76:79]
	v_mfma_f32_16x16x32_bf16 v[72:75], v[170:173], v[210:213], v[72:75]
	v_mfma_f32_16x16x32_bf16 v[64:67], v[148:151], v[218:221], v[64:67]
	v_mfma_f32_16x16x32_bf16 v[56:59], v[170:173], v[218:221], v[56:59]
	v_mfma_f32_16x16x32_bf16 v[28:31], v[174:177], v[190:193], v[28:31]
	v_mfma_f32_16x16x32_bf16 v[24:27], v[182:185], v[190:193], v[24:27]
	v_mfma_f32_16x16x32_bf16 v[20:23], v[174:177], v[198:201], v[20:23]
	v_mfma_f32_16x16x32_bf16 v[16:19], v[182:185], v[198:201], v[16:19]
	v_mfma_f32_16x16x32_bf16 v[12:15], v[174:177], v[206:209], v[12:15]
	v_mfma_f32_16x16x32_bf16 v[8:11], v[182:185], v[206:209], v[8:11]
	v_mfma_f32_16x16x32_bf16 v[4:7], v[174:177], v[214:217], v[4:7]
	v_mfma_f32_16x16x32_bf16 v[0:3], v[182:185], v[214:217], v[0:3]
	v_mfma_f32_16x16x32_bf16 v[28:31], v[178:181], v[194:197], v[28:31]
	v_mfma_f32_16x16x32_bf16 v[24:27], v[186:189], v[194:197], v[24:27]
	v_mfma_f32_16x16x32_bf16 v[20:23], v[178:181], v[202:205], v[20:23]
	v_mfma_f32_16x16x32_bf16 v[16:19], v[186:189], v[202:205], v[16:19]
	v_mfma_f32_16x16x32_bf16 v[12:15], v[178:181], v[210:213], v[12:15]
	v_mfma_f32_16x16x32_bf16 v[8:11], v[186:189], v[210:213], v[8:11]
	v_mfma_f32_16x16x32_bf16 v[4:7], v[178:181], v[218:221], v[4:7]
	v_mfma_f32_16x16x32_bf16 v[0:3], v[186:189], v[218:221], v[0:3]
	s_barrier
	s_add_u32 s18, s18, 0x100
	s_addc_u32 s19, s19, 0
	s_add_u32 s52, s52, 0x100
	s_addc_u32 s53, s53, 0
	s_cmp_ge_u32 s54, s50
	s_mov_b64 s[98:99], s[20:21]
	s_mov_b32 s20, s54
	s_cbranch_scc1 .Lpeel_exit_5
; #define PG8_STAGE(bufoff, gbase, voff) do { _Pragma("unroll") for (int _i = 0; _i < 2; ++_i) \
;         __builtin_amdgcn_global_load_lds((const unsigned*)((const char*)(gbase) + (voff)[_i]), (LAS unsigned*)(lds + (bufoff) + ldsw + _i * 8192), 16, 0, 0); } while (0)
; #define PG8_LDA(dst, b, h) do { _Pragma("unroll") for (int m = 0; m < 4; ++m) _Pragma("unroll") for (int k = 0; k < 2; ++k) dst[m][k] = *(const LAS bf16x8*)(lds + PG8_SA(b, h) + aoff + m * 2048 + k * 1024); } while (0)
; #define PG8_LDB(dst, b, h) do { _Pragma("unroll") for (int n = 0; n < 2; ++n) _Pragma("unroll") for (int k = 0; k < 2; ++k) dst[n][k] = *(const LAS bf16x8*)(lds + PG8_SB(b, h) + boff + n * 2048 + k * 1024); } while (0)
; #define PG8_MMA(ai, bj, At, Bt) do { __builtin_amdgcn_s_setprio(1); _Pragma("unroll") for (int m = 0; m < 4; ++m) _Pragma("unroll") for (int n = 0; n < 2; ++n) _Pragma("unroll") for (int k = 0; k < 2; ++k) \
;         acc[ai][bj][m][n] = __builtin_amdgcn_mfma_f32_16x16x32_bf16(Bt[n][k], At[m][k], acc[ai][bj][m][n], 0, 0, 0); __builtin_amdgcn_s_setprio(0); } while (0)
; #define PG8_WAIT_V(n) asm volatile("s_waitcnt vmcnt(" #n ")" ::: "memory")
; #define PG8_WAIT_L(n) asm volatile("s_waitcnt lgkmcnt(" #n ")" ::: "memory")
; #define PG8_BAR __builtin_amdgcn_s_barrier()
; #define PG8_SCHED __builtin_amdgcn_sched_barrier(0)
; __device__ __forceinline__ void gemm_phase(LAS unsigned char* lds, const Params& p, const bf16_t* gA, const bf16_t* gBt, const int gM, const int gN, const int gK, const int epi, const int perm, bf16_t* const Hp, const int goff, const float coef) {
;     ...
;             PG8_LDB(B0, 0, 0); PG8_LDB(B1, 0, 1); PG8_SCHED; PG8_LDA(At, 0, 0); PG8_STAGE(PG8_SA(1, 1), a1 + hstep, voffA);
;             PG8_WAIT_V(8); PG8_WAIT_L(0); PG8_BAR; PG8_MMA(0, 0, At, B0); PG8_MMA(0, 1, At, B1); PG8_BAR; PG8_SCHED;
;             PG8_LDA(At, 0, 1); PG8_STAGE(PG8_SB(0, 0), b2, voffB); PG8_STAGE(PG8_SB(0, 1), b2 + hstep, voffB); PG8_STAGE(PG8_SA(0, 0), a2, voffA);
;             PG8_WAIT_V(8); PG8_WAIT_L(0); PG8_BAR; PG8_MMA(1, 0, At, B0); PG8_MMA(1, 1, At, B1); PG8_BAR; PG8_SCHED;
;             PG8_LDB(B0, 1, 0); PG8_LDB(B1, 1, 1); PG8_SCHED; PG8_LDA(At, 1, 0); PG8_STAGE(PG8_SA(0, 1), a2 + hstep, voffA);
;             PG8_WAIT_V(8); PG8_WAIT_L(0); PG8_BAR; PG8_MMA(0, 0, At, B0); PG8_MMA(0, 1, At, B1); PG8_BAR; PG8_SCHED;
.LBB0_1827:
	ds_read_b128 v[144:147], v166
	ds_read_b128 v[148:151], v166 offset:1024
	ds_read_b128 v[152:155], v166 offset:2048
	ds_read_b128 v[170:173], v166 offset:3072
	ds_read_b128 v[174:177], v167
	ds_read_b128 v[178:181], v167 offset:1024
	ds_read_b128 v[182:185], v167 offset:2048
	ds_read_b128 v[186:189], v167 offset:3072
	s_add_i32 s54, s20, 2
	s_add_u32 s21, s18, 0xffea0080
	s_addc_u32 s22, s19, -1
	s_cmp_eq_u32 s51, s20
	s_cselect_b32 s20, s16, s52
	s_cselect_b32 s23, s15, s22
	s_cselect_b32 s22, s14, s21
	s_cselect_b32 s21, s17, s53
	s_add_i32 m0, s28, 0xc000
	ds_read_b128 v[190:193], v168
	ds_read_b128 v[194:197], v168 offset:1024
	ds_read_b128 v[198:201], v168 offset:2048
	ds_read_b128 v[202:205], v168 offset:3072
	ds_read_b128 v[206:209], v168 offset:4096
	ds_read_b128 v[210:213], v168 offset:5120
	ds_read_b128 v[214:217], v168 offset:6144
	ds_read_b128 v[218:221], v168 offset:7168
	global_load_lds_dwordx4 v136, s[18:19]
	s_add_i32 m0, s28, 0xe000
	s_nop 0
	global_load_lds_dwordx4 v138, s[18:19]
	s_waitcnt vmcnt(8) lgkmcnt(0)
	s_barrier
	v_mfma_f32_16x16x32_bf16 v[124:127], v[144:147], v[190:193], v[124:127]
	v_mfma_f32_16x16x32_bf16 v[120:123], v[152:155], v[190:193], v[120:123]
	v_mfma_f32_16x16x32_bf16 v[116:119], v[144:147], v[198:201], v[116:119]
	v_mfma_f32_16x16x32_bf16 v[112:115], v[152:155], v[198:201], v[112:115]
	v_mfma_f32_16x16x32_bf16 v[108:111], v[144:147], v[206:209], v[108:111]
	v_mfma_f32_16x16x32_bf16 v[104:107], v[152:155], v[206:209], v[104:107]
	v_mfma_f32_16x16x32_bf16 v[100:103], v[144:147], v[214:217], v[100:103]
	v_mfma_f32_16x16x32_bf16 v[96:99], v[152:155], v[214:217], v[96:99]
	v_mfma_f32_16x16x32_bf16 v[124:127], v[148:151], v[194:197], v[124:127]
	v_mfma_f32_16x16x32_bf16 v[120:123], v[170:173], v[194:197], v[120:123]
	v_mfma_f32_16x16x32_bf16 v[116:119], v[148:151], v[202:205], v[116:119]
	v_mfma_f32_16x16x32_bf16 v[112:115], v[170:173], v[202:205], v[112:115]
	v_mfma_f32_16x16x32_bf16 v[108:111], v[148:151], v[210:213], v[108:111]
	v_mfma_f32_16x16x32_bf16 v[104:107], v[170:173], v[210:213], v[104:107]
	v_mfma_f32_16x16x32_bf16 v[100:103], v[148:151], v[218:221], v[100:103]
	v_mfma_f32_16x16x32_bf16 v[96:99], v[170:173], v[218:221], v[96:99]
	v_mfma_f32_16x16x32_bf16 v[68:71], v[174:177], v[190:193], v[68:71]
	v_mfma_f32_16x16x32_bf16 v[60:63], v[182:185], v[190:193], v[60:63]
	v_mfma_f32_16x16x32_bf16 v[52:55], v[174:177], v[198:201], v[52:55]
	v_mfma_f32_16x16x32_bf16 v[48:51], v[182:185], v[198:201], v[48:51]
	v_mfma_f32_16x16x32_bf16 v[44:47], v[174:177], v[206:209], v[44:47]
	v_mfma_f32_16x16x32_bf16 v[40:43], v[182:185], v[206:209], v[40:43]
	v_mfma_f32_16x16x32_bf16 v[36:39], v[174:177], v[214:217], v[36:39]
	v_mfma_f32_16x16x32_bf16 v[32:35], v[182:185], v[214:217], v[32:35]
	v_mfma_f32_16x16x32_bf16 v[68:71], v[178:181], v[194:197], v[68:71]
	v_mfma_f32_16x16x32_bf16 v[60:63], v[186:189], v[194:197], v[60:63]
	v_mfma_f32_16x16x32_bf16 v[52:55], v[178:181], v[202:205], v[52:55]
	v_mfma_f32_16x16x32_bf16 v[48:51], v[186:189], v[202:205], v[48:51]
	v_mfma_f32_16x16x32_bf16 v[44:47], v[178:181], v[210:213], v[44:47]
	v_mfma_f32_16x16x32_bf16 v[40:43], v[186:189], v[210:213], v[40:43]
	v_mfma_f32_16x16x32_bf16 v[36:39], v[178:181], v[218:221], v[36:39]
	v_mfma_f32_16x16x32_bf16 v[32:35], v[186:189], v[218:221], v[32:35]
	s_barrier
	s_add_i32 s55, s42, s27
	s_mov_b32 m0, s55
	ds_read_b128 v[190:193], v168 offset:16384
	ds_read_b128 v[194:197], v168 offset:17408
	ds_read_b128 v[198:201], v168 offset:18432
	ds_read_b128 v[202:205], v168 offset:19456
	ds_read_b128 v[206:209], v168 offset:20480
	ds_read_b128 v[210:213], v168 offset:21504
	ds_read_b128 v[214:217], v168 offset:22528
	ds_read_b128 v[218:221], v168 offset:23552
	global_load_lds_dwordx4 v130, s[20:21]
	s_add_i32 m0, s55, 0x2000
	s_add_u32 s56, s20, 0x160000
	s_addc_u32 s57, s21, 0
	s_add_i32 s55, s43, s27
	global_load_lds_dwordx4 v134, s[20:21]
	s_mov_b32 m0, s55
	s_nop 0
	global_load_lds_dwordx4 v130, s[56:57]
	s_add_i32 m0, s55, 0x2000
	s_nop 0
	global_load_lds_dwordx4 v134, s[56:57]
	s_mov_b32 m0, s28
	s_nop 0
	global_load_lds_dwordx4 v128, s[22:23]
	s_mov_b32 m0, s29
	s_nop 0
	global_load_lds_dwordx4 v132, s[22:23]
	s_waitcnt vmcnt(8) lgkmcnt(0)
	s_barrier
	v_mfma_f32_16x16x32_bf16 v[92:95], v[144:147], v[190:193], v[92:95]
	v_mfma_f32_16x16x32_bf16 v[88:91], v[152:155], v[190:193], v[88:91]
	v_mfma_f32_16x16x32_bf16 v[84:87], v[144:147], v[198:201], v[84:87]
	v_mfma_f32_16x16x32_bf16 v[80:83], v[152:155], v[198:201], v[80:83]
	v_mfma_f32_16x16x32_bf16 v[76:79], v[144:147], v[206:209], v[76:79]
	v_mfma_f32_16x16x32_bf16 v[72:75], v[152:155], v[206:209], v[72:75]
	v_mfma_f32_16x16x32_bf16 v[64:67], v[144:147], v[214:217], v[64:67]
	v_mfma_f32_16x16x32_bf16 v[56:59], v[152:155], v[214:217], v[56:59]
	v_mfma_f32_16x16x32_bf16 v[92:95], v[148:151], v[194:197], v[92:95]
	v_mfma_f32_16x16x32_bf16 v[88:91], v[170:173], v[194:197], v[88:91]
	v_mfma_f32_16x16x32_bf16 v[84:87], v[148:151], v[202:205], v[84:87]
	v_mfma_f32_16x16x32_bf16 v[80:83], v[170:173], v[202:205], v[80:83]
	v_mfma_f32_16x16x32_bf16 v[76:79], v[148:151], v[210:213], v[76:79]
	v_mfma_f32_16x16x32_bf16 v[72:75], v[170:173], v[210:213], v[72:75]
	v_mfma_f32_16x16x32_bf16 v[64:67], v[148:151], v[218:221], v[64:67]
	v_mfma_f32_16x16x32_bf16 v[56:59], v[170:173], v[218:221], v[56:59]
	v_mfma_f32_16x16x32_bf16 v[28:31], v[174:177], v[190:193], v[28:31]
	v_mfma_f32_16x16x32_bf16 v[24:27], v[182:185], v[190:193], v[24:27]
	v_mfma_f32_16x16x32_bf16 v[20:23], v[174:177], v[198:201], v[20:23]
	v_mfma_f32_16x16x32_bf16 v[16:19], v[182:185], v[198:201], v[16:19]
	v_mfma_f32_16x16x32_bf16 v[12:15], v[174:177], v[206:209], v[12:15]
	v_mfma_f32_16x16x32_bf16 v[8:11], v[182:185], v[206:209], v[8:11]
	v_mfma_f32_16x16x32_bf16 v[4:7], v[174:177], v[214:217], v[4:7]
	v_mfma_f32_16x16x32_bf16 v[0:3], v[182:185], v[214:217], v[0:3]
	v_mfma_f32_16x16x32_bf16 v[28:31], v[178:181], v[194:197], v[28:31]
	v_mfma_f32_16x16x32_bf16 v[24:27], v[186:189], v[194:197], v[24:27]
	v_mfma_f32_16x16x32_bf16 v[20:23], v[178:181], v[202:205], v[20:23]
	v_mfma_f32_16x16x32_bf16 v[16:19], v[186:189], v[202:205], v[16:19]
	v_mfma_f32_16x16x32_bf16 v[12:15], v[178:181], v[210:213], v[12:15]
	v_mfma_f32_16x16x32_bf16 v[8:11], v[186:189], v[210:213], v[8:11]
	v_mfma_f32_16x16x32_bf16 v[4:7], v[178:181], v[218:221], v[4:7]
	v_mfma_f32_16x16x32_bf16 v[0:3], v[186:189], v[218:221], v[0:3]
	s_barrier
; #define PG8_STAGE(bufoff, gbase, voff) do { _Pragma("unroll") for (int _i = 0; _i < 2; ++_i) \
;         __builtin_amdgcn_global_load_lds((const unsigned*)((const char*)(gbase) + (voff)[_i]), (LAS unsigned*)(lds + (bufoff) + ldsw + _i * 8192), 16, 0, 0); } while (0)
; #define PG8_LDA(dst, b, h) do { _Pragma("unroll") for (int m = 0; m < 4; ++m) _Pragma("unroll") for (int k = 0; k < 2; ++k) dst[m][k] = *(const LAS bf16x8*)(lds + PG8_SA(b, h) + aoff + m * 2048 + k * 1024); } while (0)
; #define PG8_LDB(dst, b, h) do { _Pragma("unroll") for (int n = 0; n < 2; ++n) _Pragma("unroll") for (int k = 0; k < 2; ++k) dst[n][k] = *(const LAS bf16x8*)(lds + PG8_SB(b, h) + boff + n * 2048 + k * 1024); } while (0)
; #define PG8_MMA(ai, bj, At, Bt) do { __builtin_amdgcn_s_setprio(1); _Pragma("unroll") for (int m = 0; m < 4; ++m) _Pragma("unroll") for (int n = 0; n < 2; ++n) _Pragma("unroll") for (int k = 0; k < 2; ++k) \
;         acc[ai][bj][m][n] = __builtin_amdgcn_mfma_f32_16x16x32_bf16(Bt[n][k], At[m][k], acc[ai][bj][m][n], 0, 0, 0); __builtin_amdgcn_s_setprio(0); } while (0)
; #define PG8_WAIT_V(n) asm volatile("s_waitcnt vmcnt(" #n ")" ::: "memory")
; #define PG8_WAIT_L(n) asm volatile("s_waitcnt lgkmcnt(" #n ")" ::: "memory")
; #define PG8_BAR __builtin_amdgcn_s_barrier()
; #define PG8_SCHED __builtin_amdgcn_sched_barrier(0)
; __device__ __forceinline__ void gemm_phase(LAS unsigned char* lds, const Params& p, const bf16_t* gA, const bf16_t* gBt, const int gM, const int gN, const int gK, const int epi, const int perm, bf16_t* const Hp, const int goff, const float coef) {
;     ...
;             PG8_LDB(B0, 1, 0); PG8_LDB(B1, 1, 1); PG8_SCHED; PG8_LDA(At, 1, 0); PG8_STAGE(PG8_SA(0, 1), a2 + hstep, voffA);
;             PG8_WAIT_V(8); PG8_WAIT_L(0); PG8_BAR; PG8_MMA(0, 0, At, B0); PG8_MMA(0, 1, At, B1); PG8_BAR; PG8_SCHED;
;             PG8_LDA(At, 1, 1); PG8_STAGE(PG8_SB(1, 0), b3, voffB); PG8_STAGE(PG8_SB(1, 1), b3 + hstep, voffB); PG8_STAGE(PG8_SA(1, 0), a3, voffA);
;             PG8_WAIT_V(8); PG8_WAIT_L(0); PG8_BAR; PG8_MMA(1, 0, At, B0); PG8_MMA(1, 1, At, B1); PG8_BAR; PG8_SCHED;
;         }
	s_add_i32 s55, 0, 0x18000
	s_add_i32 s56, 0, 0x1c000
	ds_read_b128 v[144:147], v222
	ds_read_b128 v[148:151], v222 offset:1024
	ds_read_b128 v[152:155], v222 offset:2048
	ds_read_b128 v[170:173], v222 offset:3072
	ds_read_b128 v[174:177], v223
	ds_read_b128 v[178:181], v223 offset:1024
	ds_read_b128 v[182:185], v223 offset:2048
	ds_read_b128 v[186:189], v223 offset:3072
	s_add_u32 s22, s22, 0x160000
	s_addc_u32 s23, s23, 0
	s_mov_b32 m0, s30
	ds_read_b128 v[190:193], v168 offset:32768
	ds_read_b128 v[194:197], v168 offset:33792
	ds_read_b128 v[198:201], v168 offset:34816
	ds_read_b128 v[202:205], v168 offset:35840
	ds_read_b128 v[206:209], v168 offset:36864
	ds_read_b128 v[210:213], v168 offset:37888
	ds_read_b128 v[214:217], v168 offset:38912
	ds_read_b128 v[218:221], v168 offset:39936
	global_load_lds_dwordx4 v128, s[22:23]
	s_mov_b32 m0, s31
	s_nop 0
	global_load_lds_dwordx4 v132, s[22:23]
	s_waitcnt vmcnt(8) lgkmcnt(0)
	s_barrier
	v_mfma_f32_16x16x32_bf16 v[124:127], v[144:147], v[190:193], v[124:127]
	v_mfma_f32_16x16x32_bf16 v[120:123], v[152:155], v[190:193], v[120:123]
	v_mfma_f32_16x16x32_bf16 v[116:119], v[144:147], v[198:201], v[116:119]
	v_mfma_f32_16x16x32_bf16 v[112:115], v[152:155], v[198:201], v[112:115]
	v_mfma_f32_16x16x32_bf16 v[108:111], v[144:147], v[206:209], v[108:111]
	v_mfma_f32_16x16x32_bf16 v[104:107], v[152:155], v[206:209], v[104:107]
	v_mfma_f32_16x16x32_bf16 v[100:103], v[144:147], v[214:217], v[100:103]
	v_mfma_f32_16x16x32_bf16 v[96:99], v[152:155], v[214:217], v[96:99]
	v_mfma_f32_16x16x32_bf16 v[124:127], v[148:151], v[194:197], v[124:127]
	v_mfma_f32_16x16x32_bf16 v[120:123], v[170:173], v[194:197], v[120:123]
	v_mfma_f32_16x16x32_bf16 v[116:119], v[148:151], v[202:205], v[116:119]
	v_mfma_f32_16x16x32_bf16 v[112:115], v[170:173], v[202:205], v[112:115]
	v_mfma_f32_16x16x32_bf16 v[108:111], v[148:151], v[210:213], v[108:111]
	v_mfma_f32_16x16x32_bf16 v[104:107], v[170:173], v[210:213], v[104:107]
	v_mfma_f32_16x16x32_bf16 v[100:103], v[148:151], v[218:221], v[100:103]
	v_mfma_f32_16x16x32_bf16 v[96:99], v[170:173], v[218:221], v[96:99]
	v_mfma_f32_16x16x32_bf16 v[68:71], v[174:177], v[190:193], v[68:71]
	v_mfma_f32_16x16x32_bf16 v[60:63], v[182:185], v[190:193], v[60:63]
	v_mfma_f32_16x16x32_bf16 v[52:55], v[174:177], v[198:201], v[52:55]
	v_mfma_f32_16x16x32_bf16 v[48:51], v[182:185], v[198:201], v[48:51]
	v_mfma_f32_16x16x32_bf16 v[44:47], v[174:177], v[206:209], v[44:47]
	v_mfma_f32_16x16x32_bf16 v[40:43], v[182:185], v[206:209], v[40:43]
	v_mfma_f32_16x16x32_bf16 v[36:39], v[174:177], v[214:217], v[36:39]
	v_mfma_f32_16x16x32_bf16 v[32:35], v[182:185], v[214:217], v[32:35]
	v_mfma_f32_16x16x32_bf16 v[68:71], v[178:181], v[194:197], v[68:71]
	v_mfma_f32_16x16x32_bf16 v[60:63], v[186:189], v[194:197], v[60:63]
	v_mfma_f32_16x16x32_bf16 v[52:55], v[178:181], v[202:205], v[52:55]
	v_mfma_f32_16x16x32_bf16 v[48:51], v[186:189], v[202:205], v[48:51]
	v_mfma_f32_16x16x32_bf16 v[44:47], v[178:181], v[210:213], v[44:47]
	v_mfma_f32_16x16x32_bf16 v[40:43], v[186:189], v[210:213], v[40:43]
	v_mfma_f32_16x16x32_bf16 v[36:39], v[178:181], v[218:221], v[36:39]
	v_mfma_f32_16x16x32_bf16 v[32:35], v[186:189], v[218:221], v[32:35]
	s_barrier
	s_mov_b64 s[98:99], s[22:23]
	s_add_i32 s22, s55, s27
	s_mov_b32 m0, s22
	ds_read_b128 v[190:193], v168 offset:49152
	ds_read_b128 v[194:197], v168 offset:50176
	ds_read_b128 v[198:201], v168 offset:51200
	ds_read_b128 v[202:205], v168 offset:52224
	ds_read_b128 v[206:209], v168 offset:53248
	ds_read_b128 v[210:213], v168 offset:54272
	ds_read_b128 v[214:217], v168 offset:55296
	ds_read_b128 v[218:221], v168 offset:56320
	s_add_u32 s100, s20, 0x80
	s_addc_u32 s101, s21, 0
	global_load_lds_dwordx4 v130, s[100:101]
	s_add_i32 m0, s22, 0x2000
	s_add_u32 s20, s20, 0x160080
	s_addc_u32 s21, s21, 0
	s_add_i32 s22, s56, s27
	global_load_lds_dwordx4 v134, s[100:101]
	s_mov_b32 m0, s22
	s_nop 0
	global_load_lds_dwordx4 v130, s[20:21]
	s_add_i32 m0, s22, 0x2000
	s_nop 0
	global_load_lds_dwordx4 v134, s[20:21]
	s_mov_b32 m0, s36
	s_add_u32 s100, s98, 0xffea0080
	s_addc_u32 s101, s99, -1
	global_load_lds_dwordx4 v128, s[100:101]
	s_mov_b32 m0, s37
	s_nop 0
	global_load_lds_dwordx4 v132, s[100:101]
	s_waitcnt vmcnt(8) lgkmcnt(0)
	s_barrier
	v_mfma_f32_16x16x32_bf16 v[92:95], v[144:147], v[190:193], v[92:95]
	v_mfma_f32_16x16x32_bf16 v[88:91], v[152:155], v[190:193], v[88:91]
	v_mfma_f32_16x16x32_bf16 v[84:87], v[144:147], v[198:201], v[84:87]
	v_mfma_f32_16x16x32_bf16 v[80:83], v[152:155], v[198:201], v[80:83]
	v_mfma_f32_16x16x32_bf16 v[76:79], v[144:147], v[206:209], v[76:79]
	v_mfma_f32_16x16x32_bf16 v[72:75], v[152:155], v[206:209], v[72:75]
	v_mfma_f32_16x16x32_bf16 v[64:67], v[144:147], v[214:217], v[64:67]
	v_mfma_f32_16x16x32_bf16 v[56:59], v[152:155], v[214:217], v[56:59]
	v_mfma_f32_16x16x32_bf16 v[92:95], v[148:151], v[194:197], v[92:95]
	v_mfma_f32_16x16x32_bf16 v[88:91], v[170:173], v[194:197], v[88:91]
	v_mfma_f32_16x16x32_bf16 v[84:87], v[148:151], v[202:205], v[84:87]
	v_mfma_f32_16x16x32_bf16 v[80:83], v[170:173], v[202:205], v[80:83]
	v_mfma_f32_16x16x32_bf16 v[76:79], v[148:151], v[210:213], v[76:79]
	v_mfma_f32_16x16x32_bf16 v[72:75], v[170:173], v[210:213], v[72:75]
	v_mfma_f32_16x16x32_bf16 v[64:67], v[148:151], v[218:221], v[64:67]
	v_mfma_f32_16x16x32_bf16 v[56:59], v[170:173], v[218:221], v[56:59]
	v_mfma_f32_16x16x32_bf16 v[28:31], v[174:177], v[190:193], v[28:31]
	v_mfma_f32_16x16x32_bf16 v[24:27], v[182:185], v[190:193], v[24:27]
	v_mfma_f32_16x16x32_bf16 v[20:23], v[174:177], v[198:201], v[20:23]
	v_mfma_f32_16x16x32_bf16 v[16:19], v[182:185], v[198:201], v[16:19]
	v_mfma_f32_16x16x32_bf16 v[12:15], v[174:177], v[206:209], v[12:15]
	v_mfma_f32_16x16x32_bf16 v[8:11], v[182:185], v[206:209], v[8:11]
	v_mfma_f32_16x16x32_bf16 v[4:7], v[174:177], v[214:217], v[4:7]
	v_mfma_f32_16x16x32_bf16 v[0:3], v[182:185], v[214:217], v[0:3]
	v_mfma_f32_16x16x32_bf16 v[28:31], v[178:181], v[194:197], v[28:31]
	v_mfma_f32_16x16x32_bf16 v[24:27], v[186:189], v[194:197], v[24:27]
	v_mfma_f32_16x16x32_bf16 v[20:23], v[178:181], v[202:205], v[20:23]
	v_mfma_f32_16x16x32_bf16 v[16:19], v[186:189], v[202:205], v[16:19]
	v_mfma_f32_16x16x32_bf16 v[12:15], v[178:181], v[210:213], v[12:15]
	v_mfma_f32_16x16x32_bf16 v[8:11], v[186:189], v[210:213], v[8:11]
	v_mfma_f32_16x16x32_bf16 v[4:7], v[178:181], v[218:221], v[4:7]
	v_mfma_f32_16x16x32_bf16 v[0:3], v[186:189], v[218:221], v[0:3]
	s_barrier
	s_add_u32 s18, s18, 0x100
	s_addc_u32 s19, s19, 0
	s_add_u32 s52, s52, 0x100
	s_addc_u32 s53, s53, 0
	s_cmp_ge_u32 s54, s50
	s_mov_b64 s[98:99], s[20:21]
	s_mov_b32 s20, s54
	s_cbranch_scc0 .LBB0_1827
